# t7 + balanced LDS-DMA staging in the MT=4 K-loops (G1a, in-proj, G1b): role-owned pieces, 4 DMAs in every load segment, two loop copies by wave half
# speedup vs baseline: 1.0081x; 1.0028x over previous
.LBB0_515:
	s_and_b64 vcc, exec, s[8:9]
	s_cbranch_vccz TB_L8579_Bpeel
	s_cmp_eq_u32 s72, 28
	s_cselect_b32 s18, s60, s64
	s_cselect_b32 s19, s13, s66
	s_cselect_b32 s22, s62, s68
	s_cselect_b32 s23, s11, s70
	v_add_u32_e32 v130, 0x10000, v133
	ds_read_b128 v[136:139], v130
	ds_read_b128 v[140:143], v130 offset:1024
	ds_read_b128 v[144:147], v130 offset:2048
	ds_read_b128 v[148:151], v130 offset:3072
	v_add_u32_e32 v130, 0x14000, v133
	ds_read_b128 v[152:155], v130
	ds_read_b128 v[156:159], v130 offset:1024
	ds_read_b128 v[160:163], v130 offset:2048
	ds_read_b128 v[164:167], v130 offset:3072
	ds_read_b128 v[168:171], v134
	ds_read_b128 v[172:175], v134 offset:1024
	ds_read_b128 v[176:179], v134 offset:2048
	ds_read_b128 v[180:183], v134 offset:3072
	ds_read_b128 v[184:187], v134 offset:4096
	ds_read_b128 v[188:191], v134 offset:5120
	ds_read_b128 v[192:195], v134 offset:6144
	ds_read_b128 v[196:199], v134 offset:7168
	s_add_u32 s74, s64, 0x3ff80
	s_addc_u32 s75, s66, 0
	s_add_i32 m0, s26, 0xa000
	s_nop 0
	global_load_lds_dwordx4 v0, s[74:75]
	s_add_u32 s74, s64, 0x5ff80
	s_addc_u32 s75, s66, 0
	s_add_i32 m0, s26, 0xb000
	s_nop 0
	global_load_lds_dwordx4 v0, s[74:75]
	s_add_u32 s74, s64, 0x7ff80
	s_addc_u32 s75, s66, 0
	s_add_i32 m0, s26, 0xc000
	s_nop 0
	global_load_lds_dwordx4 v0, s[74:75]
	s_add_u32 s74, s64, 0x9ff80
	s_addc_u32 s75, s66, 0
	s_add_i32 m0, s26, 0xd000
	s_nop 0
	global_load_lds_dwordx4 v0, s[74:75]
	s_waitcnt vmcnt(8)
	s_waitcnt lgkmcnt(0)
	s_barrier
	v_mfma_f32_16x16x32_bf16 v[122:125], v[136:139], v[168:171], 0
	v_mfma_f32_16x16x32_bf16 v[114:117], v[144:147], v[168:171], 0
	v_mfma_f32_16x16x32_bf16 v[106:109], v[136:139], v[176:179], 0
	v_mfma_f32_16x16x32_bf16 v[98:101], v[144:147], v[176:179], 0
	v_mfma_f32_16x16x32_bf16 v[90:93], v[136:139], v[184:187], 0
	v_mfma_f32_16x16x32_bf16 v[82:85], v[144:147], v[184:187], 0
	v_mfma_f32_16x16x32_bf16 v[74:77], v[136:139], v[192:195], 0
	v_mfma_f32_16x16x32_bf16 v[66:69], v[144:147], v[192:195], 0
	v_mfma_f32_16x16x32_bf16 v[122:125], v[140:143], v[172:175], v[122:125]
	v_mfma_f32_16x16x32_bf16 v[114:117], v[148:151], v[172:175], v[114:117]
	v_mfma_f32_16x16x32_bf16 v[106:109], v[140:143], v[180:183], v[106:109]
	v_mfma_f32_16x16x32_bf16 v[98:101], v[148:151], v[180:183], v[98:101]
	v_mfma_f32_16x16x32_bf16 v[90:93], v[140:143], v[188:191], v[90:93]
	v_mfma_f32_16x16x32_bf16 v[82:85], v[148:151], v[188:191], v[82:85]
	v_mfma_f32_16x16x32_bf16 v[74:77], v[140:143], v[196:199], v[74:77]
	v_mfma_f32_16x16x32_bf16 v[66:69], v[148:151], v[196:199], v[66:69]
	v_mfma_f32_16x16x32_bf16 v[126:129], v[152:155], v[168:171], 0
	v_mfma_f32_16x16x32_bf16 v[118:121], v[160:163], v[168:171], 0
	v_mfma_f32_16x16x32_bf16 v[110:113], v[152:155], v[176:179], 0
	v_mfma_f32_16x16x32_bf16 v[102:105], v[160:163], v[176:179], 0
	v_mfma_f32_16x16x32_bf16 v[94:97], v[152:155], v[184:187], 0
	v_mfma_f32_16x16x32_bf16 v[86:89], v[160:163], v[184:187], 0
	v_mfma_f32_16x16x32_bf16 v[78:81], v[152:155], v[192:195], 0
	v_mfma_f32_16x16x32_bf16 v[70:73], v[160:163], v[192:195], 0
	v_mfma_f32_16x16x32_bf16 v[126:129], v[156:159], v[172:175], v[126:129]
	v_mfma_f32_16x16x32_bf16 v[118:121], v[164:167], v[172:175], v[118:121]
	v_mfma_f32_16x16x32_bf16 v[110:113], v[156:159], v[180:183], v[110:113]
	v_mfma_f32_16x16x32_bf16 v[102:105], v[164:167], v[180:183], v[102:105]
	v_mfma_f32_16x16x32_bf16 v[94:97], v[156:159], v[188:191], v[94:97]
	v_mfma_f32_16x16x32_bf16 v[86:89], v[164:167], v[188:191], v[86:89]
	v_mfma_f32_16x16x32_bf16 v[78:81], v[156:159], v[196:199], v[78:81]
	v_mfma_f32_16x16x32_bf16 v[70:73], v[164:167], v[196:199], v[70:73]
	s_barrier
	ds_read_b128 v[168:171], v134 offset:16384
	ds_read_b128 v[172:175], v134 offset:17408
	ds_read_b128 v[176:179], v134 offset:18432
	ds_read_b128 v[180:183], v134 offset:19456
	ds_read_b128 v[184:187], v134 offset:20480
	ds_read_b128 v[188:191], v134 offset:21504
	ds_read_b128 v[192:195], v134 offset:22528
	ds_read_b128 v[196:199], v134 offset:23552
	s_mov_b32 s74, s22
	s_mov_b32 s75, s23
	s_add_i32 m0, s26, 0x10000
	s_nop 0
	global_load_lds_dwordx4 v132, s[74:75]
	s_add_u32 s74, s22, 0x20000
	s_addc_u32 s75, s23, 0
	s_add_i32 m0, s26, 0x11000
	s_nop 0
	global_load_lds_dwordx4 v132, s[74:75]
	s_add_u32 s74, s22, 0x40000
	s_addc_u32 s75, s23, 0
	s_add_i32 m0, s26, 0x12000
	s_nop 0
	global_load_lds_dwordx4 v132, s[74:75]
	s_add_u32 s74, s22, 0x60000
	s_addc_u32 s75, s23, 0
	s_add_i32 m0, s26, 0x13000
	s_nop 0
	global_load_lds_dwordx4 v132, s[74:75]
	s_waitcnt vmcnt(8)
	s_waitcnt lgkmcnt(0)
	s_barrier
	v_mfma_f32_16x16x32_bf16 v[58:61], v[136:139], v[168:171], 0
	v_mfma_f32_16x16x32_bf16 v[50:53], v[144:147], v[168:171], 0
	v_mfma_f32_16x16x32_bf16 v[42:45], v[136:139], v[176:179], 0
	v_mfma_f32_16x16x32_bf16 v[34:37], v[144:147], v[176:179], 0
	v_mfma_f32_16x16x32_bf16 v[26:29], v[136:139], v[184:187], 0
	v_mfma_f32_16x16x32_bf16 v[18:21], v[144:147], v[184:187], 0
	v_mfma_f32_16x16x32_bf16 v[10:13], v[136:139], v[192:195], 0
	v_mfma_f32_16x16x32_bf16 v[2:5], v[144:147], v[192:195], 0
	v_mfma_f32_16x16x32_bf16 v[58:61], v[140:143], v[172:175], v[58:61]
	v_mfma_f32_16x16x32_bf16 v[50:53], v[148:151], v[172:175], v[50:53]
	v_mfma_f32_16x16x32_bf16 v[42:45], v[140:143], v[180:183], v[42:45]
	v_mfma_f32_16x16x32_bf16 v[34:37], v[148:151], v[180:183], v[34:37]
	v_mfma_f32_16x16x32_bf16 v[26:29], v[140:143], v[188:191], v[26:29]
	v_mfma_f32_16x16x32_bf16 v[18:21], v[148:151], v[188:191], v[18:21]
	v_mfma_f32_16x16x32_bf16 v[10:13], v[140:143], v[196:199], v[10:13]
	v_mfma_f32_16x16x32_bf16 v[2:5], v[148:151], v[196:199], v[2:5]
	v_mfma_f32_16x16x32_bf16 v[62:65], v[152:155], v[168:171], 0
	v_mfma_f32_16x16x32_bf16 v[54:57], v[160:163], v[168:171], 0
	v_mfma_f32_16x16x32_bf16 v[46:49], v[152:155], v[176:179], 0
	v_mfma_f32_16x16x32_bf16 v[38:41], v[160:163], v[176:179], 0
	v_mfma_f32_16x16x32_bf16 v[30:33], v[152:155], v[184:187], 0
	v_mfma_f32_16x16x32_bf16 v[22:25], v[160:163], v[184:187], 0
	v_mfma_f32_16x16x32_bf16 v[14:17], v[152:155], v[192:195], 0
	v_mfma_f32_16x16x32_bf16 v[6:9], v[160:163], v[192:195], 0
	v_mfma_f32_16x16x32_bf16 v[62:65], v[156:159], v[172:175], v[62:65]
	v_mfma_f32_16x16x32_bf16 v[54:57], v[164:167], v[172:175], v[54:57]
	v_mfma_f32_16x16x32_bf16 v[46:49], v[156:159], v[180:183], v[46:49]
	v_mfma_f32_16x16x32_bf16 v[38:41], v[164:167], v[180:183], v[38:41]
	v_mfma_f32_16x16x32_bf16 v[30:33], v[156:159], v[188:191], v[30:33]
	v_mfma_f32_16x16x32_bf16 v[22:25], v[164:167], v[188:191], v[22:25]
	v_mfma_f32_16x16x32_bf16 v[14:17], v[156:159], v[196:199], v[14:17]
	v_mfma_f32_16x16x32_bf16 v[6:9], v[164:167], v[196:199], v[6:9]
	s_barrier
	v_add_u32_e32 v130, 0x18000, v133
	ds_read_b128 v[136:139], v130
	ds_read_b128 v[140:143], v130 offset:1024
	ds_read_b128 v[144:147], v130 offset:2048
	ds_read_b128 v[148:151], v130 offset:3072
	v_add_u32_e32 v130, 0x1c000, v133
	ds_read_b128 v[152:155], v130
	ds_read_b128 v[156:159], v130 offset:1024
	ds_read_b128 v[160:163], v130 offset:2048
	ds_read_b128 v[164:167], v130 offset:3072
	ds_read_b128 v[168:171], v134 offset:32768
	ds_read_b128 v[172:175], v134 offset:33792
	ds_read_b128 v[176:179], v134 offset:34816
	ds_read_b128 v[180:183], v134 offset:35840
	ds_read_b128 v[184:187], v134 offset:36864
	ds_read_b128 v[188:191], v134 offset:37888
	ds_read_b128 v[192:195], v134 offset:38912
	ds_read_b128 v[196:199], v134 offset:39936
	s_add_u32 s74, s18, 0x40000
	s_addc_u32 s75, s19, 0
	s_add_i32 m0, s26, 0x2000
	s_nop 0
	global_load_lds_dwordx4 v0, s[74:75]
	s_add_u32 s74, s18, 0x60000
	s_addc_u32 s75, s19, 0
	s_add_i32 m0, s26, 0x3000
	s_nop 0
	global_load_lds_dwordx4 v0, s[74:75]
	s_add_u32 s74, s18, 0x80000
	s_addc_u32 s75, s19, 0
	s_add_i32 m0, s26, 0x4000
	s_nop 0
	global_load_lds_dwordx4 v0, s[74:75]
	s_add_u32 s74, s18, 0xa0000
	s_addc_u32 s75, s19, 0
	s_add_i32 m0, s26, 0x5000
	s_nop 0
	global_load_lds_dwordx4 v0, s[74:75]
	s_waitcnt vmcnt(8)
	s_waitcnt lgkmcnt(0)
	s_barrier
	v_mfma_f32_16x16x32_bf16 v[122:125], v[136:139], v[168:171], v[122:125]
	v_mfma_f32_16x16x32_bf16 v[114:117], v[144:147], v[168:171], v[114:117]
	v_mfma_f32_16x16x32_bf16 v[106:109], v[136:139], v[176:179], v[106:109]
	v_mfma_f32_16x16x32_bf16 v[98:101], v[144:147], v[176:179], v[98:101]
	v_mfma_f32_16x16x32_bf16 v[90:93], v[136:139], v[184:187], v[90:93]
	v_mfma_f32_16x16x32_bf16 v[82:85], v[144:147], v[184:187], v[82:85]
	v_mfma_f32_16x16x32_bf16 v[74:77], v[136:139], v[192:195], v[74:77]
	v_mfma_f32_16x16x32_bf16 v[66:69], v[144:147], v[192:195], v[66:69]
	v_mfma_f32_16x16x32_bf16 v[122:125], v[140:143], v[172:175], v[122:125]
	v_mfma_f32_16x16x32_bf16 v[114:117], v[148:151], v[172:175], v[114:117]
	v_mfma_f32_16x16x32_bf16 v[106:109], v[140:143], v[180:183], v[106:109]
	v_mfma_f32_16x16x32_bf16 v[98:101], v[148:151], v[180:183], v[98:101]
	v_mfma_f32_16x16x32_bf16 v[90:93], v[140:143], v[188:191], v[90:93]
	v_mfma_f32_16x16x32_bf16 v[82:85], v[148:151], v[188:191], v[82:85]
	v_mfma_f32_16x16x32_bf16 v[74:77], v[140:143], v[196:199], v[74:77]
	v_mfma_f32_16x16x32_bf16 v[66:69], v[148:151], v[196:199], v[66:69]
	v_mfma_f32_16x16x32_bf16 v[126:129], v[152:155], v[168:171], v[126:129]
	v_mfma_f32_16x16x32_bf16 v[118:121], v[160:163], v[168:171], v[118:121]
	v_mfma_f32_16x16x32_bf16 v[110:113], v[152:155], v[176:179], v[110:113]
	v_mfma_f32_16x16x32_bf16 v[102:105], v[160:163], v[176:179], v[102:105]
	v_mfma_f32_16x16x32_bf16 v[94:97], v[152:155], v[184:187], v[94:97]
	v_mfma_f32_16x16x32_bf16 v[86:89], v[160:163], v[184:187], v[86:89]
	v_mfma_f32_16x16x32_bf16 v[78:81], v[152:155], v[192:195], v[78:81]
	v_mfma_f32_16x16x32_bf16 v[70:73], v[160:163], v[192:195], v[70:73]
	v_mfma_f32_16x16x32_bf16 v[126:129], v[156:159], v[172:175], v[126:129]
	v_mfma_f32_16x16x32_bf16 v[118:121], v[164:167], v[172:175], v[118:121]
	v_mfma_f32_16x16x32_bf16 v[110:113], v[156:159], v[180:183], v[110:113]
	v_mfma_f32_16x16x32_bf16 v[102:105], v[164:167], v[180:183], v[102:105]
	v_mfma_f32_16x16x32_bf16 v[94:97], v[156:159], v[188:191], v[94:97]
	v_mfma_f32_16x16x32_bf16 v[86:89], v[164:167], v[188:191], v[86:89]
	v_mfma_f32_16x16x32_bf16 v[78:81], v[156:159], v[196:199], v[78:81]
	v_mfma_f32_16x16x32_bf16 v[70:73], v[164:167], v[196:199], v[70:73]
	s_barrier
	ds_read_b128 v[168:171], v134 offset:49152
	ds_read_b128 v[172:175], v134 offset:50176
	ds_read_b128 v[176:179], v134 offset:51200
	ds_read_b128 v[180:183], v134 offset:52224
	ds_read_b128 v[184:187], v134 offset:53248
	ds_read_b128 v[188:191], v134 offset:54272
	ds_read_b128 v[192:195], v134 offset:55296
	ds_read_b128 v[196:199], v134 offset:56320
	s_add_u32 s74, s22, 0x80
	s_addc_u32 s75, s23, 0
	s_add_i32 m0, s26, 0x18000
	s_nop 0
	global_load_lds_dwordx4 v132, s[74:75]
	s_add_u32 s74, s22, 0x20080
	s_addc_u32 s75, s23, 0
	s_add_i32 m0, s26, 0x19000
	s_nop 0
	global_load_lds_dwordx4 v132, s[74:75]
	s_add_u32 s74, s22, 0x40080
	s_addc_u32 s75, s23, 0
	s_add_i32 m0, s26, 0x1a000
	s_nop 0
	global_load_lds_dwordx4 v132, s[74:75]
	s_add_u32 s74, s22, 0x60080
	s_addc_u32 s75, s23, 0
	s_add_i32 m0, s26, 0x1b000
	s_nop 0
	global_load_lds_dwordx4 v132, s[74:75]
	s_waitcnt vmcnt(8)
	s_waitcnt lgkmcnt(0)
	s_barrier
	v_mfma_f32_16x16x32_bf16 v[58:61], v[136:139], v[168:171], v[58:61]
	v_mfma_f32_16x16x32_bf16 v[50:53], v[144:147], v[168:171], v[50:53]
	v_mfma_f32_16x16x32_bf16 v[42:45], v[136:139], v[176:179], v[42:45]
	v_mfma_f32_16x16x32_bf16 v[34:37], v[144:147], v[176:179], v[34:37]
	v_mfma_f32_16x16x32_bf16 v[26:29], v[136:139], v[184:187], v[26:29]
	v_mfma_f32_16x16x32_bf16 v[18:21], v[144:147], v[184:187], v[18:21]
	v_mfma_f32_16x16x32_bf16 v[10:13], v[136:139], v[192:195], v[10:13]
	v_mfma_f32_16x16x32_bf16 v[2:5], v[144:147], v[192:195], v[2:5]
	v_mfma_f32_16x16x32_bf16 v[58:61], v[140:143], v[172:175], v[58:61]
	v_mfma_f32_16x16x32_bf16 v[50:53], v[148:151], v[172:175], v[50:53]
	v_mfma_f32_16x16x32_bf16 v[42:45], v[140:143], v[180:183], v[42:45]
	v_mfma_f32_16x16x32_bf16 v[34:37], v[148:151], v[180:183], v[34:37]
	v_mfma_f32_16x16x32_bf16 v[26:29], v[140:143], v[188:191], v[26:29]
	v_mfma_f32_16x16x32_bf16 v[18:21], v[148:151], v[188:191], v[18:21]
	v_mfma_f32_16x16x32_bf16 v[10:13], v[140:143], v[196:199], v[10:13]
	v_mfma_f32_16x16x32_bf16 v[2:5], v[148:151], v[196:199], v[2:5]
	v_mfma_f32_16x16x32_bf16 v[62:65], v[152:155], v[168:171], v[62:65]
	v_mfma_f32_16x16x32_bf16 v[54:57], v[160:163], v[168:171], v[54:57]
	v_mfma_f32_16x16x32_bf16 v[46:49], v[152:155], v[176:179], v[46:49]
	v_mfma_f32_16x16x32_bf16 v[38:41], v[160:163], v[176:179], v[38:41]
	v_mfma_f32_16x16x32_bf16 v[30:33], v[152:155], v[184:187], v[30:33]
	v_mfma_f32_16x16x32_bf16 v[22:25], v[160:163], v[184:187], v[22:25]
	v_mfma_f32_16x16x32_bf16 v[14:17], v[152:155], v[192:195], v[14:17]
	v_mfma_f32_16x16x32_bf16 v[6:9], v[160:163], v[192:195], v[6:9]
	v_mfma_f32_16x16x32_bf16 v[62:65], v[156:159], v[172:175], v[62:65]
	v_mfma_f32_16x16x32_bf16 v[54:57], v[164:167], v[172:175], v[54:57]
	v_mfma_f32_16x16x32_bf16 v[46:49], v[156:159], v[180:183], v[46:49]
	v_mfma_f32_16x16x32_bf16 v[38:41], v[164:167], v[180:183], v[38:41]
	v_mfma_f32_16x16x32_bf16 v[30:33], v[156:159], v[188:191], v[30:33]
	v_mfma_f32_16x16x32_bf16 v[22:25], v[164:167], v[188:191], v[22:25]
	v_mfma_f32_16x16x32_bf16 v[14:17], v[156:159], v[196:199], v[14:17]
	v_mfma_f32_16x16x32_bf16 v[6:9], v[164:167], v[196:199], v[6:9]
	s_barrier
	s_add_i32 s72, s72, 2
	s_add_u32 s64, s64, 0x100
	s_addc_u32 s66, s66, 0
	s_add_u32 s68, s68, 0x100
	s_addc_u32 s70, s70, 0
TB_L8579_Aloop:
	s_cmp_eq_u32 s72, 28
	s_cselect_b32 s18, s60, s64
	s_cselect_b32 s19, s13, s66
	s_cselect_b32 s22, s62, s68
	s_cselect_b32 s23, s11, s70
	v_add_u32_e32 v130, 0x10000, v133
	ds_read_b128 v[136:139], v130
	ds_read_b128 v[140:143], v130 offset:1024
	ds_read_b128 v[144:147], v130 offset:2048
	ds_read_b128 v[148:151], v130 offset:3072
	v_add_u32_e32 v130, 0x14000, v133
	ds_read_b128 v[152:155], v130
	ds_read_b128 v[156:159], v130 offset:1024
	ds_read_b128 v[160:163], v130 offset:2048
	ds_read_b128 v[164:167], v130 offset:3072
	ds_read_b128 v[168:171], v134
	ds_read_b128 v[172:175], v134 offset:1024
	ds_read_b128 v[176:179], v134 offset:2048
	ds_read_b128 v[180:183], v134 offset:3072
	ds_read_b128 v[184:187], v134 offset:4096
	ds_read_b128 v[188:191], v134 offset:5120
	ds_read_b128 v[192:195], v134 offset:6144
	ds_read_b128 v[196:199], v134 offset:7168
	s_add_u32 s74, s64, 0x3ff80
	s_addc_u32 s75, s66, 0
	s_add_i32 m0, s26, 0xa000
	s_nop 0
	global_load_lds_dwordx4 v0, s[74:75]
	s_add_u32 s74, s64, 0x5ff80
	s_addc_u32 s75, s66, 0
	s_add_i32 m0, s26, 0xb000
	s_nop 0
	global_load_lds_dwordx4 v0, s[74:75]
	s_add_u32 s74, s64, 0x7ff80
	s_addc_u32 s75, s66, 0
	s_add_i32 m0, s26, 0xc000
	s_nop 0
	global_load_lds_dwordx4 v0, s[74:75]
	s_add_u32 s74, s64, 0x9ff80
	s_addc_u32 s75, s66, 0
	s_add_i32 m0, s26, 0xd000
	s_nop 0
	global_load_lds_dwordx4 v0, s[74:75]
	s_waitcnt vmcnt(8)
	s_waitcnt lgkmcnt(0)
	s_barrier
	v_mfma_f32_16x16x32_bf16 v[122:125], v[136:139], v[168:171], v[122:125]
	v_mfma_f32_16x16x32_bf16 v[114:117], v[144:147], v[168:171], v[114:117]
	v_mfma_f32_16x16x32_bf16 v[106:109], v[136:139], v[176:179], v[106:109]
	v_mfma_f32_16x16x32_bf16 v[98:101], v[144:147], v[176:179], v[98:101]
	v_mfma_f32_16x16x32_bf16 v[90:93], v[136:139], v[184:187], v[90:93]
	v_mfma_f32_16x16x32_bf16 v[82:85], v[144:147], v[184:187], v[82:85]
	v_mfma_f32_16x16x32_bf16 v[74:77], v[136:139], v[192:195], v[74:77]
	v_mfma_f32_16x16x32_bf16 v[66:69], v[144:147], v[192:195], v[66:69]
	v_mfma_f32_16x16x32_bf16 v[122:125], v[140:143], v[172:175], v[122:125]
	v_mfma_f32_16x16x32_bf16 v[114:117], v[148:151], v[172:175], v[114:117]
	v_mfma_f32_16x16x32_bf16 v[106:109], v[140:143], v[180:183], v[106:109]
	v_mfma_f32_16x16x32_bf16 v[98:101], v[148:151], v[180:183], v[98:101]
	v_mfma_f32_16x16x32_bf16 v[90:93], v[140:143], v[188:191], v[90:93]
	v_mfma_f32_16x16x32_bf16 v[82:85], v[148:151], v[188:191], v[82:85]
	v_mfma_f32_16x16x32_bf16 v[74:77], v[140:143], v[196:199], v[74:77]
	v_mfma_f32_16x16x32_bf16 v[66:69], v[148:151], v[196:199], v[66:69]
	v_mfma_f32_16x16x32_bf16 v[126:129], v[152:155], v[168:171], v[126:129]
	v_mfma_f32_16x16x32_bf16 v[118:121], v[160:163], v[168:171], v[118:121]
	v_mfma_f32_16x16x32_bf16 v[110:113], v[152:155], v[176:179], v[110:113]
	v_mfma_f32_16x16x32_bf16 v[102:105], v[160:163], v[176:179], v[102:105]
	v_mfma_f32_16x16x32_bf16 v[94:97], v[152:155], v[184:187], v[94:97]
	v_mfma_f32_16x16x32_bf16 v[86:89], v[160:163], v[184:187], v[86:89]
	v_mfma_f32_16x16x32_bf16 v[78:81], v[152:155], v[192:195], v[78:81]
	v_mfma_f32_16x16x32_bf16 v[70:73], v[160:163], v[192:195], v[70:73]
	v_mfma_f32_16x16x32_bf16 v[126:129], v[156:159], v[172:175], v[126:129]
	v_mfma_f32_16x16x32_bf16 v[118:121], v[164:167], v[172:175], v[118:121]
	v_mfma_f32_16x16x32_bf16 v[110:113], v[156:159], v[180:183], v[110:113]
	v_mfma_f32_16x16x32_bf16 v[102:105], v[164:167], v[180:183], v[102:105]
	v_mfma_f32_16x16x32_bf16 v[94:97], v[156:159], v[188:191], v[94:97]
	v_mfma_f32_16x16x32_bf16 v[86:89], v[164:167], v[188:191], v[86:89]
	v_mfma_f32_16x16x32_bf16 v[78:81], v[156:159], v[196:199], v[78:81]
	v_mfma_f32_16x16x32_bf16 v[70:73], v[164:167], v[196:199], v[70:73]
	s_barrier
	ds_read_b128 v[168:171], v134 offset:16384
	ds_read_b128 v[172:175], v134 offset:17408
	ds_read_b128 v[176:179], v134 offset:18432
	ds_read_b128 v[180:183], v134 offset:19456
	ds_read_b128 v[184:187], v134 offset:20480
	ds_read_b128 v[188:191], v134 offset:21504
	ds_read_b128 v[192:195], v134 offset:22528
	ds_read_b128 v[196:199], v134 offset:23552
	s_mov_b32 s74, s22
	s_mov_b32 s75, s23
	s_add_i32 m0, s26, 0x10000
	s_nop 0
	global_load_lds_dwordx4 v132, s[74:75]
	s_add_u32 s74, s22, 0x20000
	s_addc_u32 s75, s23, 0
	s_add_i32 m0, s26, 0x11000
	s_nop 0
	global_load_lds_dwordx4 v132, s[74:75]
	s_add_u32 s74, s22, 0x40000
	s_addc_u32 s75, s23, 0
	s_add_i32 m0, s26, 0x12000
	s_nop 0
	global_load_lds_dwordx4 v132, s[74:75]
	s_add_u32 s74, s22, 0x60000
	s_addc_u32 s75, s23, 0
	s_add_i32 m0, s26, 0x13000
	s_nop 0
	global_load_lds_dwordx4 v132, s[74:75]
	s_waitcnt vmcnt(8)
	s_waitcnt lgkmcnt(0)
	s_barrier
	v_mfma_f32_16x16x32_bf16 v[58:61], v[136:139], v[168:171], v[58:61]
	v_mfma_f32_16x16x32_bf16 v[50:53], v[144:147], v[168:171], v[50:53]
	v_mfma_f32_16x16x32_bf16 v[42:45], v[136:139], v[176:179], v[42:45]
	v_mfma_f32_16x16x32_bf16 v[34:37], v[144:147], v[176:179], v[34:37]
	v_mfma_f32_16x16x32_bf16 v[26:29], v[136:139], v[184:187], v[26:29]
	v_mfma_f32_16x16x32_bf16 v[18:21], v[144:147], v[184:187], v[18:21]
	v_mfma_f32_16x16x32_bf16 v[10:13], v[136:139], v[192:195], v[10:13]
	v_mfma_f32_16x16x32_bf16 v[2:5], v[144:147], v[192:195], v[2:5]
	v_mfma_f32_16x16x32_bf16 v[58:61], v[140:143], v[172:175], v[58:61]
	v_mfma_f32_16x16x32_bf16 v[50:53], v[148:151], v[172:175], v[50:53]
	v_mfma_f32_16x16x32_bf16 v[42:45], v[140:143], v[180:183], v[42:45]
	v_mfma_f32_16x16x32_bf16 v[34:37], v[148:151], v[180:183], v[34:37]
	v_mfma_f32_16x16x32_bf16 v[26:29], v[140:143], v[188:191], v[26:29]
	v_mfma_f32_16x16x32_bf16 v[18:21], v[148:151], v[188:191], v[18:21]
	v_mfma_f32_16x16x32_bf16 v[10:13], v[140:143], v[196:199], v[10:13]
	v_mfma_f32_16x16x32_bf16 v[2:5], v[148:151], v[196:199], v[2:5]
	v_mfma_f32_16x16x32_bf16 v[62:65], v[152:155], v[168:171], v[62:65]
	v_mfma_f32_16x16x32_bf16 v[54:57], v[160:163], v[168:171], v[54:57]
	v_mfma_f32_16x16x32_bf16 v[46:49], v[152:155], v[176:179], v[46:49]
	v_mfma_f32_16x16x32_bf16 v[38:41], v[160:163], v[176:179], v[38:41]
	v_mfma_f32_16x16x32_bf16 v[30:33], v[152:155], v[184:187], v[30:33]
	v_mfma_f32_16x16x32_bf16 v[22:25], v[160:163], v[184:187], v[22:25]
	v_mfma_f32_16x16x32_bf16 v[14:17], v[152:155], v[192:195], v[14:17]
	v_mfma_f32_16x16x32_bf16 v[6:9], v[160:163], v[192:195], v[6:9]
	v_mfma_f32_16x16x32_bf16 v[62:65], v[156:159], v[172:175], v[62:65]
	v_mfma_f32_16x16x32_bf16 v[54:57], v[164:167], v[172:175], v[54:57]
	v_mfma_f32_16x16x32_bf16 v[46:49], v[156:159], v[180:183], v[46:49]
	v_mfma_f32_16x16x32_bf16 v[38:41], v[164:167], v[180:183], v[38:41]
	v_mfma_f32_16x16x32_bf16 v[30:33], v[156:159], v[188:191], v[30:33]
	v_mfma_f32_16x16x32_bf16 v[22:25], v[164:167], v[188:191], v[22:25]
	v_mfma_f32_16x16x32_bf16 v[14:17], v[156:159], v[196:199], v[14:17]
	v_mfma_f32_16x16x32_bf16 v[6:9], v[164:167], v[196:199], v[6:9]
	s_barrier
	v_add_u32_e32 v130, 0x18000, v133
	ds_read_b128 v[136:139], v130
	ds_read_b128 v[140:143], v130 offset:1024
	ds_read_b128 v[144:147], v130 offset:2048
	ds_read_b128 v[148:151], v130 offset:3072
	v_add_u32_e32 v130, 0x1c000, v133
	ds_read_b128 v[152:155], v130
	ds_read_b128 v[156:159], v130 offset:1024
	ds_read_b128 v[160:163], v130 offset:2048
	ds_read_b128 v[164:167], v130 offset:3072
	ds_read_b128 v[168:171], v134 offset:32768
	ds_read_b128 v[172:175], v134 offset:33792
	ds_read_b128 v[176:179], v134 offset:34816
	ds_read_b128 v[180:183], v134 offset:35840
	ds_read_b128 v[184:187], v134 offset:36864
	ds_read_b128 v[188:191], v134 offset:37888
	ds_read_b128 v[192:195], v134 offset:38912
	ds_read_b128 v[196:199], v134 offset:39936
	s_add_u32 s74, s18, 0x40000
	s_addc_u32 s75, s19, 0
	s_add_i32 m0, s26, 0x2000
	s_nop 0
	global_load_lds_dwordx4 v0, s[74:75]
	s_add_u32 s74, s18, 0x60000
	s_addc_u32 s75, s19, 0
	s_add_i32 m0, s26, 0x3000
	s_nop 0
	global_load_lds_dwordx4 v0, s[74:75]
	s_add_u32 s74, s18, 0x80000
	s_addc_u32 s75, s19, 0
	s_add_i32 m0, s26, 0x4000
	s_nop 0
	global_load_lds_dwordx4 v0, s[74:75]
	s_add_u32 s74, s18, 0xa0000
	s_addc_u32 s75, s19, 0
	s_add_i32 m0, s26, 0x5000
	s_nop 0
	global_load_lds_dwordx4 v0, s[74:75]
	s_waitcnt vmcnt(8)
	s_waitcnt lgkmcnt(0)
	s_barrier
	v_mfma_f32_16x16x32_bf16 v[122:125], v[136:139], v[168:171], v[122:125]
	v_mfma_f32_16x16x32_bf16 v[114:117], v[144:147], v[168:171], v[114:117]
	v_mfma_f32_16x16x32_bf16 v[106:109], v[136:139], v[176:179], v[106:109]
	v_mfma_f32_16x16x32_bf16 v[98:101], v[144:147], v[176:179], v[98:101]
	v_mfma_f32_16x16x32_bf16 v[90:93], v[136:139], v[184:187], v[90:93]
	v_mfma_f32_16x16x32_bf16 v[82:85], v[144:147], v[184:187], v[82:85]
	v_mfma_f32_16x16x32_bf16 v[74:77], v[136:139], v[192:195], v[74:77]
	v_mfma_f32_16x16x32_bf16 v[66:69], v[144:147], v[192:195], v[66:69]
	v_mfma_f32_16x16x32_bf16 v[122:125], v[140:143], v[172:175], v[122:125]
	v_mfma_f32_16x16x32_bf16 v[114:117], v[148:151], v[172:175], v[114:117]
	v_mfma_f32_16x16x32_bf16 v[106:109], v[140:143], v[180:183], v[106:109]
	v_mfma_f32_16x16x32_bf16 v[98:101], v[148:151], v[180:183], v[98:101]
	v_mfma_f32_16x16x32_bf16 v[90:93], v[140:143], v[188:191], v[90:93]
	v_mfma_f32_16x16x32_bf16 v[82:85], v[148:151], v[188:191], v[82:85]
	v_mfma_f32_16x16x32_bf16 v[74:77], v[140:143], v[196:199], v[74:77]
	v_mfma_f32_16x16x32_bf16 v[66:69], v[148:151], v[196:199], v[66:69]
	v_mfma_f32_16x16x32_bf16 v[126:129], v[152:155], v[168:171], v[126:129]
	v_mfma_f32_16x16x32_bf16 v[118:121], v[160:163], v[168:171], v[118:121]
	v_mfma_f32_16x16x32_bf16 v[110:113], v[152:155], v[176:179], v[110:113]
	v_mfma_f32_16x16x32_bf16 v[102:105], v[160:163], v[176:179], v[102:105]
	v_mfma_f32_16x16x32_bf16 v[94:97], v[152:155], v[184:187], v[94:97]
	v_mfma_f32_16x16x32_bf16 v[86:89], v[160:163], v[184:187], v[86:89]
	v_mfma_f32_16x16x32_bf16 v[78:81], v[152:155], v[192:195], v[78:81]
	v_mfma_f32_16x16x32_bf16 v[70:73], v[160:163], v[192:195], v[70:73]
	v_mfma_f32_16x16x32_bf16 v[126:129], v[156:159], v[172:175], v[126:129]
	v_mfma_f32_16x16x32_bf16 v[118:121], v[164:167], v[172:175], v[118:121]
	v_mfma_f32_16x16x32_bf16 v[110:113], v[156:159], v[180:183], v[110:113]
	v_mfma_f32_16x16x32_bf16 v[102:105], v[164:167], v[180:183], v[102:105]
	v_mfma_f32_16x16x32_bf16 v[94:97], v[156:159], v[188:191], v[94:97]
	v_mfma_f32_16x16x32_bf16 v[86:89], v[164:167], v[188:191], v[86:89]
	v_mfma_f32_16x16x32_bf16 v[78:81], v[156:159], v[196:199], v[78:81]
	v_mfma_f32_16x16x32_bf16 v[70:73], v[164:167], v[196:199], v[70:73]
	s_barrier
	ds_read_b128 v[168:171], v134 offset:49152
	ds_read_b128 v[172:175], v134 offset:50176
	ds_read_b128 v[176:179], v134 offset:51200
	ds_read_b128 v[180:183], v134 offset:52224
	ds_read_b128 v[184:187], v134 offset:53248
	ds_read_b128 v[188:191], v134 offset:54272
	ds_read_b128 v[192:195], v134 offset:55296
	ds_read_b128 v[196:199], v134 offset:56320
	s_add_u32 s74, s22, 0x80
	s_addc_u32 s75, s23, 0
	s_add_i32 m0, s26, 0x18000
	s_nop 0
	global_load_lds_dwordx4 v132, s[74:75]
	s_add_u32 s74, s22, 0x20080
	s_addc_u32 s75, s23, 0
	s_add_i32 m0, s26, 0x19000
	s_nop 0
	global_load_lds_dwordx4 v132, s[74:75]
	s_add_u32 s74, s22, 0x40080
	s_addc_u32 s75, s23, 0
	s_add_i32 m0, s26, 0x1a000
	s_nop 0
	global_load_lds_dwordx4 v132, s[74:75]
	s_add_u32 s74, s22, 0x60080
	s_addc_u32 s75, s23, 0
	s_add_i32 m0, s26, 0x1b000
	s_nop 0
	global_load_lds_dwordx4 v132, s[74:75]
	s_waitcnt vmcnt(8)
	s_waitcnt lgkmcnt(0)
	s_barrier
	v_mfma_f32_16x16x32_bf16 v[58:61], v[136:139], v[168:171], v[58:61]
	v_mfma_f32_16x16x32_bf16 v[50:53], v[144:147], v[168:171], v[50:53]
	v_mfma_f32_16x16x32_bf16 v[42:45], v[136:139], v[176:179], v[42:45]
	v_mfma_f32_16x16x32_bf16 v[34:37], v[144:147], v[176:179], v[34:37]
	v_mfma_f32_16x16x32_bf16 v[26:29], v[136:139], v[184:187], v[26:29]
	v_mfma_f32_16x16x32_bf16 v[18:21], v[144:147], v[184:187], v[18:21]
	v_mfma_f32_16x16x32_bf16 v[10:13], v[136:139], v[192:195], v[10:13]
	v_mfma_f32_16x16x32_bf16 v[2:5], v[144:147], v[192:195], v[2:5]
	v_mfma_f32_16x16x32_bf16 v[58:61], v[140:143], v[172:175], v[58:61]
	v_mfma_f32_16x16x32_bf16 v[50:53], v[148:151], v[172:175], v[50:53]
	v_mfma_f32_16x16x32_bf16 v[42:45], v[140:143], v[180:183], v[42:45]
	v_mfma_f32_16x16x32_bf16 v[34:37], v[148:151], v[180:183], v[34:37]
	v_mfma_f32_16x16x32_bf16 v[26:29], v[140:143], v[188:191], v[26:29]
	v_mfma_f32_16x16x32_bf16 v[18:21], v[148:151], v[188:191], v[18:21]
	v_mfma_f32_16x16x32_bf16 v[10:13], v[140:143], v[196:199], v[10:13]
	v_mfma_f32_16x16x32_bf16 v[2:5], v[148:151], v[196:199], v[2:5]
	v_mfma_f32_16x16x32_bf16 v[62:65], v[152:155], v[168:171], v[62:65]
	v_mfma_f32_16x16x32_bf16 v[54:57], v[160:163], v[168:171], v[54:57]
	v_mfma_f32_16x16x32_bf16 v[46:49], v[152:155], v[176:179], v[46:49]
	v_mfma_f32_16x16x32_bf16 v[38:41], v[160:163], v[176:179], v[38:41]
	v_mfma_f32_16x16x32_bf16 v[30:33], v[152:155], v[184:187], v[30:33]
	v_mfma_f32_16x16x32_bf16 v[22:25], v[160:163], v[184:187], v[22:25]
	v_mfma_f32_16x16x32_bf16 v[14:17], v[152:155], v[192:195], v[14:17]
	v_mfma_f32_16x16x32_bf16 v[6:9], v[160:163], v[192:195], v[6:9]
	v_mfma_f32_16x16x32_bf16 v[62:65], v[156:159], v[172:175], v[62:65]
	v_mfma_f32_16x16x32_bf16 v[54:57], v[164:167], v[172:175], v[54:57]
	v_mfma_f32_16x16x32_bf16 v[46:49], v[156:159], v[180:183], v[46:49]
	v_mfma_f32_16x16x32_bf16 v[38:41], v[164:167], v[180:183], v[38:41]
	v_mfma_f32_16x16x32_bf16 v[30:33], v[156:159], v[188:191], v[30:33]
	v_mfma_f32_16x16x32_bf16 v[22:25], v[164:167], v[188:191], v[22:25]
	v_mfma_f32_16x16x32_bf16 v[14:17], v[156:159], v[196:199], v[14:17]
	v_mfma_f32_16x16x32_bf16 v[6:9], v[164:167], v[196:199], v[6:9]
	s_barrier
	s_add_i32 s72, s72, 2
	s_add_u32 s64, s64, 0x100
	s_addc_u32 s66, s66, 0
	s_add_u32 s68, s68, 0x100
	s_addc_u32 s70, s70, 0
	s_cmp_gt_u32 s72, 29
	s_cbranch_scc0 TB_L8579_Aloop
	s_branch TB_L8579_exit
TB_L8579_Bpeel:
	s_cmp_eq_u32 s72, 28
	s_cselect_b32 s18, s60, s64
	s_cselect_b32 s19, s13, s66
	s_cselect_b32 s22, s62, s68
	s_cselect_b32 s23, s11, s70
	v_add_u32_e32 v130, 0x10000, v133
	ds_read_b128 v[136:139], v130
	ds_read_b128 v[140:143], v130 offset:1024
	ds_read_b128 v[144:147], v130 offset:2048
	ds_read_b128 v[148:151], v130 offset:3072
	v_add_u32_e32 v130, 0x14000, v133
	ds_read_b128 v[152:155], v130
	ds_read_b128 v[156:159], v130 offset:1024
	ds_read_b128 v[160:163], v130 offset:2048
	ds_read_b128 v[164:167], v130 offset:3072
	ds_read_b128 v[168:171], v134
	ds_read_b128 v[172:175], v134 offset:1024
	ds_read_b128 v[176:179], v134 offset:2048
	ds_read_b128 v[180:183], v134 offset:3072
	ds_read_b128 v[184:187], v134 offset:4096
	ds_read_b128 v[188:191], v134 offset:5120
	ds_read_b128 v[192:195], v134 offset:6144
	ds_read_b128 v[196:199], v134 offset:7168
	s_add_u32 s74, s18, 0xfffe0000
	s_addc_u32 s75, s19, -1
	s_add_i32 m0, s26, 0xfffff000
	s_nop 0
	global_load_lds_dwordx4 v0, s[74:75]
	s_mov_b32 s74, s18
	s_mov_b32 s75, s19
	s_mov_b32 m0, s26
	s_nop 0
	global_load_lds_dwordx4 v0, s[74:75]
	s_add_u32 s74, s64, 0x9ff80
	s_addc_u32 s75, s66, 0
	s_add_i32 m0, s26, 0xd000
	s_nop 0
	global_load_lds_dwordx4 v0, s[74:75]
	s_add_u32 s74, s64, 0xbff80
	s_addc_u32 s75, s66, 0
	s_add_i32 m0, s26, 0xe000
	s_nop 0
	global_load_lds_dwordx4 v0, s[74:75]
	s_waitcnt vmcnt(8)
	s_waitcnt lgkmcnt(0)
	s_barrier
	v_mfma_f32_16x16x32_bf16 v[122:125], v[136:139], v[168:171], 0
	v_mfma_f32_16x16x32_bf16 v[114:117], v[144:147], v[168:171], 0
	v_mfma_f32_16x16x32_bf16 v[106:109], v[136:139], v[176:179], 0
	v_mfma_f32_16x16x32_bf16 v[98:101], v[144:147], v[176:179], 0
	v_mfma_f32_16x16x32_bf16 v[90:93], v[136:139], v[184:187], 0
	v_mfma_f32_16x16x32_bf16 v[82:85], v[144:147], v[184:187], 0
	v_mfma_f32_16x16x32_bf16 v[74:77], v[136:139], v[192:195], 0
	v_mfma_f32_16x16x32_bf16 v[66:69], v[144:147], v[192:195], 0
	v_mfma_f32_16x16x32_bf16 v[122:125], v[140:143], v[172:175], v[122:125]
	v_mfma_f32_16x16x32_bf16 v[114:117], v[148:151], v[172:175], v[114:117]
	v_mfma_f32_16x16x32_bf16 v[106:109], v[140:143], v[180:183], v[106:109]
	v_mfma_f32_16x16x32_bf16 v[98:101], v[148:151], v[180:183], v[98:101]
	v_mfma_f32_16x16x32_bf16 v[90:93], v[140:143], v[188:191], v[90:93]
	v_mfma_f32_16x16x32_bf16 v[82:85], v[148:151], v[188:191], v[82:85]
	v_mfma_f32_16x16x32_bf16 v[74:77], v[140:143], v[196:199], v[74:77]
	v_mfma_f32_16x16x32_bf16 v[66:69], v[148:151], v[196:199], v[66:69]
	v_mfma_f32_16x16x32_bf16 v[126:129], v[152:155], v[168:171], 0
	v_mfma_f32_16x16x32_bf16 v[118:121], v[160:163], v[168:171], 0
	v_mfma_f32_16x16x32_bf16 v[110:113], v[152:155], v[176:179], 0
	v_mfma_f32_16x16x32_bf16 v[102:105], v[160:163], v[176:179], 0
	v_mfma_f32_16x16x32_bf16 v[94:97], v[152:155], v[184:187], 0
	v_mfma_f32_16x16x32_bf16 v[86:89], v[160:163], v[184:187], 0
	v_mfma_f32_16x16x32_bf16 v[78:81], v[152:155], v[192:195], 0
	v_mfma_f32_16x16x32_bf16 v[70:73], v[160:163], v[192:195], 0
	v_mfma_f32_16x16x32_bf16 v[126:129], v[156:159], v[172:175], v[126:129]
	v_mfma_f32_16x16x32_bf16 v[118:121], v[164:167], v[172:175], v[118:121]
	v_mfma_f32_16x16x32_bf16 v[110:113], v[156:159], v[180:183], v[110:113]
	v_mfma_f32_16x16x32_bf16 v[102:105], v[164:167], v[180:183], v[102:105]
	v_mfma_f32_16x16x32_bf16 v[94:97], v[156:159], v[188:191], v[94:97]
	v_mfma_f32_16x16x32_bf16 v[86:89], v[164:167], v[188:191], v[86:89]
	v_mfma_f32_16x16x32_bf16 v[78:81], v[156:159], v[196:199], v[78:81]
	v_mfma_f32_16x16x32_bf16 v[70:73], v[164:167], v[196:199], v[70:73]
	s_barrier
	ds_read_b128 v[168:171], v134 offset:16384
	ds_read_b128 v[172:175], v134 offset:17408
	ds_read_b128 v[176:179], v134 offset:18432
	ds_read_b128 v[180:183], v134 offset:19456
	ds_read_b128 v[184:187], v134 offset:20480
	ds_read_b128 v[188:191], v134 offset:21504
	ds_read_b128 v[192:195], v134 offset:22528
	ds_read_b128 v[196:199], v134 offset:23552
	s_add_u32 s74, s22, 0x60000
	s_addc_u32 s75, s23, 0
	s_add_i32 m0, s26, 0x13000
	s_nop 0
	global_load_lds_dwordx4 v132, s[74:75]
	s_add_u32 s74, s22, 0x80000
	s_addc_u32 s75, s23, 0
	s_add_i32 m0, s26, 0x14000
	s_nop 0
	global_load_lds_dwordx4 v132, s[74:75]
	s_add_u32 s74, s22, 0xa0000
	s_addc_u32 s75, s23, 0
	s_add_i32 m0, s26, 0x15000
	s_nop 0
	global_load_lds_dwordx4 v132, s[74:75]
	s_add_u32 s74, s22, 0xc0000
	s_addc_u32 s75, s23, 0
	s_add_i32 m0, s26, 0x16000
	s_nop 0
	global_load_lds_dwordx4 v132, s[74:75]
	s_waitcnt vmcnt(8)
	s_waitcnt lgkmcnt(0)
	s_barrier
	v_mfma_f32_16x16x32_bf16 v[58:61], v[136:139], v[168:171], 0
	v_mfma_f32_16x16x32_bf16 v[50:53], v[144:147], v[168:171], 0
	v_mfma_f32_16x16x32_bf16 v[42:45], v[136:139], v[176:179], 0
	v_mfma_f32_16x16x32_bf16 v[34:37], v[144:147], v[176:179], 0
	v_mfma_f32_16x16x32_bf16 v[26:29], v[136:139], v[184:187], 0
	v_mfma_f32_16x16x32_bf16 v[18:21], v[144:147], v[184:187], 0
	v_mfma_f32_16x16x32_bf16 v[10:13], v[136:139], v[192:195], 0
	v_mfma_f32_16x16x32_bf16 v[2:5], v[144:147], v[192:195], 0
	v_mfma_f32_16x16x32_bf16 v[58:61], v[140:143], v[172:175], v[58:61]
	v_mfma_f32_16x16x32_bf16 v[50:53], v[148:151], v[172:175], v[50:53]
	v_mfma_f32_16x16x32_bf16 v[42:45], v[140:143], v[180:183], v[42:45]
	v_mfma_f32_16x16x32_bf16 v[34:37], v[148:151], v[180:183], v[34:37]
	v_mfma_f32_16x16x32_bf16 v[26:29], v[140:143], v[188:191], v[26:29]
	v_mfma_f32_16x16x32_bf16 v[18:21], v[148:151], v[188:191], v[18:21]
	v_mfma_f32_16x16x32_bf16 v[10:13], v[140:143], v[196:199], v[10:13]
	v_mfma_f32_16x16x32_bf16 v[2:5], v[148:151], v[196:199], v[2:5]
	v_mfma_f32_16x16x32_bf16 v[62:65], v[152:155], v[168:171], 0
	v_mfma_f32_16x16x32_bf16 v[54:57], v[160:163], v[168:171], 0
	v_mfma_f32_16x16x32_bf16 v[46:49], v[152:155], v[176:179], 0
	v_mfma_f32_16x16x32_bf16 v[38:41], v[160:163], v[176:179], 0
	v_mfma_f32_16x16x32_bf16 v[30:33], v[152:155], v[184:187], 0
	v_mfma_f32_16x16x32_bf16 v[22:25], v[160:163], v[184:187], 0
	v_mfma_f32_16x16x32_bf16 v[14:17], v[152:155], v[192:195], 0
	v_mfma_f32_16x16x32_bf16 v[6:9], v[160:163], v[192:195], 0
	v_mfma_f32_16x16x32_bf16 v[62:65], v[156:159], v[172:175], v[62:65]
	v_mfma_f32_16x16x32_bf16 v[54:57], v[164:167], v[172:175], v[54:57]
	v_mfma_f32_16x16x32_bf16 v[46:49], v[156:159], v[180:183], v[46:49]
	v_mfma_f32_16x16x32_bf16 v[38:41], v[164:167], v[180:183], v[38:41]
	v_mfma_f32_16x16x32_bf16 v[30:33], v[156:159], v[188:191], v[30:33]
	v_mfma_f32_16x16x32_bf16 v[22:25], v[164:167], v[188:191], v[22:25]
	v_mfma_f32_16x16x32_bf16 v[14:17], v[156:159], v[196:199], v[14:17]
	v_mfma_f32_16x16x32_bf16 v[6:9], v[164:167], v[196:199], v[6:9]
	s_barrier
	v_add_u32_e32 v130, 0x18000, v133
	ds_read_b128 v[136:139], v130
	ds_read_b128 v[140:143], v130 offset:1024
	ds_read_b128 v[144:147], v130 offset:2048
	ds_read_b128 v[148:151], v130 offset:3072
	v_add_u32_e32 v130, 0x1c000, v133
	ds_read_b128 v[152:155], v130
	ds_read_b128 v[156:159], v130 offset:1024
	ds_read_b128 v[160:163], v130 offset:2048
	ds_read_b128 v[164:167], v130 offset:3072
	ds_read_b128 v[168:171], v134 offset:32768
	ds_read_b128 v[172:175], v134 offset:33792
	ds_read_b128 v[176:179], v134 offset:34816
	ds_read_b128 v[180:183], v134 offset:35840
	ds_read_b128 v[184:187], v134 offset:36864
	ds_read_b128 v[188:191], v134 offset:37888
	ds_read_b128 v[192:195], v134 offset:38912
	ds_read_b128 v[196:199], v134 offset:39936
	s_add_u32 s74, s18, 0xfffe0080
	s_addc_u32 s75, s19, -1
	s_add_i32 m0, s26, 0x7000
	s_nop 0
	global_load_lds_dwordx4 v0, s[74:75]
	s_add_u32 s74, s18, 0x80
	s_addc_u32 s75, s19, 0
	s_add_i32 m0, s26, 0x8000
	s_nop 0
	global_load_lds_dwordx4 v0, s[74:75]
	s_add_u32 s74, s18, 0xa0000
	s_addc_u32 s75, s19, 0
	s_add_i32 m0, s26, 0x5000
	s_nop 0
	global_load_lds_dwordx4 v0, s[74:75]
	s_add_u32 s74, s18, 0xc0000
	s_addc_u32 s75, s19, 0
	s_add_i32 m0, s26, 0x6000
	s_nop 0
	global_load_lds_dwordx4 v0, s[74:75]
	s_waitcnt vmcnt(8)
	s_waitcnt lgkmcnt(0)
	s_barrier
	v_mfma_f32_16x16x32_bf16 v[122:125], v[136:139], v[168:171], v[122:125]
	v_mfma_f32_16x16x32_bf16 v[114:117], v[144:147], v[168:171], v[114:117]
	v_mfma_f32_16x16x32_bf16 v[106:109], v[136:139], v[176:179], v[106:109]
	v_mfma_f32_16x16x32_bf16 v[98:101], v[144:147], v[176:179], v[98:101]
	v_mfma_f32_16x16x32_bf16 v[90:93], v[136:139], v[184:187], v[90:93]
	v_mfma_f32_16x16x32_bf16 v[82:85], v[144:147], v[184:187], v[82:85]
	v_mfma_f32_16x16x32_bf16 v[74:77], v[136:139], v[192:195], v[74:77]
	v_mfma_f32_16x16x32_bf16 v[66:69], v[144:147], v[192:195], v[66:69]
	v_mfma_f32_16x16x32_bf16 v[122:125], v[140:143], v[172:175], v[122:125]
	v_mfma_f32_16x16x32_bf16 v[114:117], v[148:151], v[172:175], v[114:117]
	v_mfma_f32_16x16x32_bf16 v[106:109], v[140:143], v[180:183], v[106:109]
	v_mfma_f32_16x16x32_bf16 v[98:101], v[148:151], v[180:183], v[98:101]
	v_mfma_f32_16x16x32_bf16 v[90:93], v[140:143], v[188:191], v[90:93]
	v_mfma_f32_16x16x32_bf16 v[82:85], v[148:151], v[188:191], v[82:85]
	v_mfma_f32_16x16x32_bf16 v[74:77], v[140:143], v[196:199], v[74:77]
	v_mfma_f32_16x16x32_bf16 v[66:69], v[148:151], v[196:199], v[66:69]
	v_mfma_f32_16x16x32_bf16 v[126:129], v[152:155], v[168:171], v[126:129]
	v_mfma_f32_16x16x32_bf16 v[118:121], v[160:163], v[168:171], v[118:121]
	v_mfma_f32_16x16x32_bf16 v[110:113], v[152:155], v[176:179], v[110:113]
	v_mfma_f32_16x16x32_bf16 v[102:105], v[160:163], v[176:179], v[102:105]
	v_mfma_f32_16x16x32_bf16 v[94:97], v[152:155], v[184:187], v[94:97]
	v_mfma_f32_16x16x32_bf16 v[86:89], v[160:163], v[184:187], v[86:89]
	v_mfma_f32_16x16x32_bf16 v[78:81], v[152:155], v[192:195], v[78:81]
	v_mfma_f32_16x16x32_bf16 v[70:73], v[160:163], v[192:195], v[70:73]
	v_mfma_f32_16x16x32_bf16 v[126:129], v[156:159], v[172:175], v[126:129]
	v_mfma_f32_16x16x32_bf16 v[118:121], v[164:167], v[172:175], v[118:121]
	v_mfma_f32_16x16x32_bf16 v[110:113], v[156:159], v[180:183], v[110:113]
	v_mfma_f32_16x16x32_bf16 v[102:105], v[164:167], v[180:183], v[102:105]
	v_mfma_f32_16x16x32_bf16 v[94:97], v[156:159], v[188:191], v[94:97]
	v_mfma_f32_16x16x32_bf16 v[86:89], v[164:167], v[188:191], v[86:89]
	v_mfma_f32_16x16x32_bf16 v[78:81], v[156:159], v[196:199], v[78:81]
	v_mfma_f32_16x16x32_bf16 v[70:73], v[164:167], v[196:199], v[70:73]
	s_barrier
	ds_read_b128 v[168:171], v134 offset:49152
	ds_read_b128 v[172:175], v134 offset:50176
	ds_read_b128 v[176:179], v134 offset:51200
	ds_read_b128 v[180:183], v134 offset:52224
	ds_read_b128 v[184:187], v134 offset:53248
	ds_read_b128 v[188:191], v134 offset:54272
	ds_read_b128 v[192:195], v134 offset:55296
	ds_read_b128 v[196:199], v134 offset:56320
	s_add_u32 s74, s22, 0x60080
	s_addc_u32 s75, s23, 0
	s_add_i32 m0, s26, 0x1b000
	s_nop 0
	global_load_lds_dwordx4 v132, s[74:75]
	s_add_u32 s74, s22, 0x80080
	s_addc_u32 s75, s23, 0
	s_add_i32 m0, s26, 0x1c000
	s_nop 0
	global_load_lds_dwordx4 v132, s[74:75]
	s_add_u32 s74, s22, 0xa0080
	s_addc_u32 s75, s23, 0
	s_add_i32 m0, s26, 0x1d000
	s_nop 0
	global_load_lds_dwordx4 v132, s[74:75]
	s_add_u32 s74, s22, 0xc0080
	s_addc_u32 s75, s23, 0
	s_add_i32 m0, s26, 0x1e000
	s_nop 0
	global_load_lds_dwordx4 v132, s[74:75]
	s_waitcnt vmcnt(8)
	s_waitcnt lgkmcnt(0)
	s_barrier
	v_mfma_f32_16x16x32_bf16 v[58:61], v[136:139], v[168:171], v[58:61]
	v_mfma_f32_16x16x32_bf16 v[50:53], v[144:147], v[168:171], v[50:53]
	v_mfma_f32_16x16x32_bf16 v[42:45], v[136:139], v[176:179], v[42:45]
	v_mfma_f32_16x16x32_bf16 v[34:37], v[144:147], v[176:179], v[34:37]
	v_mfma_f32_16x16x32_bf16 v[26:29], v[136:139], v[184:187], v[26:29]
	v_mfma_f32_16x16x32_bf16 v[18:21], v[144:147], v[184:187], v[18:21]
	v_mfma_f32_16x16x32_bf16 v[10:13], v[136:139], v[192:195], v[10:13]
	v_mfma_f32_16x16x32_bf16 v[2:5], v[144:147], v[192:195], v[2:5]
	v_mfma_f32_16x16x32_bf16 v[58:61], v[140:143], v[172:175], v[58:61]
	v_mfma_f32_16x16x32_bf16 v[50:53], v[148:151], v[172:175], v[50:53]
	v_mfma_f32_16x16x32_bf16 v[42:45], v[140:143], v[180:183], v[42:45]
	v_mfma_f32_16x16x32_bf16 v[34:37], v[148:151], v[180:183], v[34:37]
	v_mfma_f32_16x16x32_bf16 v[26:29], v[140:143], v[188:191], v[26:29]
	v_mfma_f32_16x16x32_bf16 v[18:21], v[148:151], v[188:191], v[18:21]
	v_mfma_f32_16x16x32_bf16 v[10:13], v[140:143], v[196:199], v[10:13]
	v_mfma_f32_16x16x32_bf16 v[2:5], v[148:151], v[196:199], v[2:5]
	v_mfma_f32_16x16x32_bf16 v[62:65], v[152:155], v[168:171], v[62:65]
	v_mfma_f32_16x16x32_bf16 v[54:57], v[160:163], v[168:171], v[54:57]
	v_mfma_f32_16x16x32_bf16 v[46:49], v[152:155], v[176:179], v[46:49]
	v_mfma_f32_16x16x32_bf16 v[38:41], v[160:163], v[176:179], v[38:41]
	v_mfma_f32_16x16x32_bf16 v[30:33], v[152:155], v[184:187], v[30:33]
	v_mfma_f32_16x16x32_bf16 v[22:25], v[160:163], v[184:187], v[22:25]
	v_mfma_f32_16x16x32_bf16 v[14:17], v[152:155], v[192:195], v[14:17]
	v_mfma_f32_16x16x32_bf16 v[6:9], v[160:163], v[192:195], v[6:9]
	v_mfma_f32_16x16x32_bf16 v[62:65], v[156:159], v[172:175], v[62:65]
	v_mfma_f32_16x16x32_bf16 v[54:57], v[164:167], v[172:175], v[54:57]
	v_mfma_f32_16x16x32_bf16 v[46:49], v[156:159], v[180:183], v[46:49]
	v_mfma_f32_16x16x32_bf16 v[38:41], v[164:167], v[180:183], v[38:41]
	v_mfma_f32_16x16x32_bf16 v[30:33], v[156:159], v[188:191], v[30:33]
	v_mfma_f32_16x16x32_bf16 v[22:25], v[164:167], v[188:191], v[22:25]
	v_mfma_f32_16x16x32_bf16 v[14:17], v[156:159], v[196:199], v[14:17]
	v_mfma_f32_16x16x32_bf16 v[6:9], v[164:167], v[196:199], v[6:9]
	s_barrier
	s_add_i32 s72, s72, 2
	s_add_u32 s64, s64, 0x100
	s_addc_u32 s66, s66, 0
	s_add_u32 s68, s68, 0x100
	s_addc_u32 s70, s70, 0
TB_L8579_Bloop:
	s_cmp_eq_u32 s72, 28
	s_cselect_b32 s18, s60, s64
	s_cselect_b32 s19, s13, s66
	s_cselect_b32 s22, s62, s68
	s_cselect_b32 s23, s11, s70
	v_add_u32_e32 v130, 0x10000, v133
	ds_read_b128 v[136:139], v130
	ds_read_b128 v[140:143], v130 offset:1024
	ds_read_b128 v[144:147], v130 offset:2048
	ds_read_b128 v[148:151], v130 offset:3072
	v_add_u32_e32 v130, 0x14000, v133
	ds_read_b128 v[152:155], v130
	ds_read_b128 v[156:159], v130 offset:1024
	ds_read_b128 v[160:163], v130 offset:2048
	ds_read_b128 v[164:167], v130 offset:3072
	ds_read_b128 v[168:171], v134
	ds_read_b128 v[172:175], v134 offset:1024
	ds_read_b128 v[176:179], v134 offset:2048
	ds_read_b128 v[180:183], v134 offset:3072
	ds_read_b128 v[184:187], v134 offset:4096
	ds_read_b128 v[188:191], v134 offset:5120
	ds_read_b128 v[192:195], v134 offset:6144
	ds_read_b128 v[196:199], v134 offset:7168
	s_add_u32 s74, s18, 0xfffe0000
	s_addc_u32 s75, s19, -1
	s_add_i32 m0, s26, 0xfffff000
	s_nop 0
	global_load_lds_dwordx4 v0, s[74:75]
	s_mov_b32 s74, s18
	s_mov_b32 s75, s19
	s_mov_b32 m0, s26
	s_nop 0
	global_load_lds_dwordx4 v0, s[74:75]
	s_add_u32 s74, s64, 0x9ff80
	s_addc_u32 s75, s66, 0
	s_add_i32 m0, s26, 0xd000
	s_nop 0
	global_load_lds_dwordx4 v0, s[74:75]
	s_add_u32 s74, s64, 0xbff80
	s_addc_u32 s75, s66, 0
	s_add_i32 m0, s26, 0xe000
	s_nop 0
	global_load_lds_dwordx4 v0, s[74:75]
	s_waitcnt vmcnt(8)
	s_waitcnt lgkmcnt(0)
	s_barrier
	v_mfma_f32_16x16x32_bf16 v[122:125], v[136:139], v[168:171], v[122:125]
	v_mfma_f32_16x16x32_bf16 v[114:117], v[144:147], v[168:171], v[114:117]
	v_mfma_f32_16x16x32_bf16 v[106:109], v[136:139], v[176:179], v[106:109]
	v_mfma_f32_16x16x32_bf16 v[98:101], v[144:147], v[176:179], v[98:101]
	v_mfma_f32_16x16x32_bf16 v[90:93], v[136:139], v[184:187], v[90:93]
	v_mfma_f32_16x16x32_bf16 v[82:85], v[144:147], v[184:187], v[82:85]
	v_mfma_f32_16x16x32_bf16 v[74:77], v[136:139], v[192:195], v[74:77]
	v_mfma_f32_16x16x32_bf16 v[66:69], v[144:147], v[192:195], v[66:69]
	v_mfma_f32_16x16x32_bf16 v[122:125], v[140:143], v[172:175], v[122:125]
	v_mfma_f32_16x16x32_bf16 v[114:117], v[148:151], v[172:175], v[114:117]
	v_mfma_f32_16x16x32_bf16 v[106:109], v[140:143], v[180:183], v[106:109]
	v_mfma_f32_16x16x32_bf16 v[98:101], v[148:151], v[180:183], v[98:101]
	v_mfma_f32_16x16x32_bf16 v[90:93], v[140:143], v[188:191], v[90:93]
	v_mfma_f32_16x16x32_bf16 v[82:85], v[148:151], v[188:191], v[82:85]
	v_mfma_f32_16x16x32_bf16 v[74:77], v[140:143], v[196:199], v[74:77]
	v_mfma_f32_16x16x32_bf16 v[66:69], v[148:151], v[196:199], v[66:69]
	v_mfma_f32_16x16x32_bf16 v[126:129], v[152:155], v[168:171], v[126:129]
	v_mfma_f32_16x16x32_bf16 v[118:121], v[160:163], v[168:171], v[118:121]
	v_mfma_f32_16x16x32_bf16 v[110:113], v[152:155], v[176:179], v[110:113]
	v_mfma_f32_16x16x32_bf16 v[102:105], v[160:163], v[176:179], v[102:105]
	v_mfma_f32_16x16x32_bf16 v[94:97], v[152:155], v[184:187], v[94:97]
	v_mfma_f32_16x16x32_bf16 v[86:89], v[160:163], v[184:187], v[86:89]
	v_mfma_f32_16x16x32_bf16 v[78:81], v[152:155], v[192:195], v[78:81]
	v_mfma_f32_16x16x32_bf16 v[70:73], v[160:163], v[192:195], v[70:73]
	v_mfma_f32_16x16x32_bf16 v[126:129], v[156:159], v[172:175], v[126:129]
	v_mfma_f32_16x16x32_bf16 v[118:121], v[164:167], v[172:175], v[118:121]
	v_mfma_f32_16x16x32_bf16 v[110:113], v[156:159], v[180:183], v[110:113]
	v_mfma_f32_16x16x32_bf16 v[102:105], v[164:167], v[180:183], v[102:105]
	v_mfma_f32_16x16x32_bf16 v[94:97], v[156:159], v[188:191], v[94:97]
	v_mfma_f32_16x16x32_bf16 v[86:89], v[164:167], v[188:191], v[86:89]
	v_mfma_f32_16x16x32_bf16 v[78:81], v[156:159], v[196:199], v[78:81]
	v_mfma_f32_16x16x32_bf16 v[70:73], v[164:167], v[196:199], v[70:73]
	s_barrier
	ds_read_b128 v[168:171], v134 offset:16384
	ds_read_b128 v[172:175], v134 offset:17408
	ds_read_b128 v[176:179], v134 offset:18432
	ds_read_b128 v[180:183], v134 offset:19456
	ds_read_b128 v[184:187], v134 offset:20480
	ds_read_b128 v[188:191], v134 offset:21504
	ds_read_b128 v[192:195], v134 offset:22528
	ds_read_b128 v[196:199], v134 offset:23552
	s_add_u32 s74, s22, 0x60000
	s_addc_u32 s75, s23, 0
	s_add_i32 m0, s26, 0x13000
	s_nop 0
	global_load_lds_dwordx4 v132, s[74:75]
	s_add_u32 s74, s22, 0x80000
	s_addc_u32 s75, s23, 0
	s_add_i32 m0, s26, 0x14000
	s_nop 0
	global_load_lds_dwordx4 v132, s[74:75]
	s_add_u32 s74, s22, 0xa0000
	s_addc_u32 s75, s23, 0
	s_add_i32 m0, s26, 0x15000
	s_nop 0
	global_load_lds_dwordx4 v132, s[74:75]
	s_add_u32 s74, s22, 0xc0000
	s_addc_u32 s75, s23, 0
	s_add_i32 m0, s26, 0x16000
	s_nop 0
	global_load_lds_dwordx4 v132, s[74:75]
	s_waitcnt vmcnt(8)
	s_waitcnt lgkmcnt(0)
	s_barrier
	v_mfma_f32_16x16x32_bf16 v[58:61], v[136:139], v[168:171], v[58:61]
	v_mfma_f32_16x16x32_bf16 v[50:53], v[144:147], v[168:171], v[50:53]
	v_mfma_f32_16x16x32_bf16 v[42:45], v[136:139], v[176:179], v[42:45]
	v_mfma_f32_16x16x32_bf16 v[34:37], v[144:147], v[176:179], v[34:37]
	v_mfma_f32_16x16x32_bf16 v[26:29], v[136:139], v[184:187], v[26:29]
	v_mfma_f32_16x16x32_bf16 v[18:21], v[144:147], v[184:187], v[18:21]
	v_mfma_f32_16x16x32_bf16 v[10:13], v[136:139], v[192:195], v[10:13]
	v_mfma_f32_16x16x32_bf16 v[2:5], v[144:147], v[192:195], v[2:5]
	v_mfma_f32_16x16x32_bf16 v[58:61], v[140:143], v[172:175], v[58:61]
	v_mfma_f32_16x16x32_bf16 v[50:53], v[148:151], v[172:175], v[50:53]
	v_mfma_f32_16x16x32_bf16 v[42:45], v[140:143], v[180:183], v[42:45]
	v_mfma_f32_16x16x32_bf16 v[34:37], v[148:151], v[180:183], v[34:37]
	v_mfma_f32_16x16x32_bf16 v[26:29], v[140:143], v[188:191], v[26:29]
	v_mfma_f32_16x16x32_bf16 v[18:21], v[148:151], v[188:191], v[18:21]
	v_mfma_f32_16x16x32_bf16 v[10:13], v[140:143], v[196:199], v[10:13]
	v_mfma_f32_16x16x32_bf16 v[2:5], v[148:151], v[196:199], v[2:5]
	v_mfma_f32_16x16x32_bf16 v[62:65], v[152:155], v[168:171], v[62:65]
	v_mfma_f32_16x16x32_bf16 v[54:57], v[160:163], v[168:171], v[54:57]
	v_mfma_f32_16x16x32_bf16 v[46:49], v[152:155], v[176:179], v[46:49]
	v_mfma_f32_16x16x32_bf16 v[38:41], v[160:163], v[176:179], v[38:41]
	v_mfma_f32_16x16x32_bf16 v[30:33], v[152:155], v[184:187], v[30:33]
	v_mfma_f32_16x16x32_bf16 v[22:25], v[160:163], v[184:187], v[22:25]
	v_mfma_f32_16x16x32_bf16 v[14:17], v[152:155], v[192:195], v[14:17]
	v_mfma_f32_16x16x32_bf16 v[6:9], v[160:163], v[192:195], v[6:9]
	v_mfma_f32_16x16x32_bf16 v[62:65], v[156:159], v[172:175], v[62:65]
	v_mfma_f32_16x16x32_bf16 v[54:57], v[164:167], v[172:175], v[54:57]
	v_mfma_f32_16x16x32_bf16 v[46:49], v[156:159], v[180:183], v[46:49]
	v_mfma_f32_16x16x32_bf16 v[38:41], v[164:167], v[180:183], v[38:41]
	v_mfma_f32_16x16x32_bf16 v[30:33], v[156:159], v[188:191], v[30:33]
	v_mfma_f32_16x16x32_bf16 v[22:25], v[164:167], v[188:191], v[22:25]
	v_mfma_f32_16x16x32_bf16 v[14:17], v[156:159], v[196:199], v[14:17]
	v_mfma_f32_16x16x32_bf16 v[6:9], v[164:167], v[196:199], v[6:9]
	s_barrier
	v_add_u32_e32 v130, 0x18000, v133
	ds_read_b128 v[136:139], v130
	ds_read_b128 v[140:143], v130 offset:1024
	ds_read_b128 v[144:147], v130 offset:2048
	ds_read_b128 v[148:151], v130 offset:3072
	v_add_u32_e32 v130, 0x1c000, v133
	ds_read_b128 v[152:155], v130
	ds_read_b128 v[156:159], v130 offset:1024
	ds_read_b128 v[160:163], v130 offset:2048
	ds_read_b128 v[164:167], v130 offset:3072
	ds_read_b128 v[168:171], v134 offset:32768
	ds_read_b128 v[172:175], v134 offset:33792
	ds_read_b128 v[176:179], v134 offset:34816
	ds_read_b128 v[180:183], v134 offset:35840
	ds_read_b128 v[184:187], v134 offset:36864
	ds_read_b128 v[188:191], v134 offset:37888
	ds_read_b128 v[192:195], v134 offset:38912
	ds_read_b128 v[196:199], v134 offset:39936
	s_add_u32 s74, s18, 0xfffe0080
	s_addc_u32 s75, s19, -1
	s_add_i32 m0, s26, 0x7000
	s_nop 0
	global_load_lds_dwordx4 v0, s[74:75]
	s_add_u32 s74, s18, 0x80
	s_addc_u32 s75, s19, 0
	s_add_i32 m0, s26, 0x8000
	s_nop 0
	global_load_lds_dwordx4 v0, s[74:75]
	s_add_u32 s74, s18, 0xa0000
	s_addc_u32 s75, s19, 0
	s_add_i32 m0, s26, 0x5000
	s_nop 0
	global_load_lds_dwordx4 v0, s[74:75]
	s_add_u32 s74, s18, 0xc0000
	s_addc_u32 s75, s19, 0
	s_add_i32 m0, s26, 0x6000
	s_nop 0
	global_load_lds_dwordx4 v0, s[74:75]
	s_waitcnt vmcnt(8)
	s_waitcnt lgkmcnt(0)
	s_barrier
	v_mfma_f32_16x16x32_bf16 v[122:125], v[136:139], v[168:171], v[122:125]
	v_mfma_f32_16x16x32_bf16 v[114:117], v[144:147], v[168:171], v[114:117]
	v_mfma_f32_16x16x32_bf16 v[106:109], v[136:139], v[176:179], v[106:109]
	v_mfma_f32_16x16x32_bf16 v[98:101], v[144:147], v[176:179], v[98:101]
	v_mfma_f32_16x16x32_bf16 v[90:93], v[136:139], v[184:187], v[90:93]
	v_mfma_f32_16x16x32_bf16 v[82:85], v[144:147], v[184:187], v[82:85]
	v_mfma_f32_16x16x32_bf16 v[74:77], v[136:139], v[192:195], v[74:77]
	v_mfma_f32_16x16x32_bf16 v[66:69], v[144:147], v[192:195], v[66:69]
	v_mfma_f32_16x16x32_bf16 v[122:125], v[140:143], v[172:175], v[122:125]
	v_mfma_f32_16x16x32_bf16 v[114:117], v[148:151], v[172:175], v[114:117]
	v_mfma_f32_16x16x32_bf16 v[106:109], v[140:143], v[180:183], v[106:109]
	v_mfma_f32_16x16x32_bf16 v[98:101], v[148:151], v[180:183], v[98:101]
	v_mfma_f32_16x16x32_bf16 v[90:93], v[140:143], v[188:191], v[90:93]
	v_mfma_f32_16x16x32_bf16 v[82:85], v[148:151], v[188:191], v[82:85]
	v_mfma_f32_16x16x32_bf16 v[74:77], v[140:143], v[196:199], v[74:77]
	v_mfma_f32_16x16x32_bf16 v[66:69], v[148:151], v[196:199], v[66:69]
	v_mfma_f32_16x16x32_bf16 v[126:129], v[152:155], v[168:171], v[126:129]
	v_mfma_f32_16x16x32_bf16 v[118:121], v[160:163], v[168:171], v[118:121]
	v_mfma_f32_16x16x32_bf16 v[110:113], v[152:155], v[176:179], v[110:113]
	v_mfma_f32_16x16x32_bf16 v[102:105], v[160:163], v[176:179], v[102:105]
	v_mfma_f32_16x16x32_bf16 v[94:97], v[152:155], v[184:187], v[94:97]
	v_mfma_f32_16x16x32_bf16 v[86:89], v[160:163], v[184:187], v[86:89]
	v_mfma_f32_16x16x32_bf16 v[78:81], v[152:155], v[192:195], v[78:81]
	v_mfma_f32_16x16x32_bf16 v[70:73], v[160:163], v[192:195], v[70:73]
	v_mfma_f32_16x16x32_bf16 v[126:129], v[156:159], v[172:175], v[126:129]
	v_mfma_f32_16x16x32_bf16 v[118:121], v[164:167], v[172:175], v[118:121]
	v_mfma_f32_16x16x32_bf16 v[110:113], v[156:159], v[180:183], v[110:113]
	v_mfma_f32_16x16x32_bf16 v[102:105], v[164:167], v[180:183], v[102:105]
	v_mfma_f32_16x16x32_bf16 v[94:97], v[156:159], v[188:191], v[94:97]
	v_mfma_f32_16x16x32_bf16 v[86:89], v[164:167], v[188:191], v[86:89]
	v_mfma_f32_16x16x32_bf16 v[78:81], v[156:159], v[196:199], v[78:81]
	v_mfma_f32_16x16x32_bf16 v[70:73], v[164:167], v[196:199], v[70:73]
	s_barrier
	ds_read_b128 v[168:171], v134 offset:49152
	ds_read_b128 v[172:175], v134 offset:50176
	ds_read_b128 v[176:179], v134 offset:51200
	ds_read_b128 v[180:183], v134 offset:52224
	ds_read_b128 v[184:187], v134 offset:53248
	ds_read_b128 v[188:191], v134 offset:54272
	ds_read_b128 v[192:195], v134 offset:55296
	ds_read_b128 v[196:199], v134 offset:56320
	s_add_u32 s74, s22, 0x60080
	s_addc_u32 s75, s23, 0
	s_add_i32 m0, s26, 0x1b000
	s_nop 0
	global_load_lds_dwordx4 v132, s[74:75]
	s_add_u32 s74, s22, 0x80080
	s_addc_u32 s75, s23, 0
	s_add_i32 m0, s26, 0x1c000
	s_nop 0
	global_load_lds_dwordx4 v132, s[74:75]
	s_add_u32 s74, s22, 0xa0080
	s_addc_u32 s75, s23, 0
	s_add_i32 m0, s26, 0x1d000
	s_nop 0
	global_load_lds_dwordx4 v132, s[74:75]
	s_add_u32 s74, s22, 0xc0080
	s_addc_u32 s75, s23, 0
	s_add_i32 m0, s26, 0x1e000
	s_nop 0
	global_load_lds_dwordx4 v132, s[74:75]
	s_waitcnt vmcnt(8)
	s_waitcnt lgkmcnt(0)
	s_barrier
	v_mfma_f32_16x16x32_bf16 v[58:61], v[136:139], v[168:171], v[58:61]
	v_mfma_f32_16x16x32_bf16 v[50:53], v[144:147], v[168:171], v[50:53]
	v_mfma_f32_16x16x32_bf16 v[42:45], v[136:139], v[176:179], v[42:45]
	v_mfma_f32_16x16x32_bf16 v[34:37], v[144:147], v[176:179], v[34:37]
	v_mfma_f32_16x16x32_bf16 v[26:29], v[136:139], v[184:187], v[26:29]
	v_mfma_f32_16x16x32_bf16 v[18:21], v[144:147], v[184:187], v[18:21]
	v_mfma_f32_16x16x32_bf16 v[10:13], v[136:139], v[192:195], v[10:13]
	v_mfma_f32_16x16x32_bf16 v[2:5], v[144:147], v[192:195], v[2:5]
	v_mfma_f32_16x16x32_bf16 v[58:61], v[140:143], v[172:175], v[58:61]
	v_mfma_f32_16x16x32_bf16 v[50:53], v[148:151], v[172:175], v[50:53]
	v_mfma_f32_16x16x32_bf16 v[42:45], v[140:143], v[180:183], v[42:45]
	v_mfma_f32_16x16x32_bf16 v[34:37], v[148:151], v[180:183], v[34:37]
	v_mfma_f32_16x16x32_bf16 v[26:29], v[140:143], v[188:191], v[26:29]
	v_mfma_f32_16x16x32_bf16 v[18:21], v[148:151], v[188:191], v[18:21]
	v_mfma_f32_16x16x32_bf16 v[10:13], v[140:143], v[196:199], v[10:13]
	v_mfma_f32_16x16x32_bf16 v[2:5], v[148:151], v[196:199], v[2:5]
	v_mfma_f32_16x16x32_bf16 v[62:65], v[152:155], v[168:171], v[62:65]
	v_mfma_f32_16x16x32_bf16 v[54:57], v[160:163], v[168:171], v[54:57]
	v_mfma_f32_16x16x32_bf16 v[46:49], v[152:155], v[176:179], v[46:49]
	v_mfma_f32_16x16x32_bf16 v[38:41], v[160:163], v[176:179], v[38:41]
	v_mfma_f32_16x16x32_bf16 v[30:33], v[152:155], v[184:187], v[30:33]
	v_mfma_f32_16x16x32_bf16 v[22:25], v[160:163], v[184:187], v[22:25]
	v_mfma_f32_16x16x32_bf16 v[14:17], v[152:155], v[192:195], v[14:17]
	v_mfma_f32_16x16x32_bf16 v[6:9], v[160:163], v[192:195], v[6:9]
	v_mfma_f32_16x16x32_bf16 v[62:65], v[156:159], v[172:175], v[62:65]
	v_mfma_f32_16x16x32_bf16 v[54:57], v[164:167], v[172:175], v[54:57]
	v_mfma_f32_16x16x32_bf16 v[46:49], v[156:159], v[180:183], v[46:49]
	v_mfma_f32_16x16x32_bf16 v[38:41], v[164:167], v[180:183], v[38:41]
	v_mfma_f32_16x16x32_bf16 v[30:33], v[156:159], v[188:191], v[30:33]
	v_mfma_f32_16x16x32_bf16 v[22:25], v[164:167], v[188:191], v[22:25]
	v_mfma_f32_16x16x32_bf16 v[14:17], v[156:159], v[196:199], v[14:17]
	v_mfma_f32_16x16x32_bf16 v[6:9], v[164:167], v[196:199], v[6:9]
	s_barrier
	s_add_i32 s72, s72, 2
	s_add_u32 s64, s64, 0x100
	s_addc_u32 s66, s66, 0
	s_add_u32 s68, s68, 0x100
	s_addc_u32 s70, s70, 0
	s_cmp_gt_u32 s72, 29
	s_cbranch_scc0 TB_L8579_Bloop
TB_L8579_exit:
	s_and_b64 vcc, exec, s[8:9]
	s_cbranch_vccz .LBB0_518
	s_barrier

.LBB0_1046:
	s_and_b64 vcc, exec, s[12:13]
	s_cbranch_vccz TB_L24945_Bpeel
	s_cmp_eq_u32 s72, 28
	s_cselect_b32 s4, s60, s64
	s_cselect_b32 s5, s21, s66
	s_cselect_b32 s16, s62, s68
	s_cselect_b32 s17, s19, s70
	v_add_u32_e32 v0, 0x10000, v134
	ds_read_b128 v[136:139], v0
	ds_read_b128 v[140:143], v0 offset:1024
	ds_read_b128 v[144:147], v0 offset:2048
	ds_read_b128 v[148:151], v0 offset:3072
	v_add_u32_e32 v0, 0x14000, v134
	ds_read_b128 v[152:155], v0
	ds_read_b128 v[156:159], v0 offset:1024
	ds_read_b128 v[160:163], v0 offset:2048
	ds_read_b128 v[164:167], v0 offset:3072
	ds_read_b128 v[168:171], v135
	ds_read_b128 v[172:175], v135 offset:1024
	ds_read_b128 v[176:179], v135 offset:2048
	ds_read_b128 v[180:183], v135 offset:3072
	ds_read_b128 v[184:187], v135 offset:4096
	ds_read_b128 v[188:191], v135 offset:5120
	ds_read_b128 v[192:195], v135 offset:6144
	ds_read_b128 v[196:199], v135 offset:7168
	s_add_u32 s74, s64, 0x3ff80
	s_addc_u32 s75, s66, 0
	s_add_i32 m0, s28, 0xa000
	s_nop 0
	global_load_lds_dwordx4 v132, s[74:75]
	s_add_u32 s74, s64, 0x5ff80
	s_addc_u32 s75, s66, 0
	s_add_i32 m0, s28, 0xb000
	s_nop 0
	global_load_lds_dwordx4 v132, s[74:75]
	s_add_u32 s74, s64, 0x7ff80
	s_addc_u32 s75, s66, 0
	s_add_i32 m0, s28, 0xc000
	s_nop 0
	global_load_lds_dwordx4 v132, s[74:75]
	s_add_u32 s74, s64, 0x9ff80
	s_addc_u32 s75, s66, 0
	s_add_i32 m0, s28, 0xd000
	s_nop 0
	global_load_lds_dwordx4 v132, s[74:75]
	s_waitcnt vmcnt(8)
	s_waitcnt lgkmcnt(0)
	s_barrier
	v_mfma_f32_16x16x32_bf16 v[126:129], v[136:139], v[168:171], 0
	v_mfma_f32_16x16x32_bf16 v[122:125], v[144:147], v[168:171], 0
	v_mfma_f32_16x16x32_bf16 v[118:121], v[136:139], v[176:179], 0
	v_mfma_f32_16x16x32_bf16 v[114:117], v[144:147], v[176:179], 0
	v_mfma_f32_16x16x32_bf16 v[102:105], v[136:139], v[184:187], 0
	v_mfma_f32_16x16x32_bf16 v[98:101], v[144:147], v[184:187], 0
	v_mfma_f32_16x16x32_bf16 v[86:89], v[136:139], v[192:195], 0
	v_mfma_f32_16x16x32_bf16 v[82:85], v[144:147], v[192:195], 0
	v_mfma_f32_16x16x32_bf16 v[126:129], v[140:143], v[172:175], v[126:129]
	v_mfma_f32_16x16x32_bf16 v[122:125], v[148:151], v[172:175], v[122:125]
	v_mfma_f32_16x16x32_bf16 v[118:121], v[140:143], v[180:183], v[118:121]
	v_mfma_f32_16x16x32_bf16 v[114:117], v[148:151], v[180:183], v[114:117]
	v_mfma_f32_16x16x32_bf16 v[102:105], v[140:143], v[188:191], v[102:105]
	v_mfma_f32_16x16x32_bf16 v[98:101], v[148:151], v[188:191], v[98:101]
	v_mfma_f32_16x16x32_bf16 v[86:89], v[140:143], v[196:199], v[86:89]
	v_mfma_f32_16x16x32_bf16 v[82:85], v[148:151], v[196:199], v[82:85]
	v_mfma_f32_16x16x32_bf16 v[110:113], v[152:155], v[168:171], 0
	v_mfma_f32_16x16x32_bf16 v[106:109], v[160:163], v[168:171], 0
	v_mfma_f32_16x16x32_bf16 v[94:97], v[152:155], v[176:179], 0
	v_mfma_f32_16x16x32_bf16 v[90:93], v[160:163], v[176:179], 0
	v_mfma_f32_16x16x32_bf16 v[78:81], v[152:155], v[184:187], 0
	v_mfma_f32_16x16x32_bf16 v[74:77], v[160:163], v[184:187], 0
	v_mfma_f32_16x16x32_bf16 v[70:73], v[152:155], v[192:195], 0
	v_mfma_f32_16x16x32_bf16 v[66:69], v[160:163], v[192:195], 0
	v_mfma_f32_16x16x32_bf16 v[110:113], v[156:159], v[172:175], v[110:113]
	v_mfma_f32_16x16x32_bf16 v[106:109], v[164:167], v[172:175], v[106:109]
	v_mfma_f32_16x16x32_bf16 v[94:97], v[156:159], v[180:183], v[94:97]
	v_mfma_f32_16x16x32_bf16 v[90:93], v[164:167], v[180:183], v[90:93]
	v_mfma_f32_16x16x32_bf16 v[78:81], v[156:159], v[188:191], v[78:81]
	v_mfma_f32_16x16x32_bf16 v[74:77], v[164:167], v[188:191], v[74:77]
	v_mfma_f32_16x16x32_bf16 v[70:73], v[156:159], v[196:199], v[70:73]
	v_mfma_f32_16x16x32_bf16 v[66:69], v[164:167], v[196:199], v[66:69]
	s_barrier
	ds_read_b128 v[168:171], v135 offset:16384
	ds_read_b128 v[172:175], v135 offset:17408
	ds_read_b128 v[176:179], v135 offset:18432
	ds_read_b128 v[180:183], v135 offset:19456
	ds_read_b128 v[184:187], v135 offset:20480
	ds_read_b128 v[188:191], v135 offset:21504
	ds_read_b128 v[192:195], v135 offset:22528
	ds_read_b128 v[196:199], v135 offset:23552
	s_mov_b32 s74, s16
	s_mov_b32 s75, s17
	s_add_i32 m0, s28, 0x10000
	s_nop 0
	global_load_lds_dwordx4 v133, s[74:75]
	s_add_u32 s74, s16, 0x20000
	s_addc_u32 s75, s17, 0
	s_add_i32 m0, s28, 0x11000
	s_nop 0
	global_load_lds_dwordx4 v133, s[74:75]
	s_add_u32 s74, s16, 0x40000
	s_addc_u32 s75, s17, 0
	s_add_i32 m0, s28, 0x12000
	s_nop 0
	global_load_lds_dwordx4 v133, s[74:75]
	s_add_u32 s74, s16, 0x60000
	s_addc_u32 s75, s17, 0
	s_add_i32 m0, s28, 0x13000
	s_nop 0
	global_load_lds_dwordx4 v133, s[74:75]
	s_waitcnt vmcnt(8)
	s_waitcnt lgkmcnt(0)
	s_barrier
	v_mfma_f32_16x16x32_bf16 v[62:65], v[136:139], v[168:171], 0
	v_mfma_f32_16x16x32_bf16 v[58:61], v[144:147], v[168:171], 0
	v_mfma_f32_16x16x32_bf16 v[54:57], v[136:139], v[176:179], 0
	v_mfma_f32_16x16x32_bf16 v[50:53], v[144:147], v[176:179], 0
	v_mfma_f32_16x16x32_bf16 v[38:41], v[136:139], v[184:187], 0
	v_mfma_f32_16x16x32_bf16 v[34:37], v[144:147], v[184:187], 0
	v_mfma_f32_16x16x32_bf16 v[22:25], v[136:139], v[192:195], 0
	v_mfma_f32_16x16x32_bf16 v[18:21], v[144:147], v[192:195], 0
	v_mfma_f32_16x16x32_bf16 v[62:65], v[140:143], v[172:175], v[62:65]
	v_mfma_f32_16x16x32_bf16 v[58:61], v[148:151], v[172:175], v[58:61]
	v_mfma_f32_16x16x32_bf16 v[54:57], v[140:143], v[180:183], v[54:57]
	v_mfma_f32_16x16x32_bf16 v[50:53], v[148:151], v[180:183], v[50:53]
	v_mfma_f32_16x16x32_bf16 v[38:41], v[140:143], v[188:191], v[38:41]
	v_mfma_f32_16x16x32_bf16 v[34:37], v[148:151], v[188:191], v[34:37]
	v_mfma_f32_16x16x32_bf16 v[22:25], v[140:143], v[196:199], v[22:25]
	v_mfma_f32_16x16x32_bf16 v[18:21], v[148:151], v[196:199], v[18:21]
	v_mfma_f32_16x16x32_bf16 v[46:49], v[152:155], v[168:171], 0
	v_mfma_f32_16x16x32_bf16 v[42:45], v[160:163], v[168:171], 0
	v_mfma_f32_16x16x32_bf16 v[30:33], v[152:155], v[176:179], 0
	v_mfma_f32_16x16x32_bf16 v[26:29], v[160:163], v[176:179], 0
	v_mfma_f32_16x16x32_bf16 v[14:17], v[152:155], v[184:187], 0
	v_mfma_f32_16x16x32_bf16 v[10:13], v[160:163], v[184:187], 0
	v_mfma_f32_16x16x32_bf16 v[6:9], v[152:155], v[192:195], 0
	v_mfma_f32_16x16x32_bf16 v[2:5], v[160:163], v[192:195], 0
	v_mfma_f32_16x16x32_bf16 v[46:49], v[156:159], v[172:175], v[46:49]
	v_mfma_f32_16x16x32_bf16 v[42:45], v[164:167], v[172:175], v[42:45]
	v_mfma_f32_16x16x32_bf16 v[30:33], v[156:159], v[180:183], v[30:33]
	v_mfma_f32_16x16x32_bf16 v[26:29], v[164:167], v[180:183], v[26:29]
	v_mfma_f32_16x16x32_bf16 v[14:17], v[156:159], v[188:191], v[14:17]
	v_mfma_f32_16x16x32_bf16 v[10:13], v[164:167], v[188:191], v[10:13]
	v_mfma_f32_16x16x32_bf16 v[6:9], v[156:159], v[196:199], v[6:9]
	v_mfma_f32_16x16x32_bf16 v[2:5], v[164:167], v[196:199], v[2:5]
	s_barrier
	v_add_u32_e32 v0, 0x18000, v134
	ds_read_b128 v[136:139], v0
	ds_read_b128 v[140:143], v0 offset:1024
	ds_read_b128 v[144:147], v0 offset:2048
	ds_read_b128 v[148:151], v0 offset:3072
	v_add_u32_e32 v0, 0x1c000, v134
	ds_read_b128 v[152:155], v0
	ds_read_b128 v[156:159], v0 offset:1024
	ds_read_b128 v[160:163], v0 offset:2048
	ds_read_b128 v[164:167], v0 offset:3072
	ds_read_b128 v[168:171], v135 offset:32768
	ds_read_b128 v[172:175], v135 offset:33792
	ds_read_b128 v[176:179], v135 offset:34816
	ds_read_b128 v[180:183], v135 offset:35840
	ds_read_b128 v[184:187], v135 offset:36864
	ds_read_b128 v[188:191], v135 offset:37888
	ds_read_b128 v[192:195], v135 offset:38912
	ds_read_b128 v[196:199], v135 offset:39936
	s_add_u32 s74, s4, 0x40000
	s_addc_u32 s75, s5, 0
	s_add_i32 m0, s28, 0x2000
	s_nop 0
	global_load_lds_dwordx4 v132, s[74:75]
	s_add_u32 s74, s4, 0x60000
	s_addc_u32 s75, s5, 0
	s_add_i32 m0, s28, 0x3000
	s_nop 0
	global_load_lds_dwordx4 v132, s[74:75]
	s_add_u32 s74, s4, 0x80000
	s_addc_u32 s75, s5, 0
	s_add_i32 m0, s28, 0x4000
	s_nop 0
	global_load_lds_dwordx4 v132, s[74:75]
	s_add_u32 s74, s4, 0xa0000
	s_addc_u32 s75, s5, 0
	s_add_i32 m0, s28, 0x5000
	s_nop 0
	global_load_lds_dwordx4 v132, s[74:75]
	s_waitcnt vmcnt(8)
	s_waitcnt lgkmcnt(0)
	s_barrier
	v_mfma_f32_16x16x32_bf16 v[126:129], v[136:139], v[168:171], v[126:129]
	v_mfma_f32_16x16x32_bf16 v[122:125], v[144:147], v[168:171], v[122:125]
	v_mfma_f32_16x16x32_bf16 v[118:121], v[136:139], v[176:179], v[118:121]
	v_mfma_f32_16x16x32_bf16 v[114:117], v[144:147], v[176:179], v[114:117]
	v_mfma_f32_16x16x32_bf16 v[102:105], v[136:139], v[184:187], v[102:105]
	v_mfma_f32_16x16x32_bf16 v[98:101], v[144:147], v[184:187], v[98:101]
	v_mfma_f32_16x16x32_bf16 v[86:89], v[136:139], v[192:195], v[86:89]
	v_mfma_f32_16x16x32_bf16 v[82:85], v[144:147], v[192:195], v[82:85]
	v_mfma_f32_16x16x32_bf16 v[126:129], v[140:143], v[172:175], v[126:129]
	v_mfma_f32_16x16x32_bf16 v[122:125], v[148:151], v[172:175], v[122:125]
	v_mfma_f32_16x16x32_bf16 v[118:121], v[140:143], v[180:183], v[118:121]
	v_mfma_f32_16x16x32_bf16 v[114:117], v[148:151], v[180:183], v[114:117]
	v_mfma_f32_16x16x32_bf16 v[102:105], v[140:143], v[188:191], v[102:105]
	v_mfma_f32_16x16x32_bf16 v[98:101], v[148:151], v[188:191], v[98:101]
	v_mfma_f32_16x16x32_bf16 v[86:89], v[140:143], v[196:199], v[86:89]
	v_mfma_f32_16x16x32_bf16 v[82:85], v[148:151], v[196:199], v[82:85]
	v_mfma_f32_16x16x32_bf16 v[110:113], v[152:155], v[168:171], v[110:113]
	v_mfma_f32_16x16x32_bf16 v[106:109], v[160:163], v[168:171], v[106:109]
	v_mfma_f32_16x16x32_bf16 v[94:97], v[152:155], v[176:179], v[94:97]
	v_mfma_f32_16x16x32_bf16 v[90:93], v[160:163], v[176:179], v[90:93]
	v_mfma_f32_16x16x32_bf16 v[78:81], v[152:155], v[184:187], v[78:81]
	v_mfma_f32_16x16x32_bf16 v[74:77], v[160:163], v[184:187], v[74:77]
	v_mfma_f32_16x16x32_bf16 v[70:73], v[152:155], v[192:195], v[70:73]
	v_mfma_f32_16x16x32_bf16 v[66:69], v[160:163], v[192:195], v[66:69]
	v_mfma_f32_16x16x32_bf16 v[110:113], v[156:159], v[172:175], v[110:113]
	v_mfma_f32_16x16x32_bf16 v[106:109], v[164:167], v[172:175], v[106:109]
	v_mfma_f32_16x16x32_bf16 v[94:97], v[156:159], v[180:183], v[94:97]
	v_mfma_f32_16x16x32_bf16 v[90:93], v[164:167], v[180:183], v[90:93]
	v_mfma_f32_16x16x32_bf16 v[78:81], v[156:159], v[188:191], v[78:81]
	v_mfma_f32_16x16x32_bf16 v[74:77], v[164:167], v[188:191], v[74:77]
	v_mfma_f32_16x16x32_bf16 v[70:73], v[156:159], v[196:199], v[70:73]
	v_mfma_f32_16x16x32_bf16 v[66:69], v[164:167], v[196:199], v[66:69]
	s_barrier
	ds_read_b128 v[168:171], v135 offset:49152
	ds_read_b128 v[172:175], v135 offset:50176
	ds_read_b128 v[176:179], v135 offset:51200
	ds_read_b128 v[180:183], v135 offset:52224
	ds_read_b128 v[184:187], v135 offset:53248
	ds_read_b128 v[188:191], v135 offset:54272
	ds_read_b128 v[192:195], v135 offset:55296
	ds_read_b128 v[196:199], v135 offset:56320
	s_add_u32 s74, s16, 0x80
	s_addc_u32 s75, s17, 0
	s_add_i32 m0, s28, 0x18000
	s_nop 0
	global_load_lds_dwordx4 v133, s[74:75]
	s_add_u32 s74, s16, 0x20080
	s_addc_u32 s75, s17, 0
	s_add_i32 m0, s28, 0x19000
	s_nop 0
	global_load_lds_dwordx4 v133, s[74:75]
	s_add_u32 s74, s16, 0x40080
	s_addc_u32 s75, s17, 0
	s_add_i32 m0, s28, 0x1a000
	s_nop 0
	global_load_lds_dwordx4 v133, s[74:75]
	s_add_u32 s74, s16, 0x60080
	s_addc_u32 s75, s17, 0
	s_add_i32 m0, s28, 0x1b000
	s_nop 0
	global_load_lds_dwordx4 v133, s[74:75]
	s_waitcnt vmcnt(8)
	s_waitcnt lgkmcnt(0)
	s_barrier
	v_mfma_f32_16x16x32_bf16 v[62:65], v[136:139], v[168:171], v[62:65]
	v_mfma_f32_16x16x32_bf16 v[58:61], v[144:147], v[168:171], v[58:61]
	v_mfma_f32_16x16x32_bf16 v[54:57], v[136:139], v[176:179], v[54:57]
	v_mfma_f32_16x16x32_bf16 v[50:53], v[144:147], v[176:179], v[50:53]
	v_mfma_f32_16x16x32_bf16 v[38:41], v[136:139], v[184:187], v[38:41]
	v_mfma_f32_16x16x32_bf16 v[34:37], v[144:147], v[184:187], v[34:37]
	v_mfma_f32_16x16x32_bf16 v[22:25], v[136:139], v[192:195], v[22:25]
	v_mfma_f32_16x16x32_bf16 v[18:21], v[144:147], v[192:195], v[18:21]
	v_mfma_f32_16x16x32_bf16 v[62:65], v[140:143], v[172:175], v[62:65]
	v_mfma_f32_16x16x32_bf16 v[58:61], v[148:151], v[172:175], v[58:61]
	v_mfma_f32_16x16x32_bf16 v[54:57], v[140:143], v[180:183], v[54:57]
	v_mfma_f32_16x16x32_bf16 v[50:53], v[148:151], v[180:183], v[50:53]
	v_mfma_f32_16x16x32_bf16 v[38:41], v[140:143], v[188:191], v[38:41]
	v_mfma_f32_16x16x32_bf16 v[34:37], v[148:151], v[188:191], v[34:37]
	v_mfma_f32_16x16x32_bf16 v[22:25], v[140:143], v[196:199], v[22:25]
	v_mfma_f32_16x16x32_bf16 v[18:21], v[148:151], v[196:199], v[18:21]
	v_mfma_f32_16x16x32_bf16 v[46:49], v[152:155], v[168:171], v[46:49]
	v_mfma_f32_16x16x32_bf16 v[42:45], v[160:163], v[168:171], v[42:45]
	v_mfma_f32_16x16x32_bf16 v[30:33], v[152:155], v[176:179], v[30:33]
	v_mfma_f32_16x16x32_bf16 v[26:29], v[160:163], v[176:179], v[26:29]
	v_mfma_f32_16x16x32_bf16 v[14:17], v[152:155], v[184:187], v[14:17]
	v_mfma_f32_16x16x32_bf16 v[10:13], v[160:163], v[184:187], v[10:13]
	v_mfma_f32_16x16x32_bf16 v[6:9], v[152:155], v[192:195], v[6:9]
	v_mfma_f32_16x16x32_bf16 v[2:5], v[160:163], v[192:195], v[2:5]
	v_mfma_f32_16x16x32_bf16 v[46:49], v[156:159], v[172:175], v[46:49]
	v_mfma_f32_16x16x32_bf16 v[42:45], v[164:167], v[172:175], v[42:45]
	v_mfma_f32_16x16x32_bf16 v[30:33], v[156:159], v[180:183], v[30:33]
	v_mfma_f32_16x16x32_bf16 v[26:29], v[164:167], v[180:183], v[26:29]
	v_mfma_f32_16x16x32_bf16 v[14:17], v[156:159], v[188:191], v[14:17]
	v_mfma_f32_16x16x32_bf16 v[10:13], v[164:167], v[188:191], v[10:13]
	v_mfma_f32_16x16x32_bf16 v[6:9], v[156:159], v[196:199], v[6:9]
	v_mfma_f32_16x16x32_bf16 v[2:5], v[164:167], v[196:199], v[2:5]
	s_barrier
	s_add_i32 s72, s72, 2
	s_add_u32 s64, s64, 0x100
	s_addc_u32 s66, s66, 0
	s_add_u32 s68, s68, 0x100
	s_addc_u32 s70, s70, 0
TB_L24945_Aloop:
	s_cmp_eq_u32 s72, 28
	s_cselect_b32 s4, s60, s64
	s_cselect_b32 s5, s21, s66
	s_cselect_b32 s16, s62, s68
	s_cselect_b32 s17, s19, s70
	v_add_u32_e32 v0, 0x10000, v134
	ds_read_b128 v[136:139], v0
	ds_read_b128 v[140:143], v0 offset:1024
	ds_read_b128 v[144:147], v0 offset:2048
	ds_read_b128 v[148:151], v0 offset:3072
	v_add_u32_e32 v0, 0x14000, v134
	ds_read_b128 v[152:155], v0
	ds_read_b128 v[156:159], v0 offset:1024
	ds_read_b128 v[160:163], v0 offset:2048
	ds_read_b128 v[164:167], v0 offset:3072
	ds_read_b128 v[168:171], v135
	ds_read_b128 v[172:175], v135 offset:1024
	ds_read_b128 v[176:179], v135 offset:2048
	ds_read_b128 v[180:183], v135 offset:3072
	ds_read_b128 v[184:187], v135 offset:4096
	ds_read_b128 v[188:191], v135 offset:5120
	ds_read_b128 v[192:195], v135 offset:6144
	ds_read_b128 v[196:199], v135 offset:7168
	s_add_u32 s74, s64, 0x3ff80
	s_addc_u32 s75, s66, 0
	s_add_i32 m0, s28, 0xa000
	s_nop 0
	global_load_lds_dwordx4 v132, s[74:75]
	s_add_u32 s74, s64, 0x5ff80
	s_addc_u32 s75, s66, 0
	s_add_i32 m0, s28, 0xb000
	s_nop 0
	global_load_lds_dwordx4 v132, s[74:75]
	s_add_u32 s74, s64, 0x7ff80
	s_addc_u32 s75, s66, 0
	s_add_i32 m0, s28, 0xc000
	s_nop 0
	global_load_lds_dwordx4 v132, s[74:75]
	s_add_u32 s74, s64, 0x9ff80
	s_addc_u32 s75, s66, 0
	s_add_i32 m0, s28, 0xd000
	s_nop 0
	global_load_lds_dwordx4 v132, s[74:75]
	s_waitcnt vmcnt(8)
	s_waitcnt lgkmcnt(0)
	s_barrier
	v_mfma_f32_16x16x32_bf16 v[126:129], v[136:139], v[168:171], v[126:129]
	v_mfma_f32_16x16x32_bf16 v[122:125], v[144:147], v[168:171], v[122:125]
	v_mfma_f32_16x16x32_bf16 v[118:121], v[136:139], v[176:179], v[118:121]
	v_mfma_f32_16x16x32_bf16 v[114:117], v[144:147], v[176:179], v[114:117]
	v_mfma_f32_16x16x32_bf16 v[102:105], v[136:139], v[184:187], v[102:105]
	v_mfma_f32_16x16x32_bf16 v[98:101], v[144:147], v[184:187], v[98:101]
	v_mfma_f32_16x16x32_bf16 v[86:89], v[136:139], v[192:195], v[86:89]
	v_mfma_f32_16x16x32_bf16 v[82:85], v[144:147], v[192:195], v[82:85]
	v_mfma_f32_16x16x32_bf16 v[126:129], v[140:143], v[172:175], v[126:129]
	v_mfma_f32_16x16x32_bf16 v[122:125], v[148:151], v[172:175], v[122:125]
	v_mfma_f32_16x16x32_bf16 v[118:121], v[140:143], v[180:183], v[118:121]
	v_mfma_f32_16x16x32_bf16 v[114:117], v[148:151], v[180:183], v[114:117]
	v_mfma_f32_16x16x32_bf16 v[102:105], v[140:143], v[188:191], v[102:105]
	v_mfma_f32_16x16x32_bf16 v[98:101], v[148:151], v[188:191], v[98:101]
	v_mfma_f32_16x16x32_bf16 v[86:89], v[140:143], v[196:199], v[86:89]
	v_mfma_f32_16x16x32_bf16 v[82:85], v[148:151], v[196:199], v[82:85]
	v_mfma_f32_16x16x32_bf16 v[110:113], v[152:155], v[168:171], v[110:113]
	v_mfma_f32_16x16x32_bf16 v[106:109], v[160:163], v[168:171], v[106:109]
	v_mfma_f32_16x16x32_bf16 v[94:97], v[152:155], v[176:179], v[94:97]
	v_mfma_f32_16x16x32_bf16 v[90:93], v[160:163], v[176:179], v[90:93]
	v_mfma_f32_16x16x32_bf16 v[78:81], v[152:155], v[184:187], v[78:81]
	v_mfma_f32_16x16x32_bf16 v[74:77], v[160:163], v[184:187], v[74:77]
	v_mfma_f32_16x16x32_bf16 v[70:73], v[152:155], v[192:195], v[70:73]
	v_mfma_f32_16x16x32_bf16 v[66:69], v[160:163], v[192:195], v[66:69]
	v_mfma_f32_16x16x32_bf16 v[110:113], v[156:159], v[172:175], v[110:113]
	v_mfma_f32_16x16x32_bf16 v[106:109], v[164:167], v[172:175], v[106:109]
	v_mfma_f32_16x16x32_bf16 v[94:97], v[156:159], v[180:183], v[94:97]
	v_mfma_f32_16x16x32_bf16 v[90:93], v[164:167], v[180:183], v[90:93]
	v_mfma_f32_16x16x32_bf16 v[78:81], v[156:159], v[188:191], v[78:81]
	v_mfma_f32_16x16x32_bf16 v[74:77], v[164:167], v[188:191], v[74:77]
	v_mfma_f32_16x16x32_bf16 v[70:73], v[156:159], v[196:199], v[70:73]
	v_mfma_f32_16x16x32_bf16 v[66:69], v[164:167], v[196:199], v[66:69]
	s_barrier
	ds_read_b128 v[168:171], v135 offset:16384
	ds_read_b128 v[172:175], v135 offset:17408
	ds_read_b128 v[176:179], v135 offset:18432
	ds_read_b128 v[180:183], v135 offset:19456
	ds_read_b128 v[184:187], v135 offset:20480
	ds_read_b128 v[188:191], v135 offset:21504
	ds_read_b128 v[192:195], v135 offset:22528
	ds_read_b128 v[196:199], v135 offset:23552
	s_mov_b32 s74, s16
	s_mov_b32 s75, s17
	s_add_i32 m0, s28, 0x10000
	s_nop 0
	global_load_lds_dwordx4 v133, s[74:75]
	s_add_u32 s74, s16, 0x20000
	s_addc_u32 s75, s17, 0
	s_add_i32 m0, s28, 0x11000
	s_nop 0
	global_load_lds_dwordx4 v133, s[74:75]
	s_add_u32 s74, s16, 0x40000
	s_addc_u32 s75, s17, 0
	s_add_i32 m0, s28, 0x12000
	s_nop 0
	global_load_lds_dwordx4 v133, s[74:75]
	s_add_u32 s74, s16, 0x60000
	s_addc_u32 s75, s17, 0
	s_add_i32 m0, s28, 0x13000
	s_nop 0
	global_load_lds_dwordx4 v133, s[74:75]
	s_waitcnt vmcnt(8)
	s_waitcnt lgkmcnt(0)
	s_barrier
	v_mfma_f32_16x16x32_bf16 v[62:65], v[136:139], v[168:171], v[62:65]
	v_mfma_f32_16x16x32_bf16 v[58:61], v[144:147], v[168:171], v[58:61]
	v_mfma_f32_16x16x32_bf16 v[54:57], v[136:139], v[176:179], v[54:57]
	v_mfma_f32_16x16x32_bf16 v[50:53], v[144:147], v[176:179], v[50:53]
	v_mfma_f32_16x16x32_bf16 v[38:41], v[136:139], v[184:187], v[38:41]
	v_mfma_f32_16x16x32_bf16 v[34:37], v[144:147], v[184:187], v[34:37]
	v_mfma_f32_16x16x32_bf16 v[22:25], v[136:139], v[192:195], v[22:25]
	v_mfma_f32_16x16x32_bf16 v[18:21], v[144:147], v[192:195], v[18:21]
	v_mfma_f32_16x16x32_bf16 v[62:65], v[140:143], v[172:175], v[62:65]
	v_mfma_f32_16x16x32_bf16 v[58:61], v[148:151], v[172:175], v[58:61]
	v_mfma_f32_16x16x32_bf16 v[54:57], v[140:143], v[180:183], v[54:57]
	v_mfma_f32_16x16x32_bf16 v[50:53], v[148:151], v[180:183], v[50:53]
	v_mfma_f32_16x16x32_bf16 v[38:41], v[140:143], v[188:191], v[38:41]
	v_mfma_f32_16x16x32_bf16 v[34:37], v[148:151], v[188:191], v[34:37]
	v_mfma_f32_16x16x32_bf16 v[22:25], v[140:143], v[196:199], v[22:25]
	v_mfma_f32_16x16x32_bf16 v[18:21], v[148:151], v[196:199], v[18:21]
	v_mfma_f32_16x16x32_bf16 v[46:49], v[152:155], v[168:171], v[46:49]
	v_mfma_f32_16x16x32_bf16 v[42:45], v[160:163], v[168:171], v[42:45]
	v_mfma_f32_16x16x32_bf16 v[30:33], v[152:155], v[176:179], v[30:33]
	v_mfma_f32_16x16x32_bf16 v[26:29], v[160:163], v[176:179], v[26:29]
	v_mfma_f32_16x16x32_bf16 v[14:17], v[152:155], v[184:187], v[14:17]
	v_mfma_f32_16x16x32_bf16 v[10:13], v[160:163], v[184:187], v[10:13]
	v_mfma_f32_16x16x32_bf16 v[6:9], v[152:155], v[192:195], v[6:9]
	v_mfma_f32_16x16x32_bf16 v[2:5], v[160:163], v[192:195], v[2:5]
	v_mfma_f32_16x16x32_bf16 v[46:49], v[156:159], v[172:175], v[46:49]
	v_mfma_f32_16x16x32_bf16 v[42:45], v[164:167], v[172:175], v[42:45]
	v_mfma_f32_16x16x32_bf16 v[30:33], v[156:159], v[180:183], v[30:33]
	v_mfma_f32_16x16x32_bf16 v[26:29], v[164:167], v[180:183], v[26:29]
	v_mfma_f32_16x16x32_bf16 v[14:17], v[156:159], v[188:191], v[14:17]
	v_mfma_f32_16x16x32_bf16 v[10:13], v[164:167], v[188:191], v[10:13]
	v_mfma_f32_16x16x32_bf16 v[6:9], v[156:159], v[196:199], v[6:9]
	v_mfma_f32_16x16x32_bf16 v[2:5], v[164:167], v[196:199], v[2:5]
	s_barrier
	v_add_u32_e32 v0, 0x18000, v134
	ds_read_b128 v[136:139], v0
	ds_read_b128 v[140:143], v0 offset:1024
	ds_read_b128 v[144:147], v0 offset:2048
	ds_read_b128 v[148:151], v0 offset:3072
	v_add_u32_e32 v0, 0x1c000, v134
	ds_read_b128 v[152:155], v0
	ds_read_b128 v[156:159], v0 offset:1024
	ds_read_b128 v[160:163], v0 offset:2048
	ds_read_b128 v[164:167], v0 offset:3072
	ds_read_b128 v[168:171], v135 offset:32768
	ds_read_b128 v[172:175], v135 offset:33792
	ds_read_b128 v[176:179], v135 offset:34816
	ds_read_b128 v[180:183], v135 offset:35840
	ds_read_b128 v[184:187], v135 offset:36864
	ds_read_b128 v[188:191], v135 offset:37888
	ds_read_b128 v[192:195], v135 offset:38912
	ds_read_b128 v[196:199], v135 offset:39936
	s_add_u32 s74, s4, 0x40000
	s_addc_u32 s75, s5, 0
	s_add_i32 m0, s28, 0x2000
	s_nop 0
	global_load_lds_dwordx4 v132, s[74:75]
	s_add_u32 s74, s4, 0x60000
	s_addc_u32 s75, s5, 0
	s_add_i32 m0, s28, 0x3000
	s_nop 0
	global_load_lds_dwordx4 v132, s[74:75]
	s_add_u32 s74, s4, 0x80000
	s_addc_u32 s75, s5, 0
	s_add_i32 m0, s28, 0x4000
	s_nop 0
	global_load_lds_dwordx4 v132, s[74:75]
	s_add_u32 s74, s4, 0xa0000
	s_addc_u32 s75, s5, 0
	s_add_i32 m0, s28, 0x5000
	s_nop 0
	global_load_lds_dwordx4 v132, s[74:75]
	s_waitcnt vmcnt(8)
	s_waitcnt lgkmcnt(0)
	s_barrier
	v_mfma_f32_16x16x32_bf16 v[126:129], v[136:139], v[168:171], v[126:129]
	v_mfma_f32_16x16x32_bf16 v[122:125], v[144:147], v[168:171], v[122:125]
	v_mfma_f32_16x16x32_bf16 v[118:121], v[136:139], v[176:179], v[118:121]
	v_mfma_f32_16x16x32_bf16 v[114:117], v[144:147], v[176:179], v[114:117]
	v_mfma_f32_16x16x32_bf16 v[102:105], v[136:139], v[184:187], v[102:105]
	v_mfma_f32_16x16x32_bf16 v[98:101], v[144:147], v[184:187], v[98:101]
	v_mfma_f32_16x16x32_bf16 v[86:89], v[136:139], v[192:195], v[86:89]
	v_mfma_f32_16x16x32_bf16 v[82:85], v[144:147], v[192:195], v[82:85]
	v_mfma_f32_16x16x32_bf16 v[126:129], v[140:143], v[172:175], v[126:129]
	v_mfma_f32_16x16x32_bf16 v[122:125], v[148:151], v[172:175], v[122:125]
	v_mfma_f32_16x16x32_bf16 v[118:121], v[140:143], v[180:183], v[118:121]
	v_mfma_f32_16x16x32_bf16 v[114:117], v[148:151], v[180:183], v[114:117]
	v_mfma_f32_16x16x32_bf16 v[102:105], v[140:143], v[188:191], v[102:105]
	v_mfma_f32_16x16x32_bf16 v[98:101], v[148:151], v[188:191], v[98:101]
	v_mfma_f32_16x16x32_bf16 v[86:89], v[140:143], v[196:199], v[86:89]
	v_mfma_f32_16x16x32_bf16 v[82:85], v[148:151], v[196:199], v[82:85]
	v_mfma_f32_16x16x32_bf16 v[110:113], v[152:155], v[168:171], v[110:113]
	v_mfma_f32_16x16x32_bf16 v[106:109], v[160:163], v[168:171], v[106:109]
	v_mfma_f32_16x16x32_bf16 v[94:97], v[152:155], v[176:179], v[94:97]
	v_mfma_f32_16x16x32_bf16 v[90:93], v[160:163], v[176:179], v[90:93]
	v_mfma_f32_16x16x32_bf16 v[78:81], v[152:155], v[184:187], v[78:81]
	v_mfma_f32_16x16x32_bf16 v[74:77], v[160:163], v[184:187], v[74:77]
	v_mfma_f32_16x16x32_bf16 v[70:73], v[152:155], v[192:195], v[70:73]
	v_mfma_f32_16x16x32_bf16 v[66:69], v[160:163], v[192:195], v[66:69]
	v_mfma_f32_16x16x32_bf16 v[110:113], v[156:159], v[172:175], v[110:113]
	v_mfma_f32_16x16x32_bf16 v[106:109], v[164:167], v[172:175], v[106:109]
	v_mfma_f32_16x16x32_bf16 v[94:97], v[156:159], v[180:183], v[94:97]
	v_mfma_f32_16x16x32_bf16 v[90:93], v[164:167], v[180:183], v[90:93]
	v_mfma_f32_16x16x32_bf16 v[78:81], v[156:159], v[188:191], v[78:81]
	v_mfma_f32_16x16x32_bf16 v[74:77], v[164:167], v[188:191], v[74:77]
	v_mfma_f32_16x16x32_bf16 v[70:73], v[156:159], v[196:199], v[70:73]
	v_mfma_f32_16x16x32_bf16 v[66:69], v[164:167], v[196:199], v[66:69]
	s_barrier
	ds_read_b128 v[168:171], v135 offset:49152
	ds_read_b128 v[172:175], v135 offset:50176
	ds_read_b128 v[176:179], v135 offset:51200
	ds_read_b128 v[180:183], v135 offset:52224
	ds_read_b128 v[184:187], v135 offset:53248
	ds_read_b128 v[188:191], v135 offset:54272
	ds_read_b128 v[192:195], v135 offset:55296
	ds_read_b128 v[196:199], v135 offset:56320
	s_add_u32 s74, s16, 0x80
	s_addc_u32 s75, s17, 0
	s_add_i32 m0, s28, 0x18000
	s_nop 0
	global_load_lds_dwordx4 v133, s[74:75]
	s_add_u32 s74, s16, 0x20080
	s_addc_u32 s75, s17, 0
	s_add_i32 m0, s28, 0x19000
	s_nop 0
	global_load_lds_dwordx4 v133, s[74:75]
	s_add_u32 s74, s16, 0x40080
	s_addc_u32 s75, s17, 0
	s_add_i32 m0, s28, 0x1a000
	s_nop 0
	global_load_lds_dwordx4 v133, s[74:75]
	s_add_u32 s74, s16, 0x60080
	s_addc_u32 s75, s17, 0
	s_add_i32 m0, s28, 0x1b000
	s_nop 0
	global_load_lds_dwordx4 v133, s[74:75]
	s_waitcnt vmcnt(8)
	s_waitcnt lgkmcnt(0)
	s_barrier
	v_mfma_f32_16x16x32_bf16 v[62:65], v[136:139], v[168:171], v[62:65]
	v_mfma_f32_16x16x32_bf16 v[58:61], v[144:147], v[168:171], v[58:61]
	v_mfma_f32_16x16x32_bf16 v[54:57], v[136:139], v[176:179], v[54:57]
	v_mfma_f32_16x16x32_bf16 v[50:53], v[144:147], v[176:179], v[50:53]
	v_mfma_f32_16x16x32_bf16 v[38:41], v[136:139], v[184:187], v[38:41]
	v_mfma_f32_16x16x32_bf16 v[34:37], v[144:147], v[184:187], v[34:37]
	v_mfma_f32_16x16x32_bf16 v[22:25], v[136:139], v[192:195], v[22:25]
	v_mfma_f32_16x16x32_bf16 v[18:21], v[144:147], v[192:195], v[18:21]
	v_mfma_f32_16x16x32_bf16 v[62:65], v[140:143], v[172:175], v[62:65]
	v_mfma_f32_16x16x32_bf16 v[58:61], v[148:151], v[172:175], v[58:61]
	v_mfma_f32_16x16x32_bf16 v[54:57], v[140:143], v[180:183], v[54:57]
	v_mfma_f32_16x16x32_bf16 v[50:53], v[148:151], v[180:183], v[50:53]
	v_mfma_f32_16x16x32_bf16 v[38:41], v[140:143], v[188:191], v[38:41]
	v_mfma_f32_16x16x32_bf16 v[34:37], v[148:151], v[188:191], v[34:37]
	v_mfma_f32_16x16x32_bf16 v[22:25], v[140:143], v[196:199], v[22:25]
	v_mfma_f32_16x16x32_bf16 v[18:21], v[148:151], v[196:199], v[18:21]
	v_mfma_f32_16x16x32_bf16 v[46:49], v[152:155], v[168:171], v[46:49]
	v_mfma_f32_16x16x32_bf16 v[42:45], v[160:163], v[168:171], v[42:45]
	v_mfma_f32_16x16x32_bf16 v[30:33], v[152:155], v[176:179], v[30:33]
	v_mfma_f32_16x16x32_bf16 v[26:29], v[160:163], v[176:179], v[26:29]
	v_mfma_f32_16x16x32_bf16 v[14:17], v[152:155], v[184:187], v[14:17]
	v_mfma_f32_16x16x32_bf16 v[10:13], v[160:163], v[184:187], v[10:13]
	v_mfma_f32_16x16x32_bf16 v[6:9], v[152:155], v[192:195], v[6:9]
	v_mfma_f32_16x16x32_bf16 v[2:5], v[160:163], v[192:195], v[2:5]
	v_mfma_f32_16x16x32_bf16 v[46:49], v[156:159], v[172:175], v[46:49]
	v_mfma_f32_16x16x32_bf16 v[42:45], v[164:167], v[172:175], v[42:45]
	v_mfma_f32_16x16x32_bf16 v[30:33], v[156:159], v[180:183], v[30:33]
	v_mfma_f32_16x16x32_bf16 v[26:29], v[164:167], v[180:183], v[26:29]
	v_mfma_f32_16x16x32_bf16 v[14:17], v[156:159], v[188:191], v[14:17]
	v_mfma_f32_16x16x32_bf16 v[10:13], v[164:167], v[188:191], v[10:13]
	v_mfma_f32_16x16x32_bf16 v[6:9], v[156:159], v[196:199], v[6:9]
	v_mfma_f32_16x16x32_bf16 v[2:5], v[164:167], v[196:199], v[2:5]
	s_barrier
	s_add_i32 s72, s72, 2
	s_add_u32 s64, s64, 0x100
	s_addc_u32 s66, s66, 0
	s_add_u32 s68, s68, 0x100
	s_addc_u32 s70, s70, 0
	s_cmp_gt_u32 s72, 29
	s_cbranch_scc0 TB_L24945_Aloop
	s_branch TB_L24945_exit
TB_L24945_Bpeel:
	s_cmp_eq_u32 s72, 28
	s_cselect_b32 s4, s60, s64
	s_cselect_b32 s5, s21, s66
	s_cselect_b32 s16, s62, s68
	s_cselect_b32 s17, s19, s70
	v_add_u32_e32 v0, 0x10000, v134
	ds_read_b128 v[136:139], v0
	ds_read_b128 v[140:143], v0 offset:1024
	ds_read_b128 v[144:147], v0 offset:2048
	ds_read_b128 v[148:151], v0 offset:3072
	v_add_u32_e32 v0, 0x14000, v134
	ds_read_b128 v[152:155], v0
	ds_read_b128 v[156:159], v0 offset:1024
	ds_read_b128 v[160:163], v0 offset:2048
	ds_read_b128 v[164:167], v0 offset:3072
	ds_read_b128 v[168:171], v135
	ds_read_b128 v[172:175], v135 offset:1024
	ds_read_b128 v[176:179], v135 offset:2048
	ds_read_b128 v[180:183], v135 offset:3072
	ds_read_b128 v[184:187], v135 offset:4096
	ds_read_b128 v[188:191], v135 offset:5120
	ds_read_b128 v[192:195], v135 offset:6144
	ds_read_b128 v[196:199], v135 offset:7168
	s_add_u32 s74, s4, 0xfffe0000
	s_addc_u32 s75, s5, -1
	s_add_i32 m0, s28, 0xfffff000
	s_nop 0
	global_load_lds_dwordx4 v132, s[74:75]
	s_mov_b32 s74, s4
	s_mov_b32 s75, s5
	s_mov_b32 m0, s28
	s_nop 0
	global_load_lds_dwordx4 v132, s[74:75]
	s_add_u32 s74, s64, 0x9ff80
	s_addc_u32 s75, s66, 0
	s_add_i32 m0, s28, 0xd000
	s_nop 0
	global_load_lds_dwordx4 v132, s[74:75]
	s_add_u32 s74, s64, 0xbff80
	s_addc_u32 s75, s66, 0
	s_add_i32 m0, s28, 0xe000
	s_nop 0
	global_load_lds_dwordx4 v132, s[74:75]
	s_waitcnt vmcnt(8)
	s_waitcnt lgkmcnt(0)
	s_barrier
	v_mfma_f32_16x16x32_bf16 v[126:129], v[136:139], v[168:171], 0
	v_mfma_f32_16x16x32_bf16 v[122:125], v[144:147], v[168:171], 0
	v_mfma_f32_16x16x32_bf16 v[118:121], v[136:139], v[176:179], 0
	v_mfma_f32_16x16x32_bf16 v[114:117], v[144:147], v[176:179], 0
	v_mfma_f32_16x16x32_bf16 v[102:105], v[136:139], v[184:187], 0
	v_mfma_f32_16x16x32_bf16 v[98:101], v[144:147], v[184:187], 0
	v_mfma_f32_16x16x32_bf16 v[86:89], v[136:139], v[192:195], 0
	v_mfma_f32_16x16x32_bf16 v[82:85], v[144:147], v[192:195], 0
	v_mfma_f32_16x16x32_bf16 v[126:129], v[140:143], v[172:175], v[126:129]
	v_mfma_f32_16x16x32_bf16 v[122:125], v[148:151], v[172:175], v[122:125]
	v_mfma_f32_16x16x32_bf16 v[118:121], v[140:143], v[180:183], v[118:121]
	v_mfma_f32_16x16x32_bf16 v[114:117], v[148:151], v[180:183], v[114:117]
	v_mfma_f32_16x16x32_bf16 v[102:105], v[140:143], v[188:191], v[102:105]
	v_mfma_f32_16x16x32_bf16 v[98:101], v[148:151], v[188:191], v[98:101]
	v_mfma_f32_16x16x32_bf16 v[86:89], v[140:143], v[196:199], v[86:89]
	v_mfma_f32_16x16x32_bf16 v[82:85], v[148:151], v[196:199], v[82:85]
	v_mfma_f32_16x16x32_bf16 v[110:113], v[152:155], v[168:171], 0
	v_mfma_f32_16x16x32_bf16 v[106:109], v[160:163], v[168:171], 0
	v_mfma_f32_16x16x32_bf16 v[94:97], v[152:155], v[176:179], 0
	v_mfma_f32_16x16x32_bf16 v[90:93], v[160:163], v[176:179], 0
	v_mfma_f32_16x16x32_bf16 v[78:81], v[152:155], v[184:187], 0
	v_mfma_f32_16x16x32_bf16 v[74:77], v[160:163], v[184:187], 0
	v_mfma_f32_16x16x32_bf16 v[70:73], v[152:155], v[192:195], 0
	v_mfma_f32_16x16x32_bf16 v[66:69], v[160:163], v[192:195], 0
	v_mfma_f32_16x16x32_bf16 v[110:113], v[156:159], v[172:175], v[110:113]
	v_mfma_f32_16x16x32_bf16 v[106:109], v[164:167], v[172:175], v[106:109]
	v_mfma_f32_16x16x32_bf16 v[94:97], v[156:159], v[180:183], v[94:97]
	v_mfma_f32_16x16x32_bf16 v[90:93], v[164:167], v[180:183], v[90:93]
	v_mfma_f32_16x16x32_bf16 v[78:81], v[156:159], v[188:191], v[78:81]
	v_mfma_f32_16x16x32_bf16 v[74:77], v[164:167], v[188:191], v[74:77]
	v_mfma_f32_16x16x32_bf16 v[70:73], v[156:159], v[196:199], v[70:73]
	v_mfma_f32_16x16x32_bf16 v[66:69], v[164:167], v[196:199], v[66:69]
	s_barrier
	ds_read_b128 v[168:171], v135 offset:16384
	ds_read_b128 v[172:175], v135 offset:17408
	ds_read_b128 v[176:179], v135 offset:18432
	ds_read_b128 v[180:183], v135 offset:19456
	ds_read_b128 v[184:187], v135 offset:20480
	ds_read_b128 v[188:191], v135 offset:21504
	ds_read_b128 v[192:195], v135 offset:22528
	ds_read_b128 v[196:199], v135 offset:23552
	s_add_u32 s74, s16, 0x60000
	s_addc_u32 s75, s17, 0
	s_add_i32 m0, s28, 0x13000
	s_nop 0
	global_load_lds_dwordx4 v133, s[74:75]
	s_add_u32 s74, s16, 0x80000
	s_addc_u32 s75, s17, 0
	s_add_i32 m0, s28, 0x14000
	s_nop 0
	global_load_lds_dwordx4 v133, s[74:75]
	s_add_u32 s74, s16, 0xa0000
	s_addc_u32 s75, s17, 0
	s_add_i32 m0, s28, 0x15000
	s_nop 0
	global_load_lds_dwordx4 v133, s[74:75]
	s_add_u32 s74, s16, 0xc0000
	s_addc_u32 s75, s17, 0
	s_add_i32 m0, s28, 0x16000
	s_nop 0
	global_load_lds_dwordx4 v133, s[74:75]
	s_waitcnt vmcnt(8)
	s_waitcnt lgkmcnt(0)
	s_barrier
	v_mfma_f32_16x16x32_bf16 v[62:65], v[136:139], v[168:171], 0
	v_mfma_f32_16x16x32_bf16 v[58:61], v[144:147], v[168:171], 0
	v_mfma_f32_16x16x32_bf16 v[54:57], v[136:139], v[176:179], 0
	v_mfma_f32_16x16x32_bf16 v[50:53], v[144:147], v[176:179], 0
	v_mfma_f32_16x16x32_bf16 v[38:41], v[136:139], v[184:187], 0
	v_mfma_f32_16x16x32_bf16 v[34:37], v[144:147], v[184:187], 0
	v_mfma_f32_16x16x32_bf16 v[22:25], v[136:139], v[192:195], 0
	v_mfma_f32_16x16x32_bf16 v[18:21], v[144:147], v[192:195], 0
	v_mfma_f32_16x16x32_bf16 v[62:65], v[140:143], v[172:175], v[62:65]
	v_mfma_f32_16x16x32_bf16 v[58:61], v[148:151], v[172:175], v[58:61]
	v_mfma_f32_16x16x32_bf16 v[54:57], v[140:143], v[180:183], v[54:57]
	v_mfma_f32_16x16x32_bf16 v[50:53], v[148:151], v[180:183], v[50:53]
	v_mfma_f32_16x16x32_bf16 v[38:41], v[140:143], v[188:191], v[38:41]
	v_mfma_f32_16x16x32_bf16 v[34:37], v[148:151], v[188:191], v[34:37]
	v_mfma_f32_16x16x32_bf16 v[22:25], v[140:143], v[196:199], v[22:25]
	v_mfma_f32_16x16x32_bf16 v[18:21], v[148:151], v[196:199], v[18:21]
	v_mfma_f32_16x16x32_bf16 v[46:49], v[152:155], v[168:171], 0
	v_mfma_f32_16x16x32_bf16 v[42:45], v[160:163], v[168:171], 0
	v_mfma_f32_16x16x32_bf16 v[30:33], v[152:155], v[176:179], 0
	v_mfma_f32_16x16x32_bf16 v[26:29], v[160:163], v[176:179], 0
	v_mfma_f32_16x16x32_bf16 v[14:17], v[152:155], v[184:187], 0
	v_mfma_f32_16x16x32_bf16 v[10:13], v[160:163], v[184:187], 0
	v_mfma_f32_16x16x32_bf16 v[6:9], v[152:155], v[192:195], 0
	v_mfma_f32_16x16x32_bf16 v[2:5], v[160:163], v[192:195], 0
	v_mfma_f32_16x16x32_bf16 v[46:49], v[156:159], v[172:175], v[46:49]
	v_mfma_f32_16x16x32_bf16 v[42:45], v[164:167], v[172:175], v[42:45]
	v_mfma_f32_16x16x32_bf16 v[30:33], v[156:159], v[180:183], v[30:33]
	v_mfma_f32_16x16x32_bf16 v[26:29], v[164:167], v[180:183], v[26:29]
	v_mfma_f32_16x16x32_bf16 v[14:17], v[156:159], v[188:191], v[14:17]
	v_mfma_f32_16x16x32_bf16 v[10:13], v[164:167], v[188:191], v[10:13]
	v_mfma_f32_16x16x32_bf16 v[6:9], v[156:159], v[196:199], v[6:9]
	v_mfma_f32_16x16x32_bf16 v[2:5], v[164:167], v[196:199], v[2:5]
	s_barrier
	v_add_u32_e32 v0, 0x18000, v134
	ds_read_b128 v[136:139], v0
	ds_read_b128 v[140:143], v0 offset:1024
	ds_read_b128 v[144:147], v0 offset:2048
	ds_read_b128 v[148:151], v0 offset:3072
	v_add_u32_e32 v0, 0x1c000, v134
	ds_read_b128 v[152:155], v0
	ds_read_b128 v[156:159], v0 offset:1024
	ds_read_b128 v[160:163], v0 offset:2048
	ds_read_b128 v[164:167], v0 offset:3072
	ds_read_b128 v[168:171], v135 offset:32768
	ds_read_b128 v[172:175], v135 offset:33792
	ds_read_b128 v[176:179], v135 offset:34816
	ds_read_b128 v[180:183], v135 offset:35840
	ds_read_b128 v[184:187], v135 offset:36864
	ds_read_b128 v[188:191], v135 offset:37888
	ds_read_b128 v[192:195], v135 offset:38912
	ds_read_b128 v[196:199], v135 offset:39936
	s_add_u32 s74, s4, 0xfffe0080
	s_addc_u32 s75, s5, -1
	s_add_i32 m0, s28, 0x7000
	s_nop 0
	global_load_lds_dwordx4 v132, s[74:75]
	s_add_u32 s74, s4, 0x80
	s_addc_u32 s75, s5, 0
	s_add_i32 m0, s28, 0x8000
	s_nop 0
	global_load_lds_dwordx4 v132, s[74:75]
	s_add_u32 s74, s4, 0xa0000
	s_addc_u32 s75, s5, 0
	s_add_i32 m0, s28, 0x5000
	s_nop 0
	global_load_lds_dwordx4 v132, s[74:75]
	s_add_u32 s74, s4, 0xc0000
	s_addc_u32 s75, s5, 0
	s_add_i32 m0, s28, 0x6000
	s_nop 0
	global_load_lds_dwordx4 v132, s[74:75]
	s_waitcnt vmcnt(8)
	s_waitcnt lgkmcnt(0)
	s_barrier
	v_mfma_f32_16x16x32_bf16 v[126:129], v[136:139], v[168:171], v[126:129]
	v_mfma_f32_16x16x32_bf16 v[122:125], v[144:147], v[168:171], v[122:125]
	v_mfma_f32_16x16x32_bf16 v[118:121], v[136:139], v[176:179], v[118:121]
	v_mfma_f32_16x16x32_bf16 v[114:117], v[144:147], v[176:179], v[114:117]
	v_mfma_f32_16x16x32_bf16 v[102:105], v[136:139], v[184:187], v[102:105]
	v_mfma_f32_16x16x32_bf16 v[98:101], v[144:147], v[184:187], v[98:101]
	v_mfma_f32_16x16x32_bf16 v[86:89], v[136:139], v[192:195], v[86:89]
	v_mfma_f32_16x16x32_bf16 v[82:85], v[144:147], v[192:195], v[82:85]
	v_mfma_f32_16x16x32_bf16 v[126:129], v[140:143], v[172:175], v[126:129]
	v_mfma_f32_16x16x32_bf16 v[122:125], v[148:151], v[172:175], v[122:125]
	v_mfma_f32_16x16x32_bf16 v[118:121], v[140:143], v[180:183], v[118:121]
	v_mfma_f32_16x16x32_bf16 v[114:117], v[148:151], v[180:183], v[114:117]
	v_mfma_f32_16x16x32_bf16 v[102:105], v[140:143], v[188:191], v[102:105]
	v_mfma_f32_16x16x32_bf16 v[98:101], v[148:151], v[188:191], v[98:101]
	v_mfma_f32_16x16x32_bf16 v[86:89], v[140:143], v[196:199], v[86:89]
	v_mfma_f32_16x16x32_bf16 v[82:85], v[148:151], v[196:199], v[82:85]
	v_mfma_f32_16x16x32_bf16 v[110:113], v[152:155], v[168:171], v[110:113]
	v_mfma_f32_16x16x32_bf16 v[106:109], v[160:163], v[168:171], v[106:109]
	v_mfma_f32_16x16x32_bf16 v[94:97], v[152:155], v[176:179], v[94:97]
	v_mfma_f32_16x16x32_bf16 v[90:93], v[160:163], v[176:179], v[90:93]
	v_mfma_f32_16x16x32_bf16 v[78:81], v[152:155], v[184:187], v[78:81]
	v_mfma_f32_16x16x32_bf16 v[74:77], v[160:163], v[184:187], v[74:77]
	v_mfma_f32_16x16x32_bf16 v[70:73], v[152:155], v[192:195], v[70:73]
	v_mfma_f32_16x16x32_bf16 v[66:69], v[160:163], v[192:195], v[66:69]
	v_mfma_f32_16x16x32_bf16 v[110:113], v[156:159], v[172:175], v[110:113]
	v_mfma_f32_16x16x32_bf16 v[106:109], v[164:167], v[172:175], v[106:109]
	v_mfma_f32_16x16x32_bf16 v[94:97], v[156:159], v[180:183], v[94:97]
	v_mfma_f32_16x16x32_bf16 v[90:93], v[164:167], v[180:183], v[90:93]
	v_mfma_f32_16x16x32_bf16 v[78:81], v[156:159], v[188:191], v[78:81]
	v_mfma_f32_16x16x32_bf16 v[74:77], v[164:167], v[188:191], v[74:77]
	v_mfma_f32_16x16x32_bf16 v[70:73], v[156:159], v[196:199], v[70:73]
	v_mfma_f32_16x16x32_bf16 v[66:69], v[164:167], v[196:199], v[66:69]
	s_barrier
	ds_read_b128 v[168:171], v135 offset:49152
	ds_read_b128 v[172:175], v135 offset:50176
	ds_read_b128 v[176:179], v135 offset:51200
	ds_read_b128 v[180:183], v135 offset:52224
	ds_read_b128 v[184:187], v135 offset:53248
	ds_read_b128 v[188:191], v135 offset:54272
	ds_read_b128 v[192:195], v135 offset:55296
	ds_read_b128 v[196:199], v135 offset:56320
	s_add_u32 s74, s16, 0x60080
	s_addc_u32 s75, s17, 0
	s_add_i32 m0, s28, 0x1b000
	s_nop 0
	global_load_lds_dwordx4 v133, s[74:75]
	s_add_u32 s74, s16, 0x80080
	s_addc_u32 s75, s17, 0
	s_add_i32 m0, s28, 0x1c000
	s_nop 0
	global_load_lds_dwordx4 v133, s[74:75]
	s_add_u32 s74, s16, 0xa0080
	s_addc_u32 s75, s17, 0
	s_add_i32 m0, s28, 0x1d000
	s_nop 0
	global_load_lds_dwordx4 v133, s[74:75]
	s_add_u32 s74, s16, 0xc0080
	s_addc_u32 s75, s17, 0
	s_add_i32 m0, s28, 0x1e000
	s_nop 0
	global_load_lds_dwordx4 v133, s[74:75]
	s_waitcnt vmcnt(8)
	s_waitcnt lgkmcnt(0)
	s_barrier
	v_mfma_f32_16x16x32_bf16 v[62:65], v[136:139], v[168:171], v[62:65]
	v_mfma_f32_16x16x32_bf16 v[58:61], v[144:147], v[168:171], v[58:61]
	v_mfma_f32_16x16x32_bf16 v[54:57], v[136:139], v[176:179], v[54:57]
	v_mfma_f32_16x16x32_bf16 v[50:53], v[144:147], v[176:179], v[50:53]
	v_mfma_f32_16x16x32_bf16 v[38:41], v[136:139], v[184:187], v[38:41]
	v_mfma_f32_16x16x32_bf16 v[34:37], v[144:147], v[184:187], v[34:37]
	v_mfma_f32_16x16x32_bf16 v[22:25], v[136:139], v[192:195], v[22:25]
	v_mfma_f32_16x16x32_bf16 v[18:21], v[144:147], v[192:195], v[18:21]
	v_mfma_f32_16x16x32_bf16 v[62:65], v[140:143], v[172:175], v[62:65]
	v_mfma_f32_16x16x32_bf16 v[58:61], v[148:151], v[172:175], v[58:61]
	v_mfma_f32_16x16x32_bf16 v[54:57], v[140:143], v[180:183], v[54:57]
	v_mfma_f32_16x16x32_bf16 v[50:53], v[148:151], v[180:183], v[50:53]
	v_mfma_f32_16x16x32_bf16 v[38:41], v[140:143], v[188:191], v[38:41]
	v_mfma_f32_16x16x32_bf16 v[34:37], v[148:151], v[188:191], v[34:37]
	v_mfma_f32_16x16x32_bf16 v[22:25], v[140:143], v[196:199], v[22:25]
	v_mfma_f32_16x16x32_bf16 v[18:21], v[148:151], v[196:199], v[18:21]
	v_mfma_f32_16x16x32_bf16 v[46:49], v[152:155], v[168:171], v[46:49]
	v_mfma_f32_16x16x32_bf16 v[42:45], v[160:163], v[168:171], v[42:45]
	v_mfma_f32_16x16x32_bf16 v[30:33], v[152:155], v[176:179], v[30:33]
	v_mfma_f32_16x16x32_bf16 v[26:29], v[160:163], v[176:179], v[26:29]
	v_mfma_f32_16x16x32_bf16 v[14:17], v[152:155], v[184:187], v[14:17]
	v_mfma_f32_16x16x32_bf16 v[10:13], v[160:163], v[184:187], v[10:13]
	v_mfma_f32_16x16x32_bf16 v[6:9], v[152:155], v[192:195], v[6:9]
	v_mfma_f32_16x16x32_bf16 v[2:5], v[160:163], v[192:195], v[2:5]
	v_mfma_f32_16x16x32_bf16 v[46:49], v[156:159], v[172:175], v[46:49]
	v_mfma_f32_16x16x32_bf16 v[42:45], v[164:167], v[172:175], v[42:45]
	v_mfma_f32_16x16x32_bf16 v[30:33], v[156:159], v[180:183], v[30:33]
	v_mfma_f32_16x16x32_bf16 v[26:29], v[164:167], v[180:183], v[26:29]
	v_mfma_f32_16x16x32_bf16 v[14:17], v[156:159], v[188:191], v[14:17]
	v_mfma_f32_16x16x32_bf16 v[10:13], v[164:167], v[188:191], v[10:13]
	v_mfma_f32_16x16x32_bf16 v[6:9], v[156:159], v[196:199], v[6:9]
	v_mfma_f32_16x16x32_bf16 v[2:5], v[164:167], v[196:199], v[2:5]
	s_barrier
	s_add_i32 s72, s72, 2
	s_add_u32 s64, s64, 0x100
	s_addc_u32 s66, s66, 0
	s_add_u32 s68, s68, 0x100
	s_addc_u32 s70, s70, 0
TB_L24945_Bloop:
	s_cmp_eq_u32 s72, 28
	s_cselect_b32 s4, s60, s64
	s_cselect_b32 s5, s21, s66
	s_cselect_b32 s16, s62, s68
	s_cselect_b32 s17, s19, s70
	v_add_u32_e32 v0, 0x10000, v134
	ds_read_b128 v[136:139], v0
	ds_read_b128 v[140:143], v0 offset:1024
	ds_read_b128 v[144:147], v0 offset:2048
	ds_read_b128 v[148:151], v0 offset:3072
	v_add_u32_e32 v0, 0x14000, v134
	ds_read_b128 v[152:155], v0
	ds_read_b128 v[156:159], v0 offset:1024
	ds_read_b128 v[160:163], v0 offset:2048
	ds_read_b128 v[164:167], v0 offset:3072
	ds_read_b128 v[168:171], v135
	ds_read_b128 v[172:175], v135 offset:1024
	ds_read_b128 v[176:179], v135 offset:2048
	ds_read_b128 v[180:183], v135 offset:3072
	ds_read_b128 v[184:187], v135 offset:4096
	ds_read_b128 v[188:191], v135 offset:5120
	ds_read_b128 v[192:195], v135 offset:6144
	ds_read_b128 v[196:199], v135 offset:7168
	s_add_u32 s74, s4, 0xfffe0000
	s_addc_u32 s75, s5, -1
	s_add_i32 m0, s28, 0xfffff000
	s_nop 0
	global_load_lds_dwordx4 v132, s[74:75]
	s_mov_b32 s74, s4
	s_mov_b32 s75, s5
	s_mov_b32 m0, s28
	s_nop 0
	global_load_lds_dwordx4 v132, s[74:75]
	s_add_u32 s74, s64, 0x9ff80
	s_addc_u32 s75, s66, 0
	s_add_i32 m0, s28, 0xd000
	s_nop 0
	global_load_lds_dwordx4 v132, s[74:75]
	s_add_u32 s74, s64, 0xbff80
	s_addc_u32 s75, s66, 0
	s_add_i32 m0, s28, 0xe000
	s_nop 0
	global_load_lds_dwordx4 v132, s[74:75]
	s_waitcnt vmcnt(8)
	s_waitcnt lgkmcnt(0)
	s_barrier
	v_mfma_f32_16x16x32_bf16 v[126:129], v[136:139], v[168:171], v[126:129]
	v_mfma_f32_16x16x32_bf16 v[122:125], v[144:147], v[168:171], v[122:125]
	v_mfma_f32_16x16x32_bf16 v[118:121], v[136:139], v[176:179], v[118:121]
	v_mfma_f32_16x16x32_bf16 v[114:117], v[144:147], v[176:179], v[114:117]
	v_mfma_f32_16x16x32_bf16 v[102:105], v[136:139], v[184:187], v[102:105]
	v_mfma_f32_16x16x32_bf16 v[98:101], v[144:147], v[184:187], v[98:101]
	v_mfma_f32_16x16x32_bf16 v[86:89], v[136:139], v[192:195], v[86:89]
	v_mfma_f32_16x16x32_bf16 v[82:85], v[144:147], v[192:195], v[82:85]
	v_mfma_f32_16x16x32_bf16 v[126:129], v[140:143], v[172:175], v[126:129]
	v_mfma_f32_16x16x32_bf16 v[122:125], v[148:151], v[172:175], v[122:125]
	v_mfma_f32_16x16x32_bf16 v[118:121], v[140:143], v[180:183], v[118:121]
	v_mfma_f32_16x16x32_bf16 v[114:117], v[148:151], v[180:183], v[114:117]
	v_mfma_f32_16x16x32_bf16 v[102:105], v[140:143], v[188:191], v[102:105]
	v_mfma_f32_16x16x32_bf16 v[98:101], v[148:151], v[188:191], v[98:101]
	v_mfma_f32_16x16x32_bf16 v[86:89], v[140:143], v[196:199], v[86:89]
	v_mfma_f32_16x16x32_bf16 v[82:85], v[148:151], v[196:199], v[82:85]
	v_mfma_f32_16x16x32_bf16 v[110:113], v[152:155], v[168:171], v[110:113]
	v_mfma_f32_16x16x32_bf16 v[106:109], v[160:163], v[168:171], v[106:109]
	v_mfma_f32_16x16x32_bf16 v[94:97], v[152:155], v[176:179], v[94:97]
	v_mfma_f32_16x16x32_bf16 v[90:93], v[160:163], v[176:179], v[90:93]
	v_mfma_f32_16x16x32_bf16 v[78:81], v[152:155], v[184:187], v[78:81]
	v_mfma_f32_16x16x32_bf16 v[74:77], v[160:163], v[184:187], v[74:77]
	v_mfma_f32_16x16x32_bf16 v[70:73], v[152:155], v[192:195], v[70:73]
	v_mfma_f32_16x16x32_bf16 v[66:69], v[160:163], v[192:195], v[66:69]
	v_mfma_f32_16x16x32_bf16 v[110:113], v[156:159], v[172:175], v[110:113]
	v_mfma_f32_16x16x32_bf16 v[106:109], v[164:167], v[172:175], v[106:109]
	v_mfma_f32_16x16x32_bf16 v[94:97], v[156:159], v[180:183], v[94:97]
	v_mfma_f32_16x16x32_bf16 v[90:93], v[164:167], v[180:183], v[90:93]
	v_mfma_f32_16x16x32_bf16 v[78:81], v[156:159], v[188:191], v[78:81]
	v_mfma_f32_16x16x32_bf16 v[74:77], v[164:167], v[188:191], v[74:77]
	v_mfma_f32_16x16x32_bf16 v[70:73], v[156:159], v[196:199], v[70:73]
	v_mfma_f32_16x16x32_bf16 v[66:69], v[164:167], v[196:199], v[66:69]
	s_barrier
	ds_read_b128 v[168:171], v135 offset:16384
	ds_read_b128 v[172:175], v135 offset:17408
	ds_read_b128 v[176:179], v135 offset:18432
	ds_read_b128 v[180:183], v135 offset:19456
	ds_read_b128 v[184:187], v135 offset:20480
	ds_read_b128 v[188:191], v135 offset:21504
	ds_read_b128 v[192:195], v135 offset:22528
	ds_read_b128 v[196:199], v135 offset:23552
	s_add_u32 s74, s16, 0x60000
	s_addc_u32 s75, s17, 0
	s_add_i32 m0, s28, 0x13000
	s_nop 0
	global_load_lds_dwordx4 v133, s[74:75]
	s_add_u32 s74, s16, 0x80000
	s_addc_u32 s75, s17, 0
	s_add_i32 m0, s28, 0x14000
	s_nop 0
	global_load_lds_dwordx4 v133, s[74:75]
	s_add_u32 s74, s16, 0xa0000
	s_addc_u32 s75, s17, 0
	s_add_i32 m0, s28, 0x15000
	s_nop 0
	global_load_lds_dwordx4 v133, s[74:75]
	s_add_u32 s74, s16, 0xc0000
	s_addc_u32 s75, s17, 0
	s_add_i32 m0, s28, 0x16000
	s_nop 0
	global_load_lds_dwordx4 v133, s[74:75]
	s_waitcnt vmcnt(8)
	s_waitcnt lgkmcnt(0)
	s_barrier
	v_mfma_f32_16x16x32_bf16 v[62:65], v[136:139], v[168:171], v[62:65]
	v_mfma_f32_16x16x32_bf16 v[58:61], v[144:147], v[168:171], v[58:61]
	v_mfma_f32_16x16x32_bf16 v[54:57], v[136:139], v[176:179], v[54:57]
	v_mfma_f32_16x16x32_bf16 v[50:53], v[144:147], v[176:179], v[50:53]
	v_mfma_f32_16x16x32_bf16 v[38:41], v[136:139], v[184:187], v[38:41]
	v_mfma_f32_16x16x32_bf16 v[34:37], v[144:147], v[184:187], v[34:37]
	v_mfma_f32_16x16x32_bf16 v[22:25], v[136:139], v[192:195], v[22:25]
	v_mfma_f32_16x16x32_bf16 v[18:21], v[144:147], v[192:195], v[18:21]
	v_mfma_f32_16x16x32_bf16 v[62:65], v[140:143], v[172:175], v[62:65]
	v_mfma_f32_16x16x32_bf16 v[58:61], v[148:151], v[172:175], v[58:61]
	v_mfma_f32_16x16x32_bf16 v[54:57], v[140:143], v[180:183], v[54:57]
	v_mfma_f32_16x16x32_bf16 v[50:53], v[148:151], v[180:183], v[50:53]
	v_mfma_f32_16x16x32_bf16 v[38:41], v[140:143], v[188:191], v[38:41]
	v_mfma_f32_16x16x32_bf16 v[34:37], v[148:151], v[188:191], v[34:37]
	v_mfma_f32_16x16x32_bf16 v[22:25], v[140:143], v[196:199], v[22:25]
	v_mfma_f32_16x16x32_bf16 v[18:21], v[148:151], v[196:199], v[18:21]
	v_mfma_f32_16x16x32_bf16 v[46:49], v[152:155], v[168:171], v[46:49]
	v_mfma_f32_16x16x32_bf16 v[42:45], v[160:163], v[168:171], v[42:45]
	v_mfma_f32_16x16x32_bf16 v[30:33], v[152:155], v[176:179], v[30:33]
	v_mfma_f32_16x16x32_bf16 v[26:29], v[160:163], v[176:179], v[26:29]
	v_mfma_f32_16x16x32_bf16 v[14:17], v[152:155], v[184:187], v[14:17]
	v_mfma_f32_16x16x32_bf16 v[10:13], v[160:163], v[184:187], v[10:13]
	v_mfma_f32_16x16x32_bf16 v[6:9], v[152:155], v[192:195], v[6:9]
	v_mfma_f32_16x16x32_bf16 v[2:5], v[160:163], v[192:195], v[2:5]
	v_mfma_f32_16x16x32_bf16 v[46:49], v[156:159], v[172:175], v[46:49]
	v_mfma_f32_16x16x32_bf16 v[42:45], v[164:167], v[172:175], v[42:45]
	v_mfma_f32_16x16x32_bf16 v[30:33], v[156:159], v[180:183], v[30:33]
	v_mfma_f32_16x16x32_bf16 v[26:29], v[164:167], v[180:183], v[26:29]
	v_mfma_f32_16x16x32_bf16 v[14:17], v[156:159], v[188:191], v[14:17]
	v_mfma_f32_16x16x32_bf16 v[10:13], v[164:167], v[188:191], v[10:13]
	v_mfma_f32_16x16x32_bf16 v[6:9], v[156:159], v[196:199], v[6:9]
	v_mfma_f32_16x16x32_bf16 v[2:5], v[164:167], v[196:199], v[2:5]
	s_barrier
	v_add_u32_e32 v0, 0x18000, v134
	ds_read_b128 v[136:139], v0
	ds_read_b128 v[140:143], v0 offset:1024
	ds_read_b128 v[144:147], v0 offset:2048
	ds_read_b128 v[148:151], v0 offset:3072
	v_add_u32_e32 v0, 0x1c000, v134
	ds_read_b128 v[152:155], v0
	ds_read_b128 v[156:159], v0 offset:1024
	ds_read_b128 v[160:163], v0 offset:2048
	ds_read_b128 v[164:167], v0 offset:3072
	ds_read_b128 v[168:171], v135 offset:32768
	ds_read_b128 v[172:175], v135 offset:33792
	ds_read_b128 v[176:179], v135 offset:34816
	ds_read_b128 v[180:183], v135 offset:35840
	ds_read_b128 v[184:187], v135 offset:36864
	ds_read_b128 v[188:191], v135 offset:37888
	ds_read_b128 v[192:195], v135 offset:38912
	ds_read_b128 v[196:199], v135 offset:39936
	s_add_u32 s74, s4, 0xfffe0080
	s_addc_u32 s75, s5, -1
	s_add_i32 m0, s28, 0x7000
	s_nop 0
	global_load_lds_dwordx4 v132, s[74:75]
	s_add_u32 s74, s4, 0x80
	s_addc_u32 s75, s5, 0
	s_add_i32 m0, s28, 0x8000
	s_nop 0
	global_load_lds_dwordx4 v132, s[74:75]
	s_add_u32 s74, s4, 0xa0000
	s_addc_u32 s75, s5, 0
	s_add_i32 m0, s28, 0x5000
	s_nop 0
	global_load_lds_dwordx4 v132, s[74:75]
	s_add_u32 s74, s4, 0xc0000
	s_addc_u32 s75, s5, 0
	s_add_i32 m0, s28, 0x6000
	s_nop 0
	global_load_lds_dwordx4 v132, s[74:75]
	s_waitcnt vmcnt(8)
	s_waitcnt lgkmcnt(0)
	s_barrier
	v_mfma_f32_16x16x32_bf16 v[126:129], v[136:139], v[168:171], v[126:129]
	v_mfma_f32_16x16x32_bf16 v[122:125], v[144:147], v[168:171], v[122:125]
	v_mfma_f32_16x16x32_bf16 v[118:121], v[136:139], v[176:179], v[118:121]
	v_mfma_f32_16x16x32_bf16 v[114:117], v[144:147], v[176:179], v[114:117]
	v_mfma_f32_16x16x32_bf16 v[102:105], v[136:139], v[184:187], v[102:105]
	v_mfma_f32_16x16x32_bf16 v[98:101], v[144:147], v[184:187], v[98:101]
	v_mfma_f32_16x16x32_bf16 v[86:89], v[136:139], v[192:195], v[86:89]
	v_mfma_f32_16x16x32_bf16 v[82:85], v[144:147], v[192:195], v[82:85]
	v_mfma_f32_16x16x32_bf16 v[126:129], v[140:143], v[172:175], v[126:129]
	v_mfma_f32_16x16x32_bf16 v[122:125], v[148:151], v[172:175], v[122:125]
	v_mfma_f32_16x16x32_bf16 v[118:121], v[140:143], v[180:183], v[118:121]
	v_mfma_f32_16x16x32_bf16 v[114:117], v[148:151], v[180:183], v[114:117]
	v_mfma_f32_16x16x32_bf16 v[102:105], v[140:143], v[188:191], v[102:105]
	v_mfma_f32_16x16x32_bf16 v[98:101], v[148:151], v[188:191], v[98:101]
	v_mfma_f32_16x16x32_bf16 v[86:89], v[140:143], v[196:199], v[86:89]
	v_mfma_f32_16x16x32_bf16 v[82:85], v[148:151], v[196:199], v[82:85]
	v_mfma_f32_16x16x32_bf16 v[110:113], v[152:155], v[168:171], v[110:113]
	v_mfma_f32_16x16x32_bf16 v[106:109], v[160:163], v[168:171], v[106:109]
	v_mfma_f32_16x16x32_bf16 v[94:97], v[152:155], v[176:179], v[94:97]
	v_mfma_f32_16x16x32_bf16 v[90:93], v[160:163], v[176:179], v[90:93]
	v_mfma_f32_16x16x32_bf16 v[78:81], v[152:155], v[184:187], v[78:81]
	v_mfma_f32_16x16x32_bf16 v[74:77], v[160:163], v[184:187], v[74:77]
	v_mfma_f32_16x16x32_bf16 v[70:73], v[152:155], v[192:195], v[70:73]
	v_mfma_f32_16x16x32_bf16 v[66:69], v[160:163], v[192:195], v[66:69]
	v_mfma_f32_16x16x32_bf16 v[110:113], v[156:159], v[172:175], v[110:113]
	v_mfma_f32_16x16x32_bf16 v[106:109], v[164:167], v[172:175], v[106:109]
	v_mfma_f32_16x16x32_bf16 v[94:97], v[156:159], v[180:183], v[94:97]
	v_mfma_f32_16x16x32_bf16 v[90:93], v[164:167], v[180:183], v[90:93]
	v_mfma_f32_16x16x32_bf16 v[78:81], v[156:159], v[188:191], v[78:81]
	v_mfma_f32_16x16x32_bf16 v[74:77], v[164:167], v[188:191], v[74:77]
	v_mfma_f32_16x16x32_bf16 v[70:73], v[156:159], v[196:199], v[70:73]
	v_mfma_f32_16x16x32_bf16 v[66:69], v[164:167], v[196:199], v[66:69]
	s_barrier
	ds_read_b128 v[168:171], v135 offset:49152
	ds_read_b128 v[172:175], v135 offset:50176
	ds_read_b128 v[176:179], v135 offset:51200
	ds_read_b128 v[180:183], v135 offset:52224
	ds_read_b128 v[184:187], v135 offset:53248
	ds_read_b128 v[188:191], v135 offset:54272
	ds_read_b128 v[192:195], v135 offset:55296
	ds_read_b128 v[196:199], v135 offset:56320
	s_add_u32 s74, s16, 0x60080
	s_addc_u32 s75, s17, 0
	s_add_i32 m0, s28, 0x1b000
	s_nop 0
	global_load_lds_dwordx4 v133, s[74:75]
	s_add_u32 s74, s16, 0x80080
	s_addc_u32 s75, s17, 0
	s_add_i32 m0, s28, 0x1c000
	s_nop 0
	global_load_lds_dwordx4 v133, s[74:75]
	s_add_u32 s74, s16, 0xa0080
	s_addc_u32 s75, s17, 0
	s_add_i32 m0, s28, 0x1d000
	s_nop 0
	global_load_lds_dwordx4 v133, s[74:75]
	s_add_u32 s74, s16, 0xc0080
	s_addc_u32 s75, s17, 0
	s_add_i32 m0, s28, 0x1e000
	s_nop 0
	global_load_lds_dwordx4 v133, s[74:75]
	s_waitcnt vmcnt(8)
	s_waitcnt lgkmcnt(0)
	s_barrier
	v_mfma_f32_16x16x32_bf16 v[62:65], v[136:139], v[168:171], v[62:65]
	v_mfma_f32_16x16x32_bf16 v[58:61], v[144:147], v[168:171], v[58:61]
	v_mfma_f32_16x16x32_bf16 v[54:57], v[136:139], v[176:179], v[54:57]
	v_mfma_f32_16x16x32_bf16 v[50:53], v[144:147], v[176:179], v[50:53]
	v_mfma_f32_16x16x32_bf16 v[38:41], v[136:139], v[184:187], v[38:41]
	v_mfma_f32_16x16x32_bf16 v[34:37], v[144:147], v[184:187], v[34:37]
	v_mfma_f32_16x16x32_bf16 v[22:25], v[136:139], v[192:195], v[22:25]
	v_mfma_f32_16x16x32_bf16 v[18:21], v[144:147], v[192:195], v[18:21]
	v_mfma_f32_16x16x32_bf16 v[62:65], v[140:143], v[172:175], v[62:65]
	v_mfma_f32_16x16x32_bf16 v[58:61], v[148:151], v[172:175], v[58:61]
	v_mfma_f32_16x16x32_bf16 v[54:57], v[140:143], v[180:183], v[54:57]
	v_mfma_f32_16x16x32_bf16 v[50:53], v[148:151], v[180:183], v[50:53]
	v_mfma_f32_16x16x32_bf16 v[38:41], v[140:143], v[188:191], v[38:41]
	v_mfma_f32_16x16x32_bf16 v[34:37], v[148:151], v[188:191], v[34:37]
	v_mfma_f32_16x16x32_bf16 v[22:25], v[140:143], v[196:199], v[22:25]
	v_mfma_f32_16x16x32_bf16 v[18:21], v[148:151], v[196:199], v[18:21]
	v_mfma_f32_16x16x32_bf16 v[46:49], v[152:155], v[168:171], v[46:49]
	v_mfma_f32_16x16x32_bf16 v[42:45], v[160:163], v[168:171], v[42:45]
	v_mfma_f32_16x16x32_bf16 v[30:33], v[152:155], v[176:179], v[30:33]
	v_mfma_f32_16x16x32_bf16 v[26:29], v[160:163], v[176:179], v[26:29]
	v_mfma_f32_16x16x32_bf16 v[14:17], v[152:155], v[184:187], v[14:17]
	v_mfma_f32_16x16x32_bf16 v[10:13], v[160:163], v[184:187], v[10:13]
	v_mfma_f32_16x16x32_bf16 v[6:9], v[152:155], v[192:195], v[6:9]
	v_mfma_f32_16x16x32_bf16 v[2:5], v[160:163], v[192:195], v[2:5]
	v_mfma_f32_16x16x32_bf16 v[46:49], v[156:159], v[172:175], v[46:49]
	v_mfma_f32_16x16x32_bf16 v[42:45], v[164:167], v[172:175], v[42:45]
	v_mfma_f32_16x16x32_bf16 v[30:33], v[156:159], v[180:183], v[30:33]
	v_mfma_f32_16x16x32_bf16 v[26:29], v[164:167], v[180:183], v[26:29]
	v_mfma_f32_16x16x32_bf16 v[14:17], v[156:159], v[188:191], v[14:17]
	v_mfma_f32_16x16x32_bf16 v[10:13], v[164:167], v[188:191], v[10:13]
	v_mfma_f32_16x16x32_bf16 v[6:9], v[156:159], v[196:199], v[6:9]
	v_mfma_f32_16x16x32_bf16 v[2:5], v[164:167], v[196:199], v[2:5]
	s_barrier
	s_add_i32 s72, s72, 2
	s_add_u32 s64, s64, 0x100
	s_addc_u32 s66, s66, 0
	s_add_u32 s68, s68, 0x100
	s_addc_u32 s70, s70, 0
	s_cmp_gt_u32 s72, 29
	s_cbranch_scc0 TB_L24945_Bloop
TB_L24945_exit:
	s_and_b64 vcc, exec, s[12:13]
	s_cbranch_vccz .LBB0_1049
	s_barrier

.LBB0_1654:
	s_and_b64 vcc, exec, s[10:11]
	s_cbranch_vccz TB_L40000_Bpeel
	s_cmp_eq_u32 s70, 28
	s_cselect_b32 s6, s58, s62
	s_cselect_b32 s7, s15, s64
	s_cselect_b32 s22, s60, s66
	s_cselect_b32 s23, s13, s68
	v_add_u32_e32 v130, 0x10000, v133
	ds_read_b128 v[136:139], v130
	ds_read_b128 v[140:143], v130 offset:1024
	ds_read_b128 v[144:147], v130 offset:2048
	ds_read_b128 v[148:151], v130 offset:3072
	v_add_u32_e32 v130, 0x14000, v133
	ds_read_b128 v[152:155], v130
	ds_read_b128 v[156:159], v130 offset:1024
	ds_read_b128 v[160:163], v130 offset:2048
	ds_read_b128 v[164:167], v130 offset:3072
	ds_read_b128 v[168:171], v134
	ds_read_b128 v[172:175], v134 offset:1024
	ds_read_b128 v[176:179], v134 offset:2048
	ds_read_b128 v[180:183], v134 offset:3072
	ds_read_b128 v[184:187], v134 offset:4096
	ds_read_b128 v[188:191], v134 offset:5120
	ds_read_b128 v[192:195], v134 offset:6144
	ds_read_b128 v[196:199], v134 offset:7168
	s_add_u32 s74, s62, 0x3ff80
	s_addc_u32 s75, s64, 0
	s_add_i32 m0, s26, 0xa000
	s_nop 0
	global_load_lds_dwordx4 v0, s[74:75]
	s_add_u32 s74, s62, 0x5ff80
	s_addc_u32 s75, s64, 0
	s_add_i32 m0, s26, 0xb000
	s_nop 0
	global_load_lds_dwordx4 v0, s[74:75]
	s_add_u32 s74, s62, 0x7ff80
	s_addc_u32 s75, s64, 0
	s_add_i32 m0, s26, 0xc000
	s_nop 0
	global_load_lds_dwordx4 v0, s[74:75]
	s_add_u32 s74, s62, 0x9ff80
	s_addc_u32 s75, s64, 0
	s_add_i32 m0, s26, 0xd000
	s_nop 0
	global_load_lds_dwordx4 v0, s[74:75]
	s_waitcnt vmcnt(8)
	s_waitcnt lgkmcnt(0)
	s_barrier
	v_mfma_f32_16x16x32_bf16 v[122:125], v[136:139], v[168:171], 0
	v_mfma_f32_16x16x32_bf16 v[114:117], v[144:147], v[168:171], 0
	v_mfma_f32_16x16x32_bf16 v[106:109], v[136:139], v[176:179], 0
	v_mfma_f32_16x16x32_bf16 v[98:101], v[144:147], v[176:179], 0
	v_mfma_f32_16x16x32_bf16 v[90:93], v[136:139], v[184:187], 0
	v_mfma_f32_16x16x32_bf16 v[82:85], v[144:147], v[184:187], 0
	v_mfma_f32_16x16x32_bf16 v[74:77], v[136:139], v[192:195], 0
	v_mfma_f32_16x16x32_bf16 v[66:69], v[144:147], v[192:195], 0
	v_mfma_f32_16x16x32_bf16 v[122:125], v[140:143], v[172:175], v[122:125]
	v_mfma_f32_16x16x32_bf16 v[114:117], v[148:151], v[172:175], v[114:117]
	v_mfma_f32_16x16x32_bf16 v[106:109], v[140:143], v[180:183], v[106:109]
	v_mfma_f32_16x16x32_bf16 v[98:101], v[148:151], v[180:183], v[98:101]
	v_mfma_f32_16x16x32_bf16 v[90:93], v[140:143], v[188:191], v[90:93]
	v_mfma_f32_16x16x32_bf16 v[82:85], v[148:151], v[188:191], v[82:85]
	v_mfma_f32_16x16x32_bf16 v[74:77], v[140:143], v[196:199], v[74:77]
	v_mfma_f32_16x16x32_bf16 v[66:69], v[148:151], v[196:199], v[66:69]
	v_mfma_f32_16x16x32_bf16 v[126:129], v[152:155], v[168:171], 0
	v_mfma_f32_16x16x32_bf16 v[118:121], v[160:163], v[168:171], 0
	v_mfma_f32_16x16x32_bf16 v[110:113], v[152:155], v[176:179], 0
	v_mfma_f32_16x16x32_bf16 v[102:105], v[160:163], v[176:179], 0
	v_mfma_f32_16x16x32_bf16 v[94:97], v[152:155], v[184:187], 0
	v_mfma_f32_16x16x32_bf16 v[86:89], v[160:163], v[184:187], 0
	v_mfma_f32_16x16x32_bf16 v[78:81], v[152:155], v[192:195], 0
	v_mfma_f32_16x16x32_bf16 v[70:73], v[160:163], v[192:195], 0
	v_mfma_f32_16x16x32_bf16 v[126:129], v[156:159], v[172:175], v[126:129]
	v_mfma_f32_16x16x32_bf16 v[118:121], v[164:167], v[172:175], v[118:121]
	v_mfma_f32_16x16x32_bf16 v[110:113], v[156:159], v[180:183], v[110:113]
	v_mfma_f32_16x16x32_bf16 v[102:105], v[164:167], v[180:183], v[102:105]
	v_mfma_f32_16x16x32_bf16 v[94:97], v[156:159], v[188:191], v[94:97]
	v_mfma_f32_16x16x32_bf16 v[86:89], v[164:167], v[188:191], v[86:89]
	v_mfma_f32_16x16x32_bf16 v[78:81], v[156:159], v[196:199], v[78:81]
	v_mfma_f32_16x16x32_bf16 v[70:73], v[164:167], v[196:199], v[70:73]
	s_barrier
	ds_read_b128 v[168:171], v134 offset:16384
	ds_read_b128 v[172:175], v134 offset:17408
	ds_read_b128 v[176:179], v134 offset:18432
	ds_read_b128 v[180:183], v134 offset:19456
	ds_read_b128 v[184:187], v134 offset:20480
	ds_read_b128 v[188:191], v134 offset:21504
	ds_read_b128 v[192:195], v134 offset:22528
	ds_read_b128 v[196:199], v134 offset:23552
	s_mov_b32 s74, s22
	s_mov_b32 s75, s23
	s_add_i32 m0, s26, 0x10000
	s_nop 0
	global_load_lds_dwordx4 v132, s[74:75]
	s_add_u32 s74, s22, 0x20000
	s_addc_u32 s75, s23, 0
	s_add_i32 m0, s26, 0x11000
	s_nop 0
	global_load_lds_dwordx4 v132, s[74:75]
	s_add_u32 s74, s22, 0x40000
	s_addc_u32 s75, s23, 0
	s_add_i32 m0, s26, 0x12000
	s_nop 0
	global_load_lds_dwordx4 v132, s[74:75]
	s_add_u32 s74, s22, 0x60000
	s_addc_u32 s75, s23, 0
	s_add_i32 m0, s26, 0x13000
	s_nop 0
	global_load_lds_dwordx4 v132, s[74:75]
	s_waitcnt vmcnt(8)
	s_waitcnt lgkmcnt(0)
	s_barrier
	v_mfma_f32_16x16x32_bf16 v[58:61], v[136:139], v[168:171], 0
	v_mfma_f32_16x16x32_bf16 v[50:53], v[144:147], v[168:171], 0
	v_mfma_f32_16x16x32_bf16 v[42:45], v[136:139], v[176:179], 0
	v_mfma_f32_16x16x32_bf16 v[34:37], v[144:147], v[176:179], 0
	v_mfma_f32_16x16x32_bf16 v[26:29], v[136:139], v[184:187], 0
	v_mfma_f32_16x16x32_bf16 v[18:21], v[144:147], v[184:187], 0
	v_mfma_f32_16x16x32_bf16 v[10:13], v[136:139], v[192:195], 0
	v_mfma_f32_16x16x32_bf16 v[2:5], v[144:147], v[192:195], 0
	v_mfma_f32_16x16x32_bf16 v[58:61], v[140:143], v[172:175], v[58:61]
	v_mfma_f32_16x16x32_bf16 v[50:53], v[148:151], v[172:175], v[50:53]
	v_mfma_f32_16x16x32_bf16 v[42:45], v[140:143], v[180:183], v[42:45]
	v_mfma_f32_16x16x32_bf16 v[34:37], v[148:151], v[180:183], v[34:37]
	v_mfma_f32_16x16x32_bf16 v[26:29], v[140:143], v[188:191], v[26:29]
	v_mfma_f32_16x16x32_bf16 v[18:21], v[148:151], v[188:191], v[18:21]
	v_mfma_f32_16x16x32_bf16 v[10:13], v[140:143], v[196:199], v[10:13]
	v_mfma_f32_16x16x32_bf16 v[2:5], v[148:151], v[196:199], v[2:5]
	v_mfma_f32_16x16x32_bf16 v[62:65], v[152:155], v[168:171], 0
	v_mfma_f32_16x16x32_bf16 v[54:57], v[160:163], v[168:171], 0
	v_mfma_f32_16x16x32_bf16 v[46:49], v[152:155], v[176:179], 0
	v_mfma_f32_16x16x32_bf16 v[38:41], v[160:163], v[176:179], 0
	v_mfma_f32_16x16x32_bf16 v[30:33], v[152:155], v[184:187], 0
	v_mfma_f32_16x16x32_bf16 v[22:25], v[160:163], v[184:187], 0
	v_mfma_f32_16x16x32_bf16 v[14:17], v[152:155], v[192:195], 0
	v_mfma_f32_16x16x32_bf16 v[6:9], v[160:163], v[192:195], 0
	v_mfma_f32_16x16x32_bf16 v[62:65], v[156:159], v[172:175], v[62:65]
	v_mfma_f32_16x16x32_bf16 v[54:57], v[164:167], v[172:175], v[54:57]
	v_mfma_f32_16x16x32_bf16 v[46:49], v[156:159], v[180:183], v[46:49]
	v_mfma_f32_16x16x32_bf16 v[38:41], v[164:167], v[180:183], v[38:41]
	v_mfma_f32_16x16x32_bf16 v[30:33], v[156:159], v[188:191], v[30:33]
	v_mfma_f32_16x16x32_bf16 v[22:25], v[164:167], v[188:191], v[22:25]
	v_mfma_f32_16x16x32_bf16 v[14:17], v[156:159], v[196:199], v[14:17]
	v_mfma_f32_16x16x32_bf16 v[6:9], v[164:167], v[196:199], v[6:9]
	s_barrier
	v_add_u32_e32 v130, 0x18000, v133
	ds_read_b128 v[136:139], v130
	ds_read_b128 v[140:143], v130 offset:1024
	ds_read_b128 v[144:147], v130 offset:2048
	ds_read_b128 v[148:151], v130 offset:3072
	v_add_u32_e32 v130, 0x1c000, v133
	ds_read_b128 v[152:155], v130
	ds_read_b128 v[156:159], v130 offset:1024
	ds_read_b128 v[160:163], v130 offset:2048
	ds_read_b128 v[164:167], v130 offset:3072
	ds_read_b128 v[168:171], v134 offset:32768
	ds_read_b128 v[172:175], v134 offset:33792
	ds_read_b128 v[176:179], v134 offset:34816
	ds_read_b128 v[180:183], v134 offset:35840
	ds_read_b128 v[184:187], v134 offset:36864
	ds_read_b128 v[188:191], v134 offset:37888
	ds_read_b128 v[192:195], v134 offset:38912
	ds_read_b128 v[196:199], v134 offset:39936
	s_add_u32 s74, s6, 0x40000
	s_addc_u32 s75, s7, 0
	s_add_i32 m0, s26, 0x2000
	s_nop 0
	global_load_lds_dwordx4 v0, s[74:75]
	s_add_u32 s74, s6, 0x60000
	s_addc_u32 s75, s7, 0
	s_add_i32 m0, s26, 0x3000
	s_nop 0
	global_load_lds_dwordx4 v0, s[74:75]
	s_add_u32 s74, s6, 0x80000
	s_addc_u32 s75, s7, 0
	s_add_i32 m0, s26, 0x4000
	s_nop 0
	global_load_lds_dwordx4 v0, s[74:75]
	s_add_u32 s74, s6, 0xa0000
	s_addc_u32 s75, s7, 0
	s_add_i32 m0, s26, 0x5000
	s_nop 0
	global_load_lds_dwordx4 v0, s[74:75]
	s_waitcnt vmcnt(8)
	s_waitcnt lgkmcnt(0)
	s_barrier
	v_mfma_f32_16x16x32_bf16 v[122:125], v[136:139], v[168:171], v[122:125]
	v_mfma_f32_16x16x32_bf16 v[114:117], v[144:147], v[168:171], v[114:117]
	v_mfma_f32_16x16x32_bf16 v[106:109], v[136:139], v[176:179], v[106:109]
	v_mfma_f32_16x16x32_bf16 v[98:101], v[144:147], v[176:179], v[98:101]
	v_mfma_f32_16x16x32_bf16 v[90:93], v[136:139], v[184:187], v[90:93]
	v_mfma_f32_16x16x32_bf16 v[82:85], v[144:147], v[184:187], v[82:85]
	v_mfma_f32_16x16x32_bf16 v[74:77], v[136:139], v[192:195], v[74:77]
	v_mfma_f32_16x16x32_bf16 v[66:69], v[144:147], v[192:195], v[66:69]
	v_mfma_f32_16x16x32_bf16 v[122:125], v[140:143], v[172:175], v[122:125]
	v_mfma_f32_16x16x32_bf16 v[114:117], v[148:151], v[172:175], v[114:117]
	v_mfma_f32_16x16x32_bf16 v[106:109], v[140:143], v[180:183], v[106:109]
	v_mfma_f32_16x16x32_bf16 v[98:101], v[148:151], v[180:183], v[98:101]
	v_mfma_f32_16x16x32_bf16 v[90:93], v[140:143], v[188:191], v[90:93]
	v_mfma_f32_16x16x32_bf16 v[82:85], v[148:151], v[188:191], v[82:85]
	v_mfma_f32_16x16x32_bf16 v[74:77], v[140:143], v[196:199], v[74:77]
	v_mfma_f32_16x16x32_bf16 v[66:69], v[148:151], v[196:199], v[66:69]
	v_mfma_f32_16x16x32_bf16 v[126:129], v[152:155], v[168:171], v[126:129]
	v_mfma_f32_16x16x32_bf16 v[118:121], v[160:163], v[168:171], v[118:121]
	v_mfma_f32_16x16x32_bf16 v[110:113], v[152:155], v[176:179], v[110:113]
	v_mfma_f32_16x16x32_bf16 v[102:105], v[160:163], v[176:179], v[102:105]
	v_mfma_f32_16x16x32_bf16 v[94:97], v[152:155], v[184:187], v[94:97]
	v_mfma_f32_16x16x32_bf16 v[86:89], v[160:163], v[184:187], v[86:89]
	v_mfma_f32_16x16x32_bf16 v[78:81], v[152:155], v[192:195], v[78:81]
	v_mfma_f32_16x16x32_bf16 v[70:73], v[160:163], v[192:195], v[70:73]
	v_mfma_f32_16x16x32_bf16 v[126:129], v[156:159], v[172:175], v[126:129]
	v_mfma_f32_16x16x32_bf16 v[118:121], v[164:167], v[172:175], v[118:121]
	v_mfma_f32_16x16x32_bf16 v[110:113], v[156:159], v[180:183], v[110:113]
	v_mfma_f32_16x16x32_bf16 v[102:105], v[164:167], v[180:183], v[102:105]
	v_mfma_f32_16x16x32_bf16 v[94:97], v[156:159], v[188:191], v[94:97]
	v_mfma_f32_16x16x32_bf16 v[86:89], v[164:167], v[188:191], v[86:89]
	v_mfma_f32_16x16x32_bf16 v[78:81], v[156:159], v[196:199], v[78:81]
	v_mfma_f32_16x16x32_bf16 v[70:73], v[164:167], v[196:199], v[70:73]
	s_barrier
	ds_read_b128 v[168:171], v134 offset:49152
	ds_read_b128 v[172:175], v134 offset:50176
	ds_read_b128 v[176:179], v134 offset:51200
	ds_read_b128 v[180:183], v134 offset:52224
	ds_read_b128 v[184:187], v134 offset:53248
	ds_read_b128 v[188:191], v134 offset:54272
	ds_read_b128 v[192:195], v134 offset:55296
	ds_read_b128 v[196:199], v134 offset:56320
	s_add_u32 s74, s22, 0x80
	s_addc_u32 s75, s23, 0
	s_add_i32 m0, s26, 0x18000
	s_nop 0
	global_load_lds_dwordx4 v132, s[74:75]
	s_add_u32 s74, s22, 0x20080
	s_addc_u32 s75, s23, 0
	s_add_i32 m0, s26, 0x19000
	s_nop 0
	global_load_lds_dwordx4 v132, s[74:75]
	s_add_u32 s74, s22, 0x40080
	s_addc_u32 s75, s23, 0
	s_add_i32 m0, s26, 0x1a000
	s_nop 0
	global_load_lds_dwordx4 v132, s[74:75]
	s_add_u32 s74, s22, 0x60080
	s_addc_u32 s75, s23, 0
	s_add_i32 m0, s26, 0x1b000
	s_nop 0
	global_load_lds_dwordx4 v132, s[74:75]
	s_waitcnt vmcnt(8)
	s_waitcnt lgkmcnt(0)
	s_barrier
	v_mfma_f32_16x16x32_bf16 v[58:61], v[136:139], v[168:171], v[58:61]
	v_mfma_f32_16x16x32_bf16 v[50:53], v[144:147], v[168:171], v[50:53]
	v_mfma_f32_16x16x32_bf16 v[42:45], v[136:139], v[176:179], v[42:45]
	v_mfma_f32_16x16x32_bf16 v[34:37], v[144:147], v[176:179], v[34:37]
	v_mfma_f32_16x16x32_bf16 v[26:29], v[136:139], v[184:187], v[26:29]
	v_mfma_f32_16x16x32_bf16 v[18:21], v[144:147], v[184:187], v[18:21]
	v_mfma_f32_16x16x32_bf16 v[10:13], v[136:139], v[192:195], v[10:13]
	v_mfma_f32_16x16x32_bf16 v[2:5], v[144:147], v[192:195], v[2:5]
	v_mfma_f32_16x16x32_bf16 v[58:61], v[140:143], v[172:175], v[58:61]
	v_mfma_f32_16x16x32_bf16 v[50:53], v[148:151], v[172:175], v[50:53]
	v_mfma_f32_16x16x32_bf16 v[42:45], v[140:143], v[180:183], v[42:45]
	v_mfma_f32_16x16x32_bf16 v[34:37], v[148:151], v[180:183], v[34:37]
	v_mfma_f32_16x16x32_bf16 v[26:29], v[140:143], v[188:191], v[26:29]
	v_mfma_f32_16x16x32_bf16 v[18:21], v[148:151], v[188:191], v[18:21]
	v_mfma_f32_16x16x32_bf16 v[10:13], v[140:143], v[196:199], v[10:13]
	v_mfma_f32_16x16x32_bf16 v[2:5], v[148:151], v[196:199], v[2:5]
	v_mfma_f32_16x16x32_bf16 v[62:65], v[152:155], v[168:171], v[62:65]
	v_mfma_f32_16x16x32_bf16 v[54:57], v[160:163], v[168:171], v[54:57]
	v_mfma_f32_16x16x32_bf16 v[46:49], v[152:155], v[176:179], v[46:49]
	v_mfma_f32_16x16x32_bf16 v[38:41], v[160:163], v[176:179], v[38:41]
	v_mfma_f32_16x16x32_bf16 v[30:33], v[152:155], v[184:187], v[30:33]
	v_mfma_f32_16x16x32_bf16 v[22:25], v[160:163], v[184:187], v[22:25]
	v_mfma_f32_16x16x32_bf16 v[14:17], v[152:155], v[192:195], v[14:17]
	v_mfma_f32_16x16x32_bf16 v[6:9], v[160:163], v[192:195], v[6:9]
	v_mfma_f32_16x16x32_bf16 v[62:65], v[156:159], v[172:175], v[62:65]
	v_mfma_f32_16x16x32_bf16 v[54:57], v[164:167], v[172:175], v[54:57]
	v_mfma_f32_16x16x32_bf16 v[46:49], v[156:159], v[180:183], v[46:49]
	v_mfma_f32_16x16x32_bf16 v[38:41], v[164:167], v[180:183], v[38:41]
	v_mfma_f32_16x16x32_bf16 v[30:33], v[156:159], v[188:191], v[30:33]
	v_mfma_f32_16x16x32_bf16 v[22:25], v[164:167], v[188:191], v[22:25]
	v_mfma_f32_16x16x32_bf16 v[14:17], v[156:159], v[196:199], v[14:17]
	v_mfma_f32_16x16x32_bf16 v[6:9], v[164:167], v[196:199], v[6:9]
	s_barrier
	s_add_i32 s70, s70, 2
	s_add_u32 s62, s62, 0x100
	s_addc_u32 s64, s64, 0
	s_add_u32 s66, s66, 0x100
	s_addc_u32 s68, s68, 0
TB_L40000_Aloop:
	s_cmp_eq_u32 s70, 28
	s_cselect_b32 s6, s58, s62
	s_cselect_b32 s7, s15, s64
	s_cselect_b32 s22, s60, s66
	s_cselect_b32 s23, s13, s68
	v_add_u32_e32 v130, 0x10000, v133
	ds_read_b128 v[136:139], v130
	ds_read_b128 v[140:143], v130 offset:1024
	ds_read_b128 v[144:147], v130 offset:2048
	ds_read_b128 v[148:151], v130 offset:3072
	v_add_u32_e32 v130, 0x14000, v133
	ds_read_b128 v[152:155], v130
	ds_read_b128 v[156:159], v130 offset:1024
	ds_read_b128 v[160:163], v130 offset:2048
	ds_read_b128 v[164:167], v130 offset:3072
	ds_read_b128 v[168:171], v134
	ds_read_b128 v[172:175], v134 offset:1024
	ds_read_b128 v[176:179], v134 offset:2048
	ds_read_b128 v[180:183], v134 offset:3072
	ds_read_b128 v[184:187], v134 offset:4096
	ds_read_b128 v[188:191], v134 offset:5120
	ds_read_b128 v[192:195], v134 offset:6144
	ds_read_b128 v[196:199], v134 offset:7168
	s_add_u32 s74, s62, 0x3ff80
	s_addc_u32 s75, s64, 0
	s_add_i32 m0, s26, 0xa000
	s_nop 0
	global_load_lds_dwordx4 v0, s[74:75]
	s_add_u32 s74, s62, 0x5ff80
	s_addc_u32 s75, s64, 0
	s_add_i32 m0, s26, 0xb000
	s_nop 0
	global_load_lds_dwordx4 v0, s[74:75]
	s_add_u32 s74, s62, 0x7ff80
	s_addc_u32 s75, s64, 0
	s_add_i32 m0, s26, 0xc000
	s_nop 0
	global_load_lds_dwordx4 v0, s[74:75]
	s_add_u32 s74, s62, 0x9ff80
	s_addc_u32 s75, s64, 0
	s_add_i32 m0, s26, 0xd000
	s_nop 0
	global_load_lds_dwordx4 v0, s[74:75]
	s_waitcnt vmcnt(8)
	s_waitcnt lgkmcnt(0)
	s_barrier
	v_mfma_f32_16x16x32_bf16 v[122:125], v[136:139], v[168:171], v[122:125]
	v_mfma_f32_16x16x32_bf16 v[114:117], v[144:147], v[168:171], v[114:117]
	v_mfma_f32_16x16x32_bf16 v[106:109], v[136:139], v[176:179], v[106:109]
	v_mfma_f32_16x16x32_bf16 v[98:101], v[144:147], v[176:179], v[98:101]
	v_mfma_f32_16x16x32_bf16 v[90:93], v[136:139], v[184:187], v[90:93]
	v_mfma_f32_16x16x32_bf16 v[82:85], v[144:147], v[184:187], v[82:85]
	v_mfma_f32_16x16x32_bf16 v[74:77], v[136:139], v[192:195], v[74:77]
	v_mfma_f32_16x16x32_bf16 v[66:69], v[144:147], v[192:195], v[66:69]
	v_mfma_f32_16x16x32_bf16 v[122:125], v[140:143], v[172:175], v[122:125]
	v_mfma_f32_16x16x32_bf16 v[114:117], v[148:151], v[172:175], v[114:117]
	v_mfma_f32_16x16x32_bf16 v[106:109], v[140:143], v[180:183], v[106:109]
	v_mfma_f32_16x16x32_bf16 v[98:101], v[148:151], v[180:183], v[98:101]
	v_mfma_f32_16x16x32_bf16 v[90:93], v[140:143], v[188:191], v[90:93]
	v_mfma_f32_16x16x32_bf16 v[82:85], v[148:151], v[188:191], v[82:85]
	v_mfma_f32_16x16x32_bf16 v[74:77], v[140:143], v[196:199], v[74:77]
	v_mfma_f32_16x16x32_bf16 v[66:69], v[148:151], v[196:199], v[66:69]
	v_mfma_f32_16x16x32_bf16 v[126:129], v[152:155], v[168:171], v[126:129]
	v_mfma_f32_16x16x32_bf16 v[118:121], v[160:163], v[168:171], v[118:121]
	v_mfma_f32_16x16x32_bf16 v[110:113], v[152:155], v[176:179], v[110:113]
	v_mfma_f32_16x16x32_bf16 v[102:105], v[160:163], v[176:179], v[102:105]
	v_mfma_f32_16x16x32_bf16 v[94:97], v[152:155], v[184:187], v[94:97]
	v_mfma_f32_16x16x32_bf16 v[86:89], v[160:163], v[184:187], v[86:89]
	v_mfma_f32_16x16x32_bf16 v[78:81], v[152:155], v[192:195], v[78:81]
	v_mfma_f32_16x16x32_bf16 v[70:73], v[160:163], v[192:195], v[70:73]
	v_mfma_f32_16x16x32_bf16 v[126:129], v[156:159], v[172:175], v[126:129]
	v_mfma_f32_16x16x32_bf16 v[118:121], v[164:167], v[172:175], v[118:121]
	v_mfma_f32_16x16x32_bf16 v[110:113], v[156:159], v[180:183], v[110:113]
	v_mfma_f32_16x16x32_bf16 v[102:105], v[164:167], v[180:183], v[102:105]
	v_mfma_f32_16x16x32_bf16 v[94:97], v[156:159], v[188:191], v[94:97]
	v_mfma_f32_16x16x32_bf16 v[86:89], v[164:167], v[188:191], v[86:89]
	v_mfma_f32_16x16x32_bf16 v[78:81], v[156:159], v[196:199], v[78:81]
	v_mfma_f32_16x16x32_bf16 v[70:73], v[164:167], v[196:199], v[70:73]
	s_barrier
	ds_read_b128 v[168:171], v134 offset:16384
	ds_read_b128 v[172:175], v134 offset:17408
	ds_read_b128 v[176:179], v134 offset:18432
	ds_read_b128 v[180:183], v134 offset:19456
	ds_read_b128 v[184:187], v134 offset:20480
	ds_read_b128 v[188:191], v134 offset:21504
	ds_read_b128 v[192:195], v134 offset:22528
	ds_read_b128 v[196:199], v134 offset:23552
	s_mov_b32 s74, s22
	s_mov_b32 s75, s23
	s_add_i32 m0, s26, 0x10000
	s_nop 0
	global_load_lds_dwordx4 v132, s[74:75]
	s_add_u32 s74, s22, 0x20000
	s_addc_u32 s75, s23, 0
	s_add_i32 m0, s26, 0x11000
	s_nop 0
	global_load_lds_dwordx4 v132, s[74:75]
	s_add_u32 s74, s22, 0x40000
	s_addc_u32 s75, s23, 0
	s_add_i32 m0, s26, 0x12000
	s_nop 0
	global_load_lds_dwordx4 v132, s[74:75]
	s_add_u32 s74, s22, 0x60000
	s_addc_u32 s75, s23, 0
	s_add_i32 m0, s26, 0x13000
	s_nop 0
	global_load_lds_dwordx4 v132, s[74:75]
	s_waitcnt vmcnt(8)
	s_waitcnt lgkmcnt(0)
	s_barrier
	v_mfma_f32_16x16x32_bf16 v[58:61], v[136:139], v[168:171], v[58:61]
	v_mfma_f32_16x16x32_bf16 v[50:53], v[144:147], v[168:171], v[50:53]
	v_mfma_f32_16x16x32_bf16 v[42:45], v[136:139], v[176:179], v[42:45]
	v_mfma_f32_16x16x32_bf16 v[34:37], v[144:147], v[176:179], v[34:37]
	v_mfma_f32_16x16x32_bf16 v[26:29], v[136:139], v[184:187], v[26:29]
	v_mfma_f32_16x16x32_bf16 v[18:21], v[144:147], v[184:187], v[18:21]
	v_mfma_f32_16x16x32_bf16 v[10:13], v[136:139], v[192:195], v[10:13]
	v_mfma_f32_16x16x32_bf16 v[2:5], v[144:147], v[192:195], v[2:5]
	v_mfma_f32_16x16x32_bf16 v[58:61], v[140:143], v[172:175], v[58:61]
	v_mfma_f32_16x16x32_bf16 v[50:53], v[148:151], v[172:175], v[50:53]
	v_mfma_f32_16x16x32_bf16 v[42:45], v[140:143], v[180:183], v[42:45]
	v_mfma_f32_16x16x32_bf16 v[34:37], v[148:151], v[180:183], v[34:37]
	v_mfma_f32_16x16x32_bf16 v[26:29], v[140:143], v[188:191], v[26:29]
	v_mfma_f32_16x16x32_bf16 v[18:21], v[148:151], v[188:191], v[18:21]
	v_mfma_f32_16x16x32_bf16 v[10:13], v[140:143], v[196:199], v[10:13]
	v_mfma_f32_16x16x32_bf16 v[2:5], v[148:151], v[196:199], v[2:5]
	v_mfma_f32_16x16x32_bf16 v[62:65], v[152:155], v[168:171], v[62:65]
	v_mfma_f32_16x16x32_bf16 v[54:57], v[160:163], v[168:171], v[54:57]
	v_mfma_f32_16x16x32_bf16 v[46:49], v[152:155], v[176:179], v[46:49]
	v_mfma_f32_16x16x32_bf16 v[38:41], v[160:163], v[176:179], v[38:41]
	v_mfma_f32_16x16x32_bf16 v[30:33], v[152:155], v[184:187], v[30:33]
	v_mfma_f32_16x16x32_bf16 v[22:25], v[160:163], v[184:187], v[22:25]
	v_mfma_f32_16x16x32_bf16 v[14:17], v[152:155], v[192:195], v[14:17]
	v_mfma_f32_16x16x32_bf16 v[6:9], v[160:163], v[192:195], v[6:9]
	v_mfma_f32_16x16x32_bf16 v[62:65], v[156:159], v[172:175], v[62:65]
	v_mfma_f32_16x16x32_bf16 v[54:57], v[164:167], v[172:175], v[54:57]
	v_mfma_f32_16x16x32_bf16 v[46:49], v[156:159], v[180:183], v[46:49]
	v_mfma_f32_16x16x32_bf16 v[38:41], v[164:167], v[180:183], v[38:41]
	v_mfma_f32_16x16x32_bf16 v[30:33], v[156:159], v[188:191], v[30:33]
	v_mfma_f32_16x16x32_bf16 v[22:25], v[164:167], v[188:191], v[22:25]
	v_mfma_f32_16x16x32_bf16 v[14:17], v[156:159], v[196:199], v[14:17]
	v_mfma_f32_16x16x32_bf16 v[6:9], v[164:167], v[196:199], v[6:9]
	s_barrier
	v_add_u32_e32 v130, 0x18000, v133
	ds_read_b128 v[136:139], v130
	ds_read_b128 v[140:143], v130 offset:1024
	ds_read_b128 v[144:147], v130 offset:2048
	ds_read_b128 v[148:151], v130 offset:3072
	v_add_u32_e32 v130, 0x1c000, v133
	ds_read_b128 v[152:155], v130
	ds_read_b128 v[156:159], v130 offset:1024
	ds_read_b128 v[160:163], v130 offset:2048
	ds_read_b128 v[164:167], v130 offset:3072
	ds_read_b128 v[168:171], v134 offset:32768
	ds_read_b128 v[172:175], v134 offset:33792
	ds_read_b128 v[176:179], v134 offset:34816
	ds_read_b128 v[180:183], v134 offset:35840
	ds_read_b128 v[184:187], v134 offset:36864
	ds_read_b128 v[188:191], v134 offset:37888
	ds_read_b128 v[192:195], v134 offset:38912
	ds_read_b128 v[196:199], v134 offset:39936
	s_add_u32 s74, s6, 0x40000
	s_addc_u32 s75, s7, 0
	s_add_i32 m0, s26, 0x2000
	s_nop 0
	global_load_lds_dwordx4 v0, s[74:75]
	s_add_u32 s74, s6, 0x60000
	s_addc_u32 s75, s7, 0
	s_add_i32 m0, s26, 0x3000
	s_nop 0
	global_load_lds_dwordx4 v0, s[74:75]
	s_add_u32 s74, s6, 0x80000
	s_addc_u32 s75, s7, 0
	s_add_i32 m0, s26, 0x4000
	s_nop 0
	global_load_lds_dwordx4 v0, s[74:75]
	s_add_u32 s74, s6, 0xa0000
	s_addc_u32 s75, s7, 0
	s_add_i32 m0, s26, 0x5000
	s_nop 0
	global_load_lds_dwordx4 v0, s[74:75]
	s_waitcnt vmcnt(8)
	s_waitcnt lgkmcnt(0)
	s_barrier
	v_mfma_f32_16x16x32_bf16 v[122:125], v[136:139], v[168:171], v[122:125]
	v_mfma_f32_16x16x32_bf16 v[114:117], v[144:147], v[168:171], v[114:117]
	v_mfma_f32_16x16x32_bf16 v[106:109], v[136:139], v[176:179], v[106:109]
	v_mfma_f32_16x16x32_bf16 v[98:101], v[144:147], v[176:179], v[98:101]
	v_mfma_f32_16x16x32_bf16 v[90:93], v[136:139], v[184:187], v[90:93]
	v_mfma_f32_16x16x32_bf16 v[82:85], v[144:147], v[184:187], v[82:85]
	v_mfma_f32_16x16x32_bf16 v[74:77], v[136:139], v[192:195], v[74:77]
	v_mfma_f32_16x16x32_bf16 v[66:69], v[144:147], v[192:195], v[66:69]
	v_mfma_f32_16x16x32_bf16 v[122:125], v[140:143], v[172:175], v[122:125]
	v_mfma_f32_16x16x32_bf16 v[114:117], v[148:151], v[172:175], v[114:117]
	v_mfma_f32_16x16x32_bf16 v[106:109], v[140:143], v[180:183], v[106:109]
	v_mfma_f32_16x16x32_bf16 v[98:101], v[148:151], v[180:183], v[98:101]
	v_mfma_f32_16x16x32_bf16 v[90:93], v[140:143], v[188:191], v[90:93]
	v_mfma_f32_16x16x32_bf16 v[82:85], v[148:151], v[188:191], v[82:85]
	v_mfma_f32_16x16x32_bf16 v[74:77], v[140:143], v[196:199], v[74:77]
	v_mfma_f32_16x16x32_bf16 v[66:69], v[148:151], v[196:199], v[66:69]
	v_mfma_f32_16x16x32_bf16 v[126:129], v[152:155], v[168:171], v[126:129]
	v_mfma_f32_16x16x32_bf16 v[118:121], v[160:163], v[168:171], v[118:121]
	v_mfma_f32_16x16x32_bf16 v[110:113], v[152:155], v[176:179], v[110:113]
	v_mfma_f32_16x16x32_bf16 v[102:105], v[160:163], v[176:179], v[102:105]
	v_mfma_f32_16x16x32_bf16 v[94:97], v[152:155], v[184:187], v[94:97]
	v_mfma_f32_16x16x32_bf16 v[86:89], v[160:163], v[184:187], v[86:89]
	v_mfma_f32_16x16x32_bf16 v[78:81], v[152:155], v[192:195], v[78:81]
	v_mfma_f32_16x16x32_bf16 v[70:73], v[160:163], v[192:195], v[70:73]
	v_mfma_f32_16x16x32_bf16 v[126:129], v[156:159], v[172:175], v[126:129]
	v_mfma_f32_16x16x32_bf16 v[118:121], v[164:167], v[172:175], v[118:121]
	v_mfma_f32_16x16x32_bf16 v[110:113], v[156:159], v[180:183], v[110:113]
	v_mfma_f32_16x16x32_bf16 v[102:105], v[164:167], v[180:183], v[102:105]
	v_mfma_f32_16x16x32_bf16 v[94:97], v[156:159], v[188:191], v[94:97]
	v_mfma_f32_16x16x32_bf16 v[86:89], v[164:167], v[188:191], v[86:89]
	v_mfma_f32_16x16x32_bf16 v[78:81], v[156:159], v[196:199], v[78:81]
	v_mfma_f32_16x16x32_bf16 v[70:73], v[164:167], v[196:199], v[70:73]
	s_barrier
	ds_read_b128 v[168:171], v134 offset:49152
	ds_read_b128 v[172:175], v134 offset:50176
	ds_read_b128 v[176:179], v134 offset:51200
	ds_read_b128 v[180:183], v134 offset:52224
	ds_read_b128 v[184:187], v134 offset:53248
	ds_read_b128 v[188:191], v134 offset:54272
	ds_read_b128 v[192:195], v134 offset:55296
	ds_read_b128 v[196:199], v134 offset:56320
	s_add_u32 s74, s22, 0x80
	s_addc_u32 s75, s23, 0
	s_add_i32 m0, s26, 0x18000
	s_nop 0
	global_load_lds_dwordx4 v132, s[74:75]
	s_add_u32 s74, s22, 0x20080
	s_addc_u32 s75, s23, 0
	s_add_i32 m0, s26, 0x19000
	s_nop 0
	global_load_lds_dwordx4 v132, s[74:75]
	s_add_u32 s74, s22, 0x40080
	s_addc_u32 s75, s23, 0
	s_add_i32 m0, s26, 0x1a000
	s_nop 0
	global_load_lds_dwordx4 v132, s[74:75]
	s_add_u32 s74, s22, 0x60080
	s_addc_u32 s75, s23, 0
	s_add_i32 m0, s26, 0x1b000
	s_nop 0
	global_load_lds_dwordx4 v132, s[74:75]
	s_waitcnt vmcnt(8)
	s_waitcnt lgkmcnt(0)
	s_barrier
	v_mfma_f32_16x16x32_bf16 v[58:61], v[136:139], v[168:171], v[58:61]
	v_mfma_f32_16x16x32_bf16 v[50:53], v[144:147], v[168:171], v[50:53]
	v_mfma_f32_16x16x32_bf16 v[42:45], v[136:139], v[176:179], v[42:45]
	v_mfma_f32_16x16x32_bf16 v[34:37], v[144:147], v[176:179], v[34:37]
	v_mfma_f32_16x16x32_bf16 v[26:29], v[136:139], v[184:187], v[26:29]
	v_mfma_f32_16x16x32_bf16 v[18:21], v[144:147], v[184:187], v[18:21]
	v_mfma_f32_16x16x32_bf16 v[10:13], v[136:139], v[192:195], v[10:13]
	v_mfma_f32_16x16x32_bf16 v[2:5], v[144:147], v[192:195], v[2:5]
	v_mfma_f32_16x16x32_bf16 v[58:61], v[140:143], v[172:175], v[58:61]
	v_mfma_f32_16x16x32_bf16 v[50:53], v[148:151], v[172:175], v[50:53]
	v_mfma_f32_16x16x32_bf16 v[42:45], v[140:143], v[180:183], v[42:45]
	v_mfma_f32_16x16x32_bf16 v[34:37], v[148:151], v[180:183], v[34:37]
	v_mfma_f32_16x16x32_bf16 v[26:29], v[140:143], v[188:191], v[26:29]
	v_mfma_f32_16x16x32_bf16 v[18:21], v[148:151], v[188:191], v[18:21]
	v_mfma_f32_16x16x32_bf16 v[10:13], v[140:143], v[196:199], v[10:13]
	v_mfma_f32_16x16x32_bf16 v[2:5], v[148:151], v[196:199], v[2:5]
	v_mfma_f32_16x16x32_bf16 v[62:65], v[152:155], v[168:171], v[62:65]
	v_mfma_f32_16x16x32_bf16 v[54:57], v[160:163], v[168:171], v[54:57]
	v_mfma_f32_16x16x32_bf16 v[46:49], v[152:155], v[176:179], v[46:49]
	v_mfma_f32_16x16x32_bf16 v[38:41], v[160:163], v[176:179], v[38:41]
	v_mfma_f32_16x16x32_bf16 v[30:33], v[152:155], v[184:187], v[30:33]
	v_mfma_f32_16x16x32_bf16 v[22:25], v[160:163], v[184:187], v[22:25]
	v_mfma_f32_16x16x32_bf16 v[14:17], v[152:155], v[192:195], v[14:17]
	v_mfma_f32_16x16x32_bf16 v[6:9], v[160:163], v[192:195], v[6:9]
	v_mfma_f32_16x16x32_bf16 v[62:65], v[156:159], v[172:175], v[62:65]
	v_mfma_f32_16x16x32_bf16 v[54:57], v[164:167], v[172:175], v[54:57]
	v_mfma_f32_16x16x32_bf16 v[46:49], v[156:159], v[180:183], v[46:49]
	v_mfma_f32_16x16x32_bf16 v[38:41], v[164:167], v[180:183], v[38:41]
	v_mfma_f32_16x16x32_bf16 v[30:33], v[156:159], v[188:191], v[30:33]
	v_mfma_f32_16x16x32_bf16 v[22:25], v[164:167], v[188:191], v[22:25]
	v_mfma_f32_16x16x32_bf16 v[14:17], v[156:159], v[196:199], v[14:17]
	v_mfma_f32_16x16x32_bf16 v[6:9], v[164:167], v[196:199], v[6:9]
	s_barrier
	s_add_i32 s70, s70, 2
	s_add_u32 s62, s62, 0x100
	s_addc_u32 s64, s64, 0
	s_add_u32 s66, s66, 0x100
	s_addc_u32 s68, s68, 0
	s_cmp_gt_u32 s70, 29
	s_cbranch_scc0 TB_L40000_Aloop
	s_branch TB_L40000_exit
TB_L40000_Bpeel:
	s_cmp_eq_u32 s70, 28
	s_cselect_b32 s6, s58, s62
	s_cselect_b32 s7, s15, s64
	s_cselect_b32 s22, s60, s66
	s_cselect_b32 s23, s13, s68
	v_add_u32_e32 v130, 0x10000, v133
	ds_read_b128 v[136:139], v130
	ds_read_b128 v[140:143], v130 offset:1024
	ds_read_b128 v[144:147], v130 offset:2048
	ds_read_b128 v[148:151], v130 offset:3072
	v_add_u32_e32 v130, 0x14000, v133
	ds_read_b128 v[152:155], v130
	ds_read_b128 v[156:159], v130 offset:1024
	ds_read_b128 v[160:163], v130 offset:2048
	ds_read_b128 v[164:167], v130 offset:3072
	ds_read_b128 v[168:171], v134
	ds_read_b128 v[172:175], v134 offset:1024
	ds_read_b128 v[176:179], v134 offset:2048
	ds_read_b128 v[180:183], v134 offset:3072
	ds_read_b128 v[184:187], v134 offset:4096
	ds_read_b128 v[188:191], v134 offset:5120
	ds_read_b128 v[192:195], v134 offset:6144
	ds_read_b128 v[196:199], v134 offset:7168
	s_add_u32 s74, s6, 0xfffe0000
	s_addc_u32 s75, s7, -1
	s_add_i32 m0, s26, 0xfffff000
	s_nop 0
	global_load_lds_dwordx4 v0, s[74:75]
	s_mov_b32 s74, s6
	s_mov_b32 s75, s7
	s_mov_b32 m0, s26
	s_nop 0
	global_load_lds_dwordx4 v0, s[74:75]
	s_add_u32 s74, s62, 0x9ff80
	s_addc_u32 s75, s64, 0
	s_add_i32 m0, s26, 0xd000
	s_nop 0
	global_load_lds_dwordx4 v0, s[74:75]
	s_add_u32 s74, s62, 0xbff80
	s_addc_u32 s75, s64, 0
	s_add_i32 m0, s26, 0xe000
	s_nop 0
	global_load_lds_dwordx4 v0, s[74:75]
	s_waitcnt vmcnt(8)
	s_waitcnt lgkmcnt(0)
	s_barrier
	v_mfma_f32_16x16x32_bf16 v[122:125], v[136:139], v[168:171], 0
	v_mfma_f32_16x16x32_bf16 v[114:117], v[144:147], v[168:171], 0
	v_mfma_f32_16x16x32_bf16 v[106:109], v[136:139], v[176:179], 0
	v_mfma_f32_16x16x32_bf16 v[98:101], v[144:147], v[176:179], 0
	v_mfma_f32_16x16x32_bf16 v[90:93], v[136:139], v[184:187], 0
	v_mfma_f32_16x16x32_bf16 v[82:85], v[144:147], v[184:187], 0
	v_mfma_f32_16x16x32_bf16 v[74:77], v[136:139], v[192:195], 0
	v_mfma_f32_16x16x32_bf16 v[66:69], v[144:147], v[192:195], 0
	v_mfma_f32_16x16x32_bf16 v[122:125], v[140:143], v[172:175], v[122:125]
	v_mfma_f32_16x16x32_bf16 v[114:117], v[148:151], v[172:175], v[114:117]
	v_mfma_f32_16x16x32_bf16 v[106:109], v[140:143], v[180:183], v[106:109]
	v_mfma_f32_16x16x32_bf16 v[98:101], v[148:151], v[180:183], v[98:101]
	v_mfma_f32_16x16x32_bf16 v[90:93], v[140:143], v[188:191], v[90:93]
	v_mfma_f32_16x16x32_bf16 v[82:85], v[148:151], v[188:191], v[82:85]
	v_mfma_f32_16x16x32_bf16 v[74:77], v[140:143], v[196:199], v[74:77]
	v_mfma_f32_16x16x32_bf16 v[66:69], v[148:151], v[196:199], v[66:69]
	v_mfma_f32_16x16x32_bf16 v[126:129], v[152:155], v[168:171], 0
	v_mfma_f32_16x16x32_bf16 v[118:121], v[160:163], v[168:171], 0
	v_mfma_f32_16x16x32_bf16 v[110:113], v[152:155], v[176:179], 0
	v_mfma_f32_16x16x32_bf16 v[102:105], v[160:163], v[176:179], 0
	v_mfma_f32_16x16x32_bf16 v[94:97], v[152:155], v[184:187], 0
	v_mfma_f32_16x16x32_bf16 v[86:89], v[160:163], v[184:187], 0
	v_mfma_f32_16x16x32_bf16 v[78:81], v[152:155], v[192:195], 0
	v_mfma_f32_16x16x32_bf16 v[70:73], v[160:163], v[192:195], 0
	v_mfma_f32_16x16x32_bf16 v[126:129], v[156:159], v[172:175], v[126:129]
	v_mfma_f32_16x16x32_bf16 v[118:121], v[164:167], v[172:175], v[118:121]
	v_mfma_f32_16x16x32_bf16 v[110:113], v[156:159], v[180:183], v[110:113]
	v_mfma_f32_16x16x32_bf16 v[102:105], v[164:167], v[180:183], v[102:105]
	v_mfma_f32_16x16x32_bf16 v[94:97], v[156:159], v[188:191], v[94:97]
	v_mfma_f32_16x16x32_bf16 v[86:89], v[164:167], v[188:191], v[86:89]
	v_mfma_f32_16x16x32_bf16 v[78:81], v[156:159], v[196:199], v[78:81]
	v_mfma_f32_16x16x32_bf16 v[70:73], v[164:167], v[196:199], v[70:73]
	s_barrier
	ds_read_b128 v[168:171], v134 offset:16384
	ds_read_b128 v[172:175], v134 offset:17408
	ds_read_b128 v[176:179], v134 offset:18432
	ds_read_b128 v[180:183], v134 offset:19456
	ds_read_b128 v[184:187], v134 offset:20480
	ds_read_b128 v[188:191], v134 offset:21504
	ds_read_b128 v[192:195], v134 offset:22528
	ds_read_b128 v[196:199], v134 offset:23552
	s_add_u32 s74, s22, 0x60000
	s_addc_u32 s75, s23, 0
	s_add_i32 m0, s26, 0x13000
	s_nop 0
	global_load_lds_dwordx4 v132, s[74:75]
	s_add_u32 s74, s22, 0x80000
	s_addc_u32 s75, s23, 0
	s_add_i32 m0, s26, 0x14000
	s_nop 0
	global_load_lds_dwordx4 v132, s[74:75]
	s_add_u32 s74, s22, 0xa0000
	s_addc_u32 s75, s23, 0
	s_add_i32 m0, s26, 0x15000
	s_nop 0
	global_load_lds_dwordx4 v132, s[74:75]
	s_add_u32 s74, s22, 0xc0000
	s_addc_u32 s75, s23, 0
	s_add_i32 m0, s26, 0x16000
	s_nop 0
	global_load_lds_dwordx4 v132, s[74:75]
	s_waitcnt vmcnt(8)
	s_waitcnt lgkmcnt(0)
	s_barrier
	v_mfma_f32_16x16x32_bf16 v[58:61], v[136:139], v[168:171], 0
	v_mfma_f32_16x16x32_bf16 v[50:53], v[144:147], v[168:171], 0
	v_mfma_f32_16x16x32_bf16 v[42:45], v[136:139], v[176:179], 0
	v_mfma_f32_16x16x32_bf16 v[34:37], v[144:147], v[176:179], 0
	v_mfma_f32_16x16x32_bf16 v[26:29], v[136:139], v[184:187], 0
	v_mfma_f32_16x16x32_bf16 v[18:21], v[144:147], v[184:187], 0
	v_mfma_f32_16x16x32_bf16 v[10:13], v[136:139], v[192:195], 0
	v_mfma_f32_16x16x32_bf16 v[2:5], v[144:147], v[192:195], 0
	v_mfma_f32_16x16x32_bf16 v[58:61], v[140:143], v[172:175], v[58:61]
	v_mfma_f32_16x16x32_bf16 v[50:53], v[148:151], v[172:175], v[50:53]
	v_mfma_f32_16x16x32_bf16 v[42:45], v[140:143], v[180:183], v[42:45]
	v_mfma_f32_16x16x32_bf16 v[34:37], v[148:151], v[180:183], v[34:37]
	v_mfma_f32_16x16x32_bf16 v[26:29], v[140:143], v[188:191], v[26:29]
	v_mfma_f32_16x16x32_bf16 v[18:21], v[148:151], v[188:191], v[18:21]
	v_mfma_f32_16x16x32_bf16 v[10:13], v[140:143], v[196:199], v[10:13]
	v_mfma_f32_16x16x32_bf16 v[2:5], v[148:151], v[196:199], v[2:5]
	v_mfma_f32_16x16x32_bf16 v[62:65], v[152:155], v[168:171], 0
	v_mfma_f32_16x16x32_bf16 v[54:57], v[160:163], v[168:171], 0
	v_mfma_f32_16x16x32_bf16 v[46:49], v[152:155], v[176:179], 0
	v_mfma_f32_16x16x32_bf16 v[38:41], v[160:163], v[176:179], 0
	v_mfma_f32_16x16x32_bf16 v[30:33], v[152:155], v[184:187], 0
	v_mfma_f32_16x16x32_bf16 v[22:25], v[160:163], v[184:187], 0
	v_mfma_f32_16x16x32_bf16 v[14:17], v[152:155], v[192:195], 0
	v_mfma_f32_16x16x32_bf16 v[6:9], v[160:163], v[192:195], 0
	v_mfma_f32_16x16x32_bf16 v[62:65], v[156:159], v[172:175], v[62:65]
	v_mfma_f32_16x16x32_bf16 v[54:57], v[164:167], v[172:175], v[54:57]
	v_mfma_f32_16x16x32_bf16 v[46:49], v[156:159], v[180:183], v[46:49]
	v_mfma_f32_16x16x32_bf16 v[38:41], v[164:167], v[180:183], v[38:41]
	v_mfma_f32_16x16x32_bf16 v[30:33], v[156:159], v[188:191], v[30:33]
	v_mfma_f32_16x16x32_bf16 v[22:25], v[164:167], v[188:191], v[22:25]
	v_mfma_f32_16x16x32_bf16 v[14:17], v[156:159], v[196:199], v[14:17]
	v_mfma_f32_16x16x32_bf16 v[6:9], v[164:167], v[196:199], v[6:9]
	s_barrier
	v_add_u32_e32 v130, 0x18000, v133
	ds_read_b128 v[136:139], v130
	ds_read_b128 v[140:143], v130 offset:1024
	ds_read_b128 v[144:147], v130 offset:2048
	ds_read_b128 v[148:151], v130 offset:3072
	v_add_u32_e32 v130, 0x1c000, v133
	ds_read_b128 v[152:155], v130
	ds_read_b128 v[156:159], v130 offset:1024
	ds_read_b128 v[160:163], v130 offset:2048
	ds_read_b128 v[164:167], v130 offset:3072
	ds_read_b128 v[168:171], v134 offset:32768
	ds_read_b128 v[172:175], v134 offset:33792
	ds_read_b128 v[176:179], v134 offset:34816
	ds_read_b128 v[180:183], v134 offset:35840
	ds_read_b128 v[184:187], v134 offset:36864
	ds_read_b128 v[188:191], v134 offset:37888
	ds_read_b128 v[192:195], v134 offset:38912
	ds_read_b128 v[196:199], v134 offset:39936
	s_add_u32 s74, s6, 0xfffe0080
	s_addc_u32 s75, s7, -1
	s_add_i32 m0, s26, 0x7000
	s_nop 0
	global_load_lds_dwordx4 v0, s[74:75]
	s_add_u32 s74, s6, 0x80
	s_addc_u32 s75, s7, 0
	s_add_i32 m0, s26, 0x8000
	s_nop 0
	global_load_lds_dwordx4 v0, s[74:75]
	s_add_u32 s74, s6, 0xa0000
	s_addc_u32 s75, s7, 0
	s_add_i32 m0, s26, 0x5000
	s_nop 0
	global_load_lds_dwordx4 v0, s[74:75]
	s_add_u32 s74, s6, 0xc0000
	s_addc_u32 s75, s7, 0
	s_add_i32 m0, s26, 0x6000
	s_nop 0
	global_load_lds_dwordx4 v0, s[74:75]
	s_waitcnt vmcnt(8)
	s_waitcnt lgkmcnt(0)
	s_barrier
	v_mfma_f32_16x16x32_bf16 v[122:125], v[136:139], v[168:171], v[122:125]
	v_mfma_f32_16x16x32_bf16 v[114:117], v[144:147], v[168:171], v[114:117]
	v_mfma_f32_16x16x32_bf16 v[106:109], v[136:139], v[176:179], v[106:109]
	v_mfma_f32_16x16x32_bf16 v[98:101], v[144:147], v[176:179], v[98:101]
	v_mfma_f32_16x16x32_bf16 v[90:93], v[136:139], v[184:187], v[90:93]
	v_mfma_f32_16x16x32_bf16 v[82:85], v[144:147], v[184:187], v[82:85]
	v_mfma_f32_16x16x32_bf16 v[74:77], v[136:139], v[192:195], v[74:77]
	v_mfma_f32_16x16x32_bf16 v[66:69], v[144:147], v[192:195], v[66:69]
	v_mfma_f32_16x16x32_bf16 v[122:125], v[140:143], v[172:175], v[122:125]
	v_mfma_f32_16x16x32_bf16 v[114:117], v[148:151], v[172:175], v[114:117]
	v_mfma_f32_16x16x32_bf16 v[106:109], v[140:143], v[180:183], v[106:109]
	v_mfma_f32_16x16x32_bf16 v[98:101], v[148:151], v[180:183], v[98:101]
	v_mfma_f32_16x16x32_bf16 v[90:93], v[140:143], v[188:191], v[90:93]
	v_mfma_f32_16x16x32_bf16 v[82:85], v[148:151], v[188:191], v[82:85]
	v_mfma_f32_16x16x32_bf16 v[74:77], v[140:143], v[196:199], v[74:77]
	v_mfma_f32_16x16x32_bf16 v[66:69], v[148:151], v[196:199], v[66:69]
	v_mfma_f32_16x16x32_bf16 v[126:129], v[152:155], v[168:171], v[126:129]
	v_mfma_f32_16x16x32_bf16 v[118:121], v[160:163], v[168:171], v[118:121]
	v_mfma_f32_16x16x32_bf16 v[110:113], v[152:155], v[176:179], v[110:113]
	v_mfma_f32_16x16x32_bf16 v[102:105], v[160:163], v[176:179], v[102:105]
	v_mfma_f32_16x16x32_bf16 v[94:97], v[152:155], v[184:187], v[94:97]
	v_mfma_f32_16x16x32_bf16 v[86:89], v[160:163], v[184:187], v[86:89]
	v_mfma_f32_16x16x32_bf16 v[78:81], v[152:155], v[192:195], v[78:81]
	v_mfma_f32_16x16x32_bf16 v[70:73], v[160:163], v[192:195], v[70:73]
	v_mfma_f32_16x16x32_bf16 v[126:129], v[156:159], v[172:175], v[126:129]
	v_mfma_f32_16x16x32_bf16 v[118:121], v[164:167], v[172:175], v[118:121]
	v_mfma_f32_16x16x32_bf16 v[110:113], v[156:159], v[180:183], v[110:113]
	v_mfma_f32_16x16x32_bf16 v[102:105], v[164:167], v[180:183], v[102:105]
	v_mfma_f32_16x16x32_bf16 v[94:97], v[156:159], v[188:191], v[94:97]
	v_mfma_f32_16x16x32_bf16 v[86:89], v[164:167], v[188:191], v[86:89]
	v_mfma_f32_16x16x32_bf16 v[78:81], v[156:159], v[196:199], v[78:81]
	v_mfma_f32_16x16x32_bf16 v[70:73], v[164:167], v[196:199], v[70:73]
	s_barrier
	ds_read_b128 v[168:171], v134 offset:49152
	ds_read_b128 v[172:175], v134 offset:50176
	ds_read_b128 v[176:179], v134 offset:51200
	ds_read_b128 v[180:183], v134 offset:52224
	ds_read_b128 v[184:187], v134 offset:53248
	ds_read_b128 v[188:191], v134 offset:54272
	ds_read_b128 v[192:195], v134 offset:55296
	ds_read_b128 v[196:199], v134 offset:56320
	s_add_u32 s74, s22, 0x60080
	s_addc_u32 s75, s23, 0
	s_add_i32 m0, s26, 0x1b000
	s_nop 0
	global_load_lds_dwordx4 v132, s[74:75]
	s_add_u32 s74, s22, 0x80080
	s_addc_u32 s75, s23, 0
	s_add_i32 m0, s26, 0x1c000
	s_nop 0
	global_load_lds_dwordx4 v132, s[74:75]
	s_add_u32 s74, s22, 0xa0080
	s_addc_u32 s75, s23, 0
	s_add_i32 m0, s26, 0x1d000
	s_nop 0
	global_load_lds_dwordx4 v132, s[74:75]
	s_add_u32 s74, s22, 0xc0080
	s_addc_u32 s75, s23, 0
	s_add_i32 m0, s26, 0x1e000
	s_nop 0
	global_load_lds_dwordx4 v132, s[74:75]
	s_waitcnt vmcnt(8)
	s_waitcnt lgkmcnt(0)
	s_barrier
	v_mfma_f32_16x16x32_bf16 v[58:61], v[136:139], v[168:171], v[58:61]
	v_mfma_f32_16x16x32_bf16 v[50:53], v[144:147], v[168:171], v[50:53]
	v_mfma_f32_16x16x32_bf16 v[42:45], v[136:139], v[176:179], v[42:45]
	v_mfma_f32_16x16x32_bf16 v[34:37], v[144:147], v[176:179], v[34:37]
	v_mfma_f32_16x16x32_bf16 v[26:29], v[136:139], v[184:187], v[26:29]
	v_mfma_f32_16x16x32_bf16 v[18:21], v[144:147], v[184:187], v[18:21]
	v_mfma_f32_16x16x32_bf16 v[10:13], v[136:139], v[192:195], v[10:13]
	v_mfma_f32_16x16x32_bf16 v[2:5], v[144:147], v[192:195], v[2:5]
	v_mfma_f32_16x16x32_bf16 v[58:61], v[140:143], v[172:175], v[58:61]
	v_mfma_f32_16x16x32_bf16 v[50:53], v[148:151], v[172:175], v[50:53]
	v_mfma_f32_16x16x32_bf16 v[42:45], v[140:143], v[180:183], v[42:45]
	v_mfma_f32_16x16x32_bf16 v[34:37], v[148:151], v[180:183], v[34:37]
	v_mfma_f32_16x16x32_bf16 v[26:29], v[140:143], v[188:191], v[26:29]
	v_mfma_f32_16x16x32_bf16 v[18:21], v[148:151], v[188:191], v[18:21]
	v_mfma_f32_16x16x32_bf16 v[10:13], v[140:143], v[196:199], v[10:13]
	v_mfma_f32_16x16x32_bf16 v[2:5], v[148:151], v[196:199], v[2:5]
	v_mfma_f32_16x16x32_bf16 v[62:65], v[152:155], v[168:171], v[62:65]
	v_mfma_f32_16x16x32_bf16 v[54:57], v[160:163], v[168:171], v[54:57]
	v_mfma_f32_16x16x32_bf16 v[46:49], v[152:155], v[176:179], v[46:49]
	v_mfma_f32_16x16x32_bf16 v[38:41], v[160:163], v[176:179], v[38:41]
	v_mfma_f32_16x16x32_bf16 v[30:33], v[152:155], v[184:187], v[30:33]
	v_mfma_f32_16x16x32_bf16 v[22:25], v[160:163], v[184:187], v[22:25]
	v_mfma_f32_16x16x32_bf16 v[14:17], v[152:155], v[192:195], v[14:17]
	v_mfma_f32_16x16x32_bf16 v[6:9], v[160:163], v[192:195], v[6:9]
	v_mfma_f32_16x16x32_bf16 v[62:65], v[156:159], v[172:175], v[62:65]
	v_mfma_f32_16x16x32_bf16 v[54:57], v[164:167], v[172:175], v[54:57]
	v_mfma_f32_16x16x32_bf16 v[46:49], v[156:159], v[180:183], v[46:49]
	v_mfma_f32_16x16x32_bf16 v[38:41], v[164:167], v[180:183], v[38:41]
	v_mfma_f32_16x16x32_bf16 v[30:33], v[156:159], v[188:191], v[30:33]
	v_mfma_f32_16x16x32_bf16 v[22:25], v[164:167], v[188:191], v[22:25]
	v_mfma_f32_16x16x32_bf16 v[14:17], v[156:159], v[196:199], v[14:17]
	v_mfma_f32_16x16x32_bf16 v[6:9], v[164:167], v[196:199], v[6:9]
	s_barrier
	s_add_i32 s70, s70, 2
	s_add_u32 s62, s62, 0x100
	s_addc_u32 s64, s64, 0
	s_add_u32 s66, s66, 0x100
	s_addc_u32 s68, s68, 0
TB_L40000_Bloop:
	s_cmp_eq_u32 s70, 28
	s_cselect_b32 s6, s58, s62
	s_cselect_b32 s7, s15, s64
	s_cselect_b32 s22, s60, s66
	s_cselect_b32 s23, s13, s68
	v_add_u32_e32 v130, 0x10000, v133
	ds_read_b128 v[136:139], v130
	ds_read_b128 v[140:143], v130 offset:1024
	ds_read_b128 v[144:147], v130 offset:2048
	ds_read_b128 v[148:151], v130 offset:3072
	v_add_u32_e32 v130, 0x14000, v133
	ds_read_b128 v[152:155], v130
	ds_read_b128 v[156:159], v130 offset:1024
	ds_read_b128 v[160:163], v130 offset:2048
	ds_read_b128 v[164:167], v130 offset:3072
	ds_read_b128 v[168:171], v134
	ds_read_b128 v[172:175], v134 offset:1024
	ds_read_b128 v[176:179], v134 offset:2048
	ds_read_b128 v[180:183], v134 offset:3072
	ds_read_b128 v[184:187], v134 offset:4096
	ds_read_b128 v[188:191], v134 offset:5120
	ds_read_b128 v[192:195], v134 offset:6144
	ds_read_b128 v[196:199], v134 offset:7168
	s_add_u32 s74, s6, 0xfffe0000
	s_addc_u32 s75, s7, -1
	s_add_i32 m0, s26, 0xfffff000
	s_nop 0
	global_load_lds_dwordx4 v0, s[74:75]
	s_mov_b32 s74, s6
	s_mov_b32 s75, s7
	s_mov_b32 m0, s26
	s_nop 0
	global_load_lds_dwordx4 v0, s[74:75]
	s_add_u32 s74, s62, 0x9ff80
	s_addc_u32 s75, s64, 0
	s_add_i32 m0, s26, 0xd000
	s_nop 0
	global_load_lds_dwordx4 v0, s[74:75]
	s_add_u32 s74, s62, 0xbff80
	s_addc_u32 s75, s64, 0
	s_add_i32 m0, s26, 0xe000
	s_nop 0
	global_load_lds_dwordx4 v0, s[74:75]
	s_waitcnt vmcnt(8)
	s_waitcnt lgkmcnt(0)
	s_barrier
	v_mfma_f32_16x16x32_bf16 v[122:125], v[136:139], v[168:171], v[122:125]
	v_mfma_f32_16x16x32_bf16 v[114:117], v[144:147], v[168:171], v[114:117]
	v_mfma_f32_16x16x32_bf16 v[106:109], v[136:139], v[176:179], v[106:109]
	v_mfma_f32_16x16x32_bf16 v[98:101], v[144:147], v[176:179], v[98:101]
	v_mfma_f32_16x16x32_bf16 v[90:93], v[136:139], v[184:187], v[90:93]
	v_mfma_f32_16x16x32_bf16 v[82:85], v[144:147], v[184:187], v[82:85]
	v_mfma_f32_16x16x32_bf16 v[74:77], v[136:139], v[192:195], v[74:77]
	v_mfma_f32_16x16x32_bf16 v[66:69], v[144:147], v[192:195], v[66:69]
	v_mfma_f32_16x16x32_bf16 v[122:125], v[140:143], v[172:175], v[122:125]
	v_mfma_f32_16x16x32_bf16 v[114:117], v[148:151], v[172:175], v[114:117]
	v_mfma_f32_16x16x32_bf16 v[106:109], v[140:143], v[180:183], v[106:109]
	v_mfma_f32_16x16x32_bf16 v[98:101], v[148:151], v[180:183], v[98:101]
	v_mfma_f32_16x16x32_bf16 v[90:93], v[140:143], v[188:191], v[90:93]
	v_mfma_f32_16x16x32_bf16 v[82:85], v[148:151], v[188:191], v[82:85]
	v_mfma_f32_16x16x32_bf16 v[74:77], v[140:143], v[196:199], v[74:77]
	v_mfma_f32_16x16x32_bf16 v[66:69], v[148:151], v[196:199], v[66:69]
	v_mfma_f32_16x16x32_bf16 v[126:129], v[152:155], v[168:171], v[126:129]
	v_mfma_f32_16x16x32_bf16 v[118:121], v[160:163], v[168:171], v[118:121]
	v_mfma_f32_16x16x32_bf16 v[110:113], v[152:155], v[176:179], v[110:113]
	v_mfma_f32_16x16x32_bf16 v[102:105], v[160:163], v[176:179], v[102:105]
	v_mfma_f32_16x16x32_bf16 v[94:97], v[152:155], v[184:187], v[94:97]
	v_mfma_f32_16x16x32_bf16 v[86:89], v[160:163], v[184:187], v[86:89]
	v_mfma_f32_16x16x32_bf16 v[78:81], v[152:155], v[192:195], v[78:81]
	v_mfma_f32_16x16x32_bf16 v[70:73], v[160:163], v[192:195], v[70:73]
	v_mfma_f32_16x16x32_bf16 v[126:129], v[156:159], v[172:175], v[126:129]
	v_mfma_f32_16x16x32_bf16 v[118:121], v[164:167], v[172:175], v[118:121]
	v_mfma_f32_16x16x32_bf16 v[110:113], v[156:159], v[180:183], v[110:113]
	v_mfma_f32_16x16x32_bf16 v[102:105], v[164:167], v[180:183], v[102:105]
	v_mfma_f32_16x16x32_bf16 v[94:97], v[156:159], v[188:191], v[94:97]
	v_mfma_f32_16x16x32_bf16 v[86:89], v[164:167], v[188:191], v[86:89]
	v_mfma_f32_16x16x32_bf16 v[78:81], v[156:159], v[196:199], v[78:81]
	v_mfma_f32_16x16x32_bf16 v[70:73], v[164:167], v[196:199], v[70:73]
	s_barrier
	ds_read_b128 v[168:171], v134 offset:16384
	ds_read_b128 v[172:175], v134 offset:17408
	ds_read_b128 v[176:179], v134 offset:18432
	ds_read_b128 v[180:183], v134 offset:19456
	ds_read_b128 v[184:187], v134 offset:20480
	ds_read_b128 v[188:191], v134 offset:21504
	ds_read_b128 v[192:195], v134 offset:22528
	ds_read_b128 v[196:199], v134 offset:23552
	s_add_u32 s74, s22, 0x60000
	s_addc_u32 s75, s23, 0
	s_add_i32 m0, s26, 0x13000
	s_nop 0
	global_load_lds_dwordx4 v132, s[74:75]
	s_add_u32 s74, s22, 0x80000
	s_addc_u32 s75, s23, 0
	s_add_i32 m0, s26, 0x14000
	s_nop 0
	global_load_lds_dwordx4 v132, s[74:75]
	s_add_u32 s74, s22, 0xa0000
	s_addc_u32 s75, s23, 0
	s_add_i32 m0, s26, 0x15000
	s_nop 0
	global_load_lds_dwordx4 v132, s[74:75]
	s_add_u32 s74, s22, 0xc0000
	s_addc_u32 s75, s23, 0
	s_add_i32 m0, s26, 0x16000
	s_nop 0
	global_load_lds_dwordx4 v132, s[74:75]
	s_waitcnt vmcnt(8)
	s_waitcnt lgkmcnt(0)
	s_barrier
	v_mfma_f32_16x16x32_bf16 v[58:61], v[136:139], v[168:171], v[58:61]
	v_mfma_f32_16x16x32_bf16 v[50:53], v[144:147], v[168:171], v[50:53]
	v_mfma_f32_16x16x32_bf16 v[42:45], v[136:139], v[176:179], v[42:45]
	v_mfma_f32_16x16x32_bf16 v[34:37], v[144:147], v[176:179], v[34:37]
	v_mfma_f32_16x16x32_bf16 v[26:29], v[136:139], v[184:187], v[26:29]
	v_mfma_f32_16x16x32_bf16 v[18:21], v[144:147], v[184:187], v[18:21]
	v_mfma_f32_16x16x32_bf16 v[10:13], v[136:139], v[192:195], v[10:13]
	v_mfma_f32_16x16x32_bf16 v[2:5], v[144:147], v[192:195], v[2:5]
	v_mfma_f32_16x16x32_bf16 v[58:61], v[140:143], v[172:175], v[58:61]
	v_mfma_f32_16x16x32_bf16 v[50:53], v[148:151], v[172:175], v[50:53]
	v_mfma_f32_16x16x32_bf16 v[42:45], v[140:143], v[180:183], v[42:45]
	v_mfma_f32_16x16x32_bf16 v[34:37], v[148:151], v[180:183], v[34:37]
	v_mfma_f32_16x16x32_bf16 v[26:29], v[140:143], v[188:191], v[26:29]
	v_mfma_f32_16x16x32_bf16 v[18:21], v[148:151], v[188:191], v[18:21]
	v_mfma_f32_16x16x32_bf16 v[10:13], v[140:143], v[196:199], v[10:13]
	v_mfma_f32_16x16x32_bf16 v[2:5], v[148:151], v[196:199], v[2:5]
	v_mfma_f32_16x16x32_bf16 v[62:65], v[152:155], v[168:171], v[62:65]
	v_mfma_f32_16x16x32_bf16 v[54:57], v[160:163], v[168:171], v[54:57]
	v_mfma_f32_16x16x32_bf16 v[46:49], v[152:155], v[176:179], v[46:49]
	v_mfma_f32_16x16x32_bf16 v[38:41], v[160:163], v[176:179], v[38:41]
	v_mfma_f32_16x16x32_bf16 v[30:33], v[152:155], v[184:187], v[30:33]
	v_mfma_f32_16x16x32_bf16 v[22:25], v[160:163], v[184:187], v[22:25]
	v_mfma_f32_16x16x32_bf16 v[14:17], v[152:155], v[192:195], v[14:17]
	v_mfma_f32_16x16x32_bf16 v[6:9], v[160:163], v[192:195], v[6:9]
	v_mfma_f32_16x16x32_bf16 v[62:65], v[156:159], v[172:175], v[62:65]
	v_mfma_f32_16x16x32_bf16 v[54:57], v[164:167], v[172:175], v[54:57]
	v_mfma_f32_16x16x32_bf16 v[46:49], v[156:159], v[180:183], v[46:49]
	v_mfma_f32_16x16x32_bf16 v[38:41], v[164:167], v[180:183], v[38:41]
	v_mfma_f32_16x16x32_bf16 v[30:33], v[156:159], v[188:191], v[30:33]
	v_mfma_f32_16x16x32_bf16 v[22:25], v[164:167], v[188:191], v[22:25]
	v_mfma_f32_16x16x32_bf16 v[14:17], v[156:159], v[196:199], v[14:17]
	v_mfma_f32_16x16x32_bf16 v[6:9], v[164:167], v[196:199], v[6:9]
	s_barrier
	v_add_u32_e32 v130, 0x18000, v133
	ds_read_b128 v[136:139], v130
	ds_read_b128 v[140:143], v130 offset:1024
	ds_read_b128 v[144:147], v130 offset:2048
	ds_read_b128 v[148:151], v130 offset:3072
	v_add_u32_e32 v130, 0x1c000, v133
	ds_read_b128 v[152:155], v130
	ds_read_b128 v[156:159], v130 offset:1024
	ds_read_b128 v[160:163], v130 offset:2048
	ds_read_b128 v[164:167], v130 offset:3072
	ds_read_b128 v[168:171], v134 offset:32768
	ds_read_b128 v[172:175], v134 offset:33792
	ds_read_b128 v[176:179], v134 offset:34816
	ds_read_b128 v[180:183], v134 offset:35840
	ds_read_b128 v[184:187], v134 offset:36864
	ds_read_b128 v[188:191], v134 offset:37888
	ds_read_b128 v[192:195], v134 offset:38912
	ds_read_b128 v[196:199], v134 offset:39936
	s_add_u32 s74, s6, 0xfffe0080
	s_addc_u32 s75, s7, -1
	s_add_i32 m0, s26, 0x7000
	s_nop 0
	global_load_lds_dwordx4 v0, s[74:75]
	s_add_u32 s74, s6, 0x80
	s_addc_u32 s75, s7, 0
	s_add_i32 m0, s26, 0x8000
	s_nop 0
	global_load_lds_dwordx4 v0, s[74:75]
	s_add_u32 s74, s6, 0xa0000
	s_addc_u32 s75, s7, 0
	s_add_i32 m0, s26, 0x5000
	s_nop 0
	global_load_lds_dwordx4 v0, s[74:75]
	s_add_u32 s74, s6, 0xc0000
	s_addc_u32 s75, s7, 0
	s_add_i32 m0, s26, 0x6000
	s_nop 0
	global_load_lds_dwordx4 v0, s[74:75]
	s_waitcnt vmcnt(8)
	s_waitcnt lgkmcnt(0)
	s_barrier
	v_mfma_f32_16x16x32_bf16 v[122:125], v[136:139], v[168:171], v[122:125]
	v_mfma_f32_16x16x32_bf16 v[114:117], v[144:147], v[168:171], v[114:117]
	v_mfma_f32_16x16x32_bf16 v[106:109], v[136:139], v[176:179], v[106:109]
	v_mfma_f32_16x16x32_bf16 v[98:101], v[144:147], v[176:179], v[98:101]
	v_mfma_f32_16x16x32_bf16 v[90:93], v[136:139], v[184:187], v[90:93]
	v_mfma_f32_16x16x32_bf16 v[82:85], v[144:147], v[184:187], v[82:85]
	v_mfma_f32_16x16x32_bf16 v[74:77], v[136:139], v[192:195], v[74:77]
	v_mfma_f32_16x16x32_bf16 v[66:69], v[144:147], v[192:195], v[66:69]
	v_mfma_f32_16x16x32_bf16 v[122:125], v[140:143], v[172:175], v[122:125]
	v_mfma_f32_16x16x32_bf16 v[114:117], v[148:151], v[172:175], v[114:117]
	v_mfma_f32_16x16x32_bf16 v[106:109], v[140:143], v[180:183], v[106:109]
	v_mfma_f32_16x16x32_bf16 v[98:101], v[148:151], v[180:183], v[98:101]
	v_mfma_f32_16x16x32_bf16 v[90:93], v[140:143], v[188:191], v[90:93]
	v_mfma_f32_16x16x32_bf16 v[82:85], v[148:151], v[188:191], v[82:85]
	v_mfma_f32_16x16x32_bf16 v[74:77], v[140:143], v[196:199], v[74:77]
	v_mfma_f32_16x16x32_bf16 v[66:69], v[148:151], v[196:199], v[66:69]
	v_mfma_f32_16x16x32_bf16 v[126:129], v[152:155], v[168:171], v[126:129]
	v_mfma_f32_16x16x32_bf16 v[118:121], v[160:163], v[168:171], v[118:121]
	v_mfma_f32_16x16x32_bf16 v[110:113], v[152:155], v[176:179], v[110:113]
	v_mfma_f32_16x16x32_bf16 v[102:105], v[160:163], v[176:179], v[102:105]
	v_mfma_f32_16x16x32_bf16 v[94:97], v[152:155], v[184:187], v[94:97]
	v_mfma_f32_16x16x32_bf16 v[86:89], v[160:163], v[184:187], v[86:89]
	v_mfma_f32_16x16x32_bf16 v[78:81], v[152:155], v[192:195], v[78:81]
	v_mfma_f32_16x16x32_bf16 v[70:73], v[160:163], v[192:195], v[70:73]
	v_mfma_f32_16x16x32_bf16 v[126:129], v[156:159], v[172:175], v[126:129]
	v_mfma_f32_16x16x32_bf16 v[118:121], v[164:167], v[172:175], v[118:121]
	v_mfma_f32_16x16x32_bf16 v[110:113], v[156:159], v[180:183], v[110:113]
	v_mfma_f32_16x16x32_bf16 v[102:105], v[164:167], v[180:183], v[102:105]
	v_mfma_f32_16x16x32_bf16 v[94:97], v[156:159], v[188:191], v[94:97]
	v_mfma_f32_16x16x32_bf16 v[86:89], v[164:167], v[188:191], v[86:89]
	v_mfma_f32_16x16x32_bf16 v[78:81], v[156:159], v[196:199], v[78:81]
	v_mfma_f32_16x16x32_bf16 v[70:73], v[164:167], v[196:199], v[70:73]
	s_barrier
	ds_read_b128 v[168:171], v134 offset:49152
	ds_read_b128 v[172:175], v134 offset:50176
	ds_read_b128 v[176:179], v134 offset:51200
	ds_read_b128 v[180:183], v134 offset:52224
	ds_read_b128 v[184:187], v134 offset:53248
	ds_read_b128 v[188:191], v134 offset:54272
	ds_read_b128 v[192:195], v134 offset:55296
	ds_read_b128 v[196:199], v134 offset:56320
	s_add_u32 s74, s22, 0x60080
	s_addc_u32 s75, s23, 0
	s_add_i32 m0, s26, 0x1b000
	s_nop 0
	global_load_lds_dwordx4 v132, s[74:75]
	s_add_u32 s74, s22, 0x80080
	s_addc_u32 s75, s23, 0
	s_add_i32 m0, s26, 0x1c000
	s_nop 0
	global_load_lds_dwordx4 v132, s[74:75]
	s_add_u32 s74, s22, 0xa0080
	s_addc_u32 s75, s23, 0
	s_add_i32 m0, s26, 0x1d000
	s_nop 0
	global_load_lds_dwordx4 v132, s[74:75]
	s_add_u32 s74, s22, 0xc0080
	s_addc_u32 s75, s23, 0
	s_add_i32 m0, s26, 0x1e000
	s_nop 0
	global_load_lds_dwordx4 v132, s[74:75]
	s_waitcnt vmcnt(8)
	s_waitcnt lgkmcnt(0)
	s_barrier
	v_mfma_f32_16x16x32_bf16 v[58:61], v[136:139], v[168:171], v[58:61]
	v_mfma_f32_16x16x32_bf16 v[50:53], v[144:147], v[168:171], v[50:53]
	v_mfma_f32_16x16x32_bf16 v[42:45], v[136:139], v[176:179], v[42:45]
	v_mfma_f32_16x16x32_bf16 v[34:37], v[144:147], v[176:179], v[34:37]
	v_mfma_f32_16x16x32_bf16 v[26:29], v[136:139], v[184:187], v[26:29]
	v_mfma_f32_16x16x32_bf16 v[18:21], v[144:147], v[184:187], v[18:21]
	v_mfma_f32_16x16x32_bf16 v[10:13], v[136:139], v[192:195], v[10:13]
	v_mfma_f32_16x16x32_bf16 v[2:5], v[144:147], v[192:195], v[2:5]
	v_mfma_f32_16x16x32_bf16 v[58:61], v[140:143], v[172:175], v[58:61]
	v_mfma_f32_16x16x32_bf16 v[50:53], v[148:151], v[172:175], v[50:53]
	v_mfma_f32_16x16x32_bf16 v[42:45], v[140:143], v[180:183], v[42:45]
	v_mfma_f32_16x16x32_bf16 v[34:37], v[148:151], v[180:183], v[34:37]
	v_mfma_f32_16x16x32_bf16 v[26:29], v[140:143], v[188:191], v[26:29]
	v_mfma_f32_16x16x32_bf16 v[18:21], v[148:151], v[188:191], v[18:21]
	v_mfma_f32_16x16x32_bf16 v[10:13], v[140:143], v[196:199], v[10:13]
	v_mfma_f32_16x16x32_bf16 v[2:5], v[148:151], v[196:199], v[2:5]
	v_mfma_f32_16x16x32_bf16 v[62:65], v[152:155], v[168:171], v[62:65]
	v_mfma_f32_16x16x32_bf16 v[54:57], v[160:163], v[168:171], v[54:57]
	v_mfma_f32_16x16x32_bf16 v[46:49], v[152:155], v[176:179], v[46:49]
	v_mfma_f32_16x16x32_bf16 v[38:41], v[160:163], v[176:179], v[38:41]
	v_mfma_f32_16x16x32_bf16 v[30:33], v[152:155], v[184:187], v[30:33]
	v_mfma_f32_16x16x32_bf16 v[22:25], v[160:163], v[184:187], v[22:25]
	v_mfma_f32_16x16x32_bf16 v[14:17], v[152:155], v[192:195], v[14:17]
	v_mfma_f32_16x16x32_bf16 v[6:9], v[160:163], v[192:195], v[6:9]
	v_mfma_f32_16x16x32_bf16 v[62:65], v[156:159], v[172:175], v[62:65]
	v_mfma_f32_16x16x32_bf16 v[54:57], v[164:167], v[172:175], v[54:57]
	v_mfma_f32_16x16x32_bf16 v[46:49], v[156:159], v[180:183], v[46:49]
	v_mfma_f32_16x16x32_bf16 v[38:41], v[164:167], v[180:183], v[38:41]
	v_mfma_f32_16x16x32_bf16 v[30:33], v[156:159], v[188:191], v[30:33]
	v_mfma_f32_16x16x32_bf16 v[22:25], v[164:167], v[188:191], v[22:25]
	v_mfma_f32_16x16x32_bf16 v[14:17], v[156:159], v[196:199], v[14:17]
	v_mfma_f32_16x16x32_bf16 v[6:9], v[164:167], v[196:199], v[6:9]
	s_barrier
	s_add_i32 s70, s70, 2
	s_add_u32 s62, s62, 0x100
	s_addc_u32 s64, s64, 0
	s_add_u32 s66, s66, 0x100
	s_addc_u32 s68, s68, 0
	s_cmp_gt_u32 s70, 29
	s_cbranch_scc0 TB_L40000_Bloop
TB_L40000_exit:
	s_and_b64 vcc, exec, s[10:11]
	s_cbranch_vccz .LBB0_1657
	s_barrier
